# a9 + GEMM K-loops: per-burst s_setprio toggles removed, one static s_setprio 1 for the younger wave half at loop entry
# speedup vs baseline: 1.0048x; 1.0048x over previous
.LBB0_296:
	s_ashr_i32 s39, s38, 31
	s_lshl_b64 s[8:9], s[38:39], 19
	s_add_u32 s40, s78, s8
	s_addc_u32 s41, s79, s9
	s_and_b64 s[8:9], s[4:5], exec
	s_cselect_b32 s8, s41, s65
	s_cselect_b32 s9, s40, s64
	s_ashr_i32 s19, s18, 31
	s_lshl_b64 s[42:43], s[18:19], 19
	s_add_u32 s42, s26, s42
	s_addc_u32 s43, s27, s43
	s_and_b64 s[68:69], s[4:5], exec
	s_cselect_b32 s19, s43, s67
	s_cselect_b32 s39, s42, s66
	s_add_u32 s64, s64, 0x40080
	s_addc_u32 s65, s65, 0
	s_add_u32 s63, s66, 0x100
	v_mov_b32_e32 v0, 0
	s_addc_u32 s85, s67, 0
	s_mov_b32 s86, -2
	v_mov_b32_e32 v1, v0
	v_mov_b32_e32 v2, v0
	v_mov_b32_e32 v3, v0
	v_mov_b32_e32 v4, v0
	v_mov_b32_e32 v5, v0
	v_mov_b32_e32 v6, v0
	v_mov_b32_e32 v7, v0
	v_mov_b32_e32 v16, v0
	v_mov_b32_e32 v17, v0
	v_mov_b32_e32 v18, v0
	v_mov_b32_e32 v19, v0
	v_mov_b32_e32 v20, v0
	v_mov_b32_e32 v21, v0
	v_mov_b32_e32 v22, v0
	v_mov_b32_e32 v23, v0
	v_mov_b32_e32 v32, v0
	v_mov_b32_e32 v33, v0
	v_mov_b32_e32 v34, v0
	v_mov_b32_e32 v35, v0
	v_mov_b32_e32 v36, v0
	v_mov_b32_e32 v37, v0
	v_mov_b32_e32 v38, v0
	v_mov_b32_e32 v39, v0
	v_mov_b32_e32 v48, v0
	v_mov_b32_e32 v49, v0
	v_mov_b32_e32 v50, v0
	v_mov_b32_e32 v51, v0
	v_mov_b32_e32 v52, v0
	v_mov_b32_e32 v53, v0
	v_mov_b32_e32 v54, v0
	v_mov_b32_e32 v55, v0
	v_mov_b32_e32 v8, v0
	v_mov_b32_e32 v9, v0
	v_mov_b32_e32 v10, v0
	v_mov_b32_e32 v11, v0
	v_mov_b32_e32 v12, v0
	v_mov_b32_e32 v13, v0
	v_mov_b32_e32 v14, v0
	v_mov_b32_e32 v15, v0
	v_mov_b32_e32 v24, v0
	v_mov_b32_e32 v25, v0
	v_mov_b32_e32 v26, v0
	v_mov_b32_e32 v27, v0
	v_mov_b32_e32 v28, v0
	v_mov_b32_e32 v29, v0
	v_mov_b32_e32 v30, v0
	v_mov_b32_e32 v31, v0
	v_mov_b32_e32 v40, v0
	v_mov_b32_e32 v41, v0
	v_mov_b32_e32 v42, v0
	v_mov_b32_e32 v43, v0
	v_mov_b32_e32 v44, v0
	v_mov_b32_e32 v45, v0
	v_mov_b32_e32 v46, v0
	v_mov_b32_e32 v47, v0
	v_mov_b32_e32 v56, v0
	v_mov_b32_e32 v57, v0
	v_mov_b32_e32 v58, v0
	v_mov_b32_e32 v59, v0
	v_mov_b32_e32 v60, v0
	v_mov_b32_e32 v61, v0
	v_mov_b32_e32 v62, v0
	v_mov_b32_e32 v63, v0
	v_mov_b32_e32 v64, v0
	v_mov_b32_e32 v65, v0
	v_mov_b32_e32 v66, v0
	v_mov_b32_e32 v67, v0
	v_mov_b32_e32 v68, v0
	v_mov_b32_e32 v69, v0
	v_mov_b32_e32 v70, v0
	v_mov_b32_e32 v71, v0
	v_mov_b32_e32 v80, v0
	v_mov_b32_e32 v81, v0
	v_mov_b32_e32 v82, v0
	v_mov_b32_e32 v83, v0
	v_mov_b32_e32 v84, v0
	v_mov_b32_e32 v85, v0
	v_mov_b32_e32 v86, v0
	v_mov_b32_e32 v87, v0
	v_mov_b32_e32 v96, v0
	v_mov_b32_e32 v97, v0
	v_mov_b32_e32 v98, v0
	v_mov_b32_e32 v99, v0
	v_mov_b32_e32 v100, v0
	v_mov_b32_e32 v101, v0
	v_mov_b32_e32 v102, v0
	v_mov_b32_e32 v103, v0
	v_mov_b32_e32 v112, v0
	v_mov_b32_e32 v113, v0
	v_mov_b32_e32 v114, v0
	v_mov_b32_e32 v115, v0
	v_mov_b32_e32 v116, v0
	v_mov_b32_e32 v117, v0
	v_mov_b32_e32 v118, v0
	v_mov_b32_e32 v119, v0
	v_mov_b32_e32 v72, v0
	v_mov_b32_e32 v73, v0
	v_mov_b32_e32 v74, v0
	v_mov_b32_e32 v75, v0
	v_mov_b32_e32 v76, v0
	v_mov_b32_e32 v77, v0
	v_mov_b32_e32 v78, v0
	v_mov_b32_e32 v79, v0
	v_mov_b32_e32 v88, v0
	v_mov_b32_e32 v89, v0
	v_mov_b32_e32 v90, v0
	v_mov_b32_e32 v91, v0
	v_mov_b32_e32 v92, v0
	v_mov_b32_e32 v93, v0
	v_mov_b32_e32 v94, v0
	v_mov_b32_e32 v95, v0
	v_mov_b32_e32 v104, v0
	v_mov_b32_e32 v105, v0
	v_mov_b32_e32 v106, v0
	v_mov_b32_e32 v107, v0
	v_mov_b32_e32 v108, v0
	v_mov_b32_e32 v109, v0
	v_mov_b32_e32 v110, v0
	v_mov_b32_e32 v111, v0
	v_mov_b32_e32 v120, v0
	v_mov_b32_e32 v121, v0
	v_mov_b32_e32 v122, v0
	v_mov_b32_e32 v123, v0
	v_mov_b32_e32 v124, v0
	v_mov_b32_e32 v125, v0
	v_mov_b32_e32 v126, v0
	v_mov_b32_e32 v127, v0
	s_and_b64 vcc, exec, s[10:11]
	s_cbranch_vccnz .Lmy_pr_0
	s_setprio 1
.Lmy_pr_0:
.LBB0_297:
	ds_read_b128 v[164:167], v157
	ds_read_b128 v[168:171], v157 offset:1024
	ds_read_b128 v[172:175], v157 offset:2048
	ds_read_b128 v[176:179], v157 offset:3072
	ds_read_b128 v[180:183], v159
	ds_read_b128 v[184:187], v159 offset:1024
	ds_read_b128 v[188:191], v159 offset:2048
	ds_read_b128 v[192:195], v159 offset:3072
	s_add_u32 s66, s64, 0xfffc0080
	s_addc_u32 s67, s65, -1
	s_cmp_eq_u32 s86, 12
	s_cselect_b32 s69, s8, s67
	s_cselect_b32 s68, s9, s66
	s_cselect_b32 s67, s19, s85
	s_cselect_b32 s66, s39, s63
	v_lshl_add_u64 v[148:149], s[64:65], 0, v[140:141]
	s_add_i32 m0, s61, 0xc000
	ds_read_b128 v[196:199], v161
	ds_read_b128 v[200:203], v161 offset:1024
	ds_read_b128 v[204:207], v161 offset:2048
	ds_read_b128 v[208:211], v161 offset:3072
	ds_read_b128 v[212:215], v161 offset:4096
	ds_read_b128 v[216:219], v161 offset:5120
	ds_read_b128 v[220:223], v161 offset:6144
	ds_read_b128 v[224:227], v161 offset:7168
	global_load_lds_dwordx4 v[148:149], off
	v_lshl_add_u64 v[148:149], s[64:65], 0, v[142:143]
	s_add_i32 m0, s61, 0xe000
	s_nop 0
	global_load_lds_dwordx4 v[148:149], off
	s_waitcnt vmcnt(8)
	s_waitcnt lgkmcnt(0)
	s_barrier
	s_waitcnt lgkmcnt(0)
	v_mfma_f32_16x16x32_bf16 v[124:127], v[164:167], v[196:199], v[124:127]
	v_mfma_f32_16x16x32_bf16 v[120:123], v[172:175], v[196:199], v[120:123]
	v_mfma_f32_16x16x32_bf16 v[108:111], v[164:167], v[204:207], v[108:111]
	v_mfma_f32_16x16x32_bf16 v[104:107], v[172:175], v[204:207], v[104:107]
	v_mfma_f32_16x16x32_bf16 v[92:95], v[164:167], v[212:215], v[92:95]
	v_mfma_f32_16x16x32_bf16 v[88:91], v[172:175], v[212:215], v[88:91]
	v_mfma_f32_16x16x32_bf16 v[76:79], v[164:167], v[220:223], v[76:79]
	v_mfma_f32_16x16x32_bf16 v[72:75], v[172:175], v[220:223], v[72:75]
	v_mfma_f32_16x16x32_bf16 v[124:127], v[168:171], v[200:203], v[124:127]
	v_mfma_f32_16x16x32_bf16 v[120:123], v[176:179], v[200:203], v[120:123]
	v_mfma_f32_16x16x32_bf16 v[108:111], v[168:171], v[208:211], v[108:111]
	v_mfma_f32_16x16x32_bf16 v[104:107], v[176:179], v[208:211], v[104:107]
	v_mfma_f32_16x16x32_bf16 v[92:95], v[168:171], v[216:219], v[92:95]
	v_mfma_f32_16x16x32_bf16 v[88:91], v[176:179], v[216:219], v[88:91]
	v_mfma_f32_16x16x32_bf16 v[76:79], v[168:171], v[224:227], v[76:79]
	v_mfma_f32_16x16x32_bf16 v[72:75], v[176:179], v[224:227], v[72:75]
	v_mfma_f32_16x16x32_bf16 v[116:119], v[180:183], v[196:199], v[116:119]
	v_mfma_f32_16x16x32_bf16 v[112:115], v[188:191], v[196:199], v[112:115]
	v_mfma_f32_16x16x32_bf16 v[100:103], v[180:183], v[204:207], v[100:103]
	v_mfma_f32_16x16x32_bf16 v[96:99], v[188:191], v[204:207], v[96:99]
	v_mfma_f32_16x16x32_bf16 v[84:87], v[180:183], v[212:215], v[84:87]
	v_mfma_f32_16x16x32_bf16 v[80:83], v[188:191], v[212:215], v[80:83]
	v_mfma_f32_16x16x32_bf16 v[68:71], v[180:183], v[220:223], v[68:71]
	v_mfma_f32_16x16x32_bf16 v[64:67], v[188:191], v[220:223], v[64:67]
	v_mfma_f32_16x16x32_bf16 v[116:119], v[184:187], v[200:203], v[116:119]
	v_mfma_f32_16x16x32_bf16 v[112:115], v[192:195], v[200:203], v[112:115]
	v_mfma_f32_16x16x32_bf16 v[100:103], v[184:187], v[208:211], v[100:103]
	v_mfma_f32_16x16x32_bf16 v[96:99], v[192:195], v[208:211], v[96:99]
	v_mfma_f32_16x16x32_bf16 v[84:87], v[184:187], v[216:219], v[84:87]
	v_mfma_f32_16x16x32_bf16 v[80:83], v[192:195], v[216:219], v[80:83]
	v_mfma_f32_16x16x32_bf16 v[68:71], v[184:187], v[224:227], v[68:71]
	v_mfma_f32_16x16x32_bf16 v[64:67], v[192:195], v[224:227], v[64:67]
	s_barrier
	s_add_i32 s90, s82, s35
	v_lshl_add_u64 v[148:149], s[66:67], 0, v[130:131]
	s_mov_b32 m0, s90
	ds_read_b128 v[196:199], v161 offset:16384
	ds_read_b128 v[200:203], v161 offset:17408
	ds_read_b128 v[204:207], v161 offset:18432
	ds_read_b128 v[208:211], v161 offset:19456
	ds_read_b128 v[212:215], v161 offset:20480
	ds_read_b128 v[216:219], v161 offset:21504
	ds_read_b128 v[220:223], v161 offset:22528
	ds_read_b128 v[224:227], v161 offset:23552
	global_load_lds_dwordx4 v[148:149], off
	s_add_i32 m0, s90, 0x2000
	s_add_u32 s90, s66, 0x40000
	v_lshl_add_u64 v[152:153], s[66:67], 0, v[134:135]
	s_addc_u32 s91, s67, 0
	s_add_i32 s92, s83, s35
	global_load_lds_dwordx4 v[152:153], off
	v_lshl_add_u64 v[228:229], s[90:91], 0, v[130:131]
	s_mov_b32 m0, s92
	v_lshl_add_u64 v[230:231], s[68:69], 0, v[132:133]
	global_load_lds_dwordx4 v[228:229], off
	v_lshl_add_u64 v[228:229], s[90:91], 0, v[134:135]
	s_add_i32 m0, s92, 0x2000
	s_nop 0
	global_load_lds_dwordx4 v[228:229], off
	v_lshl_add_u64 v[228:229], s[68:69], 0, v[128:129]
	s_mov_b32 m0, s61
	s_nop 0
	global_load_lds_dwordx4 v[228:229], off
	s_mov_b32 m0, s70
	s_nop 0
	global_load_lds_dwordx4 v[230:231], off
	s_waitcnt vmcnt(8)
	s_waitcnt lgkmcnt(0)
	s_barrier
	s_waitcnt lgkmcnt(0)
	v_mfma_f32_16x16x32_bf16 v[60:63], v[164:167], v[196:199], v[60:63]
	v_mfma_f32_16x16x32_bf16 v[56:59], v[172:175], v[196:199], v[56:59]
	v_mfma_f32_16x16x32_bf16 v[44:47], v[164:167], v[204:207], v[44:47]
	v_mfma_f32_16x16x32_bf16 v[40:43], v[172:175], v[204:207], v[40:43]
	v_mfma_f32_16x16x32_bf16 v[28:31], v[164:167], v[212:215], v[28:31]
	v_mfma_f32_16x16x32_bf16 v[24:27], v[172:175], v[212:215], v[24:27]
	v_mfma_f32_16x16x32_bf16 v[12:15], v[164:167], v[220:223], v[12:15]
	v_mfma_f32_16x16x32_bf16 v[8:11], v[172:175], v[220:223], v[8:11]
	v_mfma_f32_16x16x32_bf16 v[60:63], v[168:171], v[200:203], v[60:63]
	v_mfma_f32_16x16x32_bf16 v[56:59], v[176:179], v[200:203], v[56:59]
	v_mfma_f32_16x16x32_bf16 v[44:47], v[168:171], v[208:211], v[44:47]
	v_mfma_f32_16x16x32_bf16 v[40:43], v[176:179], v[208:211], v[40:43]
	v_mfma_f32_16x16x32_bf16 v[28:31], v[168:171], v[216:219], v[28:31]
	v_mfma_f32_16x16x32_bf16 v[24:27], v[176:179], v[216:219], v[24:27]
	v_mfma_f32_16x16x32_bf16 v[12:15], v[168:171], v[224:227], v[12:15]
	v_mfma_f32_16x16x32_bf16 v[8:11], v[176:179], v[224:227], v[8:11]
	v_mfma_f32_16x16x32_bf16 v[52:55], v[180:183], v[196:199], v[52:55]
	v_mfma_f32_16x16x32_bf16 v[48:51], v[188:191], v[196:199], v[48:51]
	v_mfma_f32_16x16x32_bf16 v[36:39], v[180:183], v[204:207], v[36:39]
	v_mfma_f32_16x16x32_bf16 v[32:35], v[188:191], v[204:207], v[32:35]
	v_mfma_f32_16x16x32_bf16 v[20:23], v[180:183], v[212:215], v[20:23]
	v_mfma_f32_16x16x32_bf16 v[16:19], v[188:191], v[212:215], v[16:19]
	v_mfma_f32_16x16x32_bf16 v[4:7], v[180:183], v[220:223], v[4:7]
	v_mfma_f32_16x16x32_bf16 v[0:3], v[188:191], v[220:223], v[0:3]
	v_mfma_f32_16x16x32_bf16 v[52:55], v[184:187], v[200:203], v[52:55]
	v_mfma_f32_16x16x32_bf16 v[48:51], v[192:195], v[200:203], v[48:51]
	v_mfma_f32_16x16x32_bf16 v[36:39], v[184:187], v[208:211], v[36:39]
	v_mfma_f32_16x16x32_bf16 v[32:35], v[192:195], v[208:211], v[32:35]
	v_mfma_f32_16x16x32_bf16 v[20:23], v[184:187], v[216:219], v[20:23]
	v_mfma_f32_16x16x32_bf16 v[16:19], v[192:195], v[216:219], v[16:19]
	v_mfma_f32_16x16x32_bf16 v[4:7], v[184:187], v[224:227], v[4:7]
	v_mfma_f32_16x16x32_bf16 v[0:3], v[192:195], v[224:227], v[0:3]
	s_barrier
	s_add_i32 s90, 0, 0x18000
	v_add_u32_e32 v136, s90, v151
	s_add_i32 s91, 0, 0x1c000
	ds_read_b128 v[164:167], v136
	ds_read_b128 v[168:171], v136 offset:1024
	ds_read_b128 v[172:175], v136 offset:2048
	ds_read_b128 v[176:179], v136 offset:3072
	v_add_u32_e32 v136, s91, v151
	ds_read_b128 v[180:183], v136
	ds_read_b128 v[184:187], v136 offset:1024
	ds_read_b128 v[188:191], v136 offset:2048
	ds_read_b128 v[192:195], v136 offset:3072
	s_add_u32 s68, s68, 0x40000
	s_addc_u32 s69, s69, 0
	s_mov_b32 m0, s71
	v_lshl_add_u64 v[232:233], s[68:69], 0, v[128:129]
	ds_read_b128 v[196:199], v161 offset:32768
	ds_read_b128 v[200:203], v161 offset:33792
	ds_read_b128 v[204:207], v161 offset:34816
	ds_read_b128 v[208:211], v161 offset:35840
	ds_read_b128 v[212:215], v161 offset:36864
	ds_read_b128 v[216:219], v161 offset:37888
	ds_read_b128 v[220:223], v161 offset:38912
	ds_read_b128 v[224:227], v161 offset:39936
	global_load_lds_dwordx4 v[232:233], off
	v_lshl_add_u64 v[232:233], s[68:69], 0, v[132:133]
	s_mov_b32 m0, s72
	s_nop 0
	global_load_lds_dwordx4 v[232:233], off
	s_waitcnt vmcnt(8)
	s_waitcnt lgkmcnt(0)
	s_barrier
	s_waitcnt lgkmcnt(0)
	v_mfma_f32_16x16x32_bf16 v[124:127], v[164:167], v[196:199], v[124:127]
	v_mfma_f32_16x16x32_bf16 v[120:123], v[172:175], v[196:199], v[120:123]
	v_mfma_f32_16x16x32_bf16 v[108:111], v[164:167], v[204:207], v[108:111]
	v_mfma_f32_16x16x32_bf16 v[104:107], v[172:175], v[204:207], v[104:107]
	v_mfma_f32_16x16x32_bf16 v[92:95], v[164:167], v[212:215], v[92:95]
	v_mfma_f32_16x16x32_bf16 v[88:91], v[172:175], v[212:215], v[88:91]
	v_mfma_f32_16x16x32_bf16 v[76:79], v[164:167], v[220:223], v[76:79]
	v_mfma_f32_16x16x32_bf16 v[72:75], v[172:175], v[220:223], v[72:75]
	v_mfma_f32_16x16x32_bf16 v[124:127], v[168:171], v[200:203], v[124:127]
	v_mfma_f32_16x16x32_bf16 v[120:123], v[176:179], v[200:203], v[120:123]
	v_mfma_f32_16x16x32_bf16 v[108:111], v[168:171], v[208:211], v[108:111]
	v_mfma_f32_16x16x32_bf16 v[104:107], v[176:179], v[208:211], v[104:107]
	v_mfma_f32_16x16x32_bf16 v[92:95], v[168:171], v[216:219], v[92:95]
	v_mfma_f32_16x16x32_bf16 v[88:91], v[176:179], v[216:219], v[88:91]
	v_mfma_f32_16x16x32_bf16 v[76:79], v[168:171], v[224:227], v[76:79]
	v_mfma_f32_16x16x32_bf16 v[72:75], v[176:179], v[224:227], v[72:75]
	v_mfma_f32_16x16x32_bf16 v[116:119], v[180:183], v[196:199], v[116:119]
	v_mfma_f32_16x16x32_bf16 v[112:115], v[188:191], v[196:199], v[112:115]
	v_mfma_f32_16x16x32_bf16 v[100:103], v[180:183], v[204:207], v[100:103]
	v_mfma_f32_16x16x32_bf16 v[96:99], v[188:191], v[204:207], v[96:99]
	v_mfma_f32_16x16x32_bf16 v[84:87], v[180:183], v[212:215], v[84:87]
	v_mfma_f32_16x16x32_bf16 v[80:83], v[188:191], v[212:215], v[80:83]
	v_mfma_f32_16x16x32_bf16 v[68:71], v[180:183], v[220:223], v[68:71]
	v_mfma_f32_16x16x32_bf16 v[64:67], v[188:191], v[220:223], v[64:67]
	v_mfma_f32_16x16x32_bf16 v[116:119], v[184:187], v[200:203], v[116:119]
	v_mfma_f32_16x16x32_bf16 v[112:115], v[192:195], v[200:203], v[112:115]
	v_mfma_f32_16x16x32_bf16 v[100:103], v[184:187], v[208:211], v[100:103]
	v_mfma_f32_16x16x32_bf16 v[96:99], v[192:195], v[208:211], v[96:99]
	v_mfma_f32_16x16x32_bf16 v[84:87], v[184:187], v[216:219], v[84:87]
	v_mfma_f32_16x16x32_bf16 v[80:83], v[192:195], v[216:219], v[80:83]
	v_mfma_f32_16x16x32_bf16 v[68:71], v[184:187], v[224:227], v[68:71]
	v_mfma_f32_16x16x32_bf16 v[64:67], v[192:195], v[224:227], v[64:67]
	s_barrier
	s_add_i32 s68, s90, s35
	v_lshl_add_u64 v[148:149], v[148:149], 0, s[6:7]
	s_mov_b32 m0, s68
	ds_read_b128 v[196:199], v161 offset:49152
	ds_read_b128 v[200:203], v161 offset:50176
	ds_read_b128 v[204:207], v161 offset:51200
	ds_read_b128 v[208:211], v161 offset:52224
	ds_read_b128 v[212:215], v161 offset:53248
	ds_read_b128 v[216:219], v161 offset:54272
	ds_read_b128 v[220:223], v161 offset:55296
	ds_read_b128 v[224:227], v161 offset:56320
	global_load_lds_dwordx4 v[148:149], off
	s_add_i32 m0, s68, 0x2000
	s_add_u32 s66, s66, 0x40080
	v_lshl_add_u64 v[148:149], v[152:153], 0, s[6:7]
	s_addc_u32 s67, s67, 0
	s_add_i32 s68, s91, s35
	global_load_lds_dwordx4 v[148:149], off
	v_lshl_add_u64 v[148:149], s[66:67], 0, v[130:131]
	s_mov_b32 m0, s68
	s_nop 0
	global_load_lds_dwordx4 v[148:149], off
	v_lshl_add_u64 v[148:149], s[66:67], 0, v[134:135]
	s_add_i32 m0, s68, 0x2000
	s_nop 0
	global_load_lds_dwordx4 v[148:149], off
	v_lshl_add_u64 v[148:149], v[228:229], 0, s[6:7]
	s_mov_b32 m0, s75
	s_nop 0
	global_load_lds_dwordx4 v[148:149], off
	v_lshl_add_u64 v[148:149], v[230:231], 0, s[6:7]
	s_mov_b32 m0, s76
	s_nop 0
	global_load_lds_dwordx4 v[148:149], off
	s_waitcnt vmcnt(8)
	s_waitcnt lgkmcnt(0)
	s_barrier
	s_waitcnt lgkmcnt(0)
	v_mfma_f32_16x16x32_bf16 v[60:63], v[164:167], v[196:199], v[60:63]
	v_mfma_f32_16x16x32_bf16 v[56:59], v[172:175], v[196:199], v[56:59]
	v_mfma_f32_16x16x32_bf16 v[44:47], v[164:167], v[204:207], v[44:47]
	v_mfma_f32_16x16x32_bf16 v[40:43], v[172:175], v[204:207], v[40:43]
	v_mfma_f32_16x16x32_bf16 v[28:31], v[164:167], v[212:215], v[28:31]
	v_mfma_f32_16x16x32_bf16 v[24:27], v[172:175], v[212:215], v[24:27]
	v_mfma_f32_16x16x32_bf16 v[12:15], v[164:167], v[220:223], v[12:15]
	v_mfma_f32_16x16x32_bf16 v[8:11], v[172:175], v[220:223], v[8:11]
	v_mfma_f32_16x16x32_bf16 v[60:63], v[168:171], v[200:203], v[60:63]
	v_mfma_f32_16x16x32_bf16 v[56:59], v[176:179], v[200:203], v[56:59]
	v_mfma_f32_16x16x32_bf16 v[44:47], v[168:171], v[208:211], v[44:47]
	v_mfma_f32_16x16x32_bf16 v[40:43], v[176:179], v[208:211], v[40:43]
	v_mfma_f32_16x16x32_bf16 v[28:31], v[168:171], v[216:219], v[28:31]
	v_mfma_f32_16x16x32_bf16 v[24:27], v[176:179], v[216:219], v[24:27]
	v_mfma_f32_16x16x32_bf16 v[12:15], v[168:171], v[224:227], v[12:15]
	v_mfma_f32_16x16x32_bf16 v[8:11], v[176:179], v[224:227], v[8:11]
	v_mfma_f32_16x16x32_bf16 v[52:55], v[180:183], v[196:199], v[52:55]
	v_mfma_f32_16x16x32_bf16 v[48:51], v[188:191], v[196:199], v[48:51]
	v_mfma_f32_16x16x32_bf16 v[36:39], v[180:183], v[204:207], v[36:39]
	v_mfma_f32_16x16x32_bf16 v[32:35], v[188:191], v[204:207], v[32:35]
	v_mfma_f32_16x16x32_bf16 v[20:23], v[180:183], v[212:215], v[20:23]
	v_mfma_f32_16x16x32_bf16 v[16:19], v[188:191], v[212:215], v[16:19]
	v_mfma_f32_16x16x32_bf16 v[4:7], v[180:183], v[220:223], v[4:7]
	v_mfma_f32_16x16x32_bf16 v[0:3], v[188:191], v[220:223], v[0:3]
	v_mfma_f32_16x16x32_bf16 v[52:55], v[184:187], v[200:203], v[52:55]
	v_mfma_f32_16x16x32_bf16 v[48:51], v[192:195], v[200:203], v[48:51]
	v_mfma_f32_16x16x32_bf16 v[36:39], v[184:187], v[208:211], v[36:39]
	v_mfma_f32_16x16x32_bf16 v[32:35], v[192:195], v[208:211], v[32:35]
	v_mfma_f32_16x16x32_bf16 v[20:23], v[184:187], v[216:219], v[20:23]
	v_mfma_f32_16x16x32_bf16 v[16:19], v[192:195], v[216:219], v[16:19]
	v_mfma_f32_16x16x32_bf16 v[4:7], v[184:187], v[224:227], v[4:7]
	v_mfma_f32_16x16x32_bf16 v[0:3], v[192:195], v[224:227], v[0:3]
	s_barrier
	s_add_i32 s86, s86, 2
	s_add_u32 s64, s64, 0x100
	s_addc_u32 s65, s65, 0
	s_add_u32 s63, s63, 0x100
	s_addc_u32 s85, s85, 0
	s_cmp_gt_u32 s86, 13
	s_cbranch_scc0 .LBB0_297
	s_setprio 0
	s_and_b64 vcc, exec, s[10:11]
	s_cbranch_vccz .LBB0_300
	s_barrier

.LBB0_443:
	v_mov_b32_e32 v127, 0
	s_and_b64 vcc, exec, s[0:1]
	v_mov_b32_e32 v126, v127
	v_mov_b32_e32 v125, v127
	v_mov_b32_e32 v124, v127
	v_mov_b32_e32 v123, v127
	v_mov_b32_e32 v122, v127
	v_mov_b32_e32 v121, v127
	v_mov_b32_e32 v120, v127
	v_mov_b32_e32 v111, v127
	v_mov_b32_e32 v110, v127
	v_mov_b32_e32 v109, v127
	v_mov_b32_e32 v108, v127
	v_mov_b32_e32 v107, v127
	v_mov_b32_e32 v106, v127
	v_mov_b32_e32 v105, v127
	v_mov_b32_e32 v104, v127
	v_mov_b32_e32 v95, v127
	v_mov_b32_e32 v94, v127
	v_mov_b32_e32 v93, v127
	v_mov_b32_e32 v92, v127
	v_mov_b32_e32 v91, v127
	v_mov_b32_e32 v90, v127
	v_mov_b32_e32 v89, v127
	v_mov_b32_e32 v88, v127
	v_mov_b32_e32 v79, v127
	v_mov_b32_e32 v78, v127
	v_mov_b32_e32 v77, v127
	v_mov_b32_e32 v76, v127
	v_mov_b32_e32 v75, v127
	v_mov_b32_e32 v74, v127
	v_mov_b32_e32 v73, v127
	v_mov_b32_e32 v72, v127
	v_mov_b32_e32 v119, v127
	v_mov_b32_e32 v118, v127
	v_mov_b32_e32 v117, v127
	v_mov_b32_e32 v116, v127
	v_mov_b32_e32 v115, v127
	v_mov_b32_e32 v114, v127
	v_mov_b32_e32 v113, v127
	v_mov_b32_e32 v112, v127
	v_mov_b32_e32 v103, v127
	v_mov_b32_e32 v102, v127
	v_mov_b32_e32 v101, v127
	v_mov_b32_e32 v100, v127
	v_mov_b32_e32 v99, v127
	v_mov_b32_e32 v98, v127
	v_mov_b32_e32 v97, v127
	v_mov_b32_e32 v96, v127
	v_mov_b32_e32 v87, v127
	v_mov_b32_e32 v86, v127
	v_mov_b32_e32 v85, v127
	v_mov_b32_e32 v84, v127
	v_mov_b32_e32 v83, v127
	v_mov_b32_e32 v82, v127
	v_mov_b32_e32 v81, v127
	v_mov_b32_e32 v80, v127
	v_mov_b32_e32 v71, v127
	v_mov_b32_e32 v70, v127
	v_mov_b32_e32 v69, v127
	v_mov_b32_e32 v68, v127
	v_mov_b32_e32 v67, v127
	v_mov_b32_e32 v66, v127
	v_mov_b32_e32 v65, v127
	v_mov_b32_e32 v64, v127
	v_mov_b32_e32 v63, v127
	v_mov_b32_e32 v62, v127
	v_mov_b32_e32 v61, v127
	v_mov_b32_e32 v60, v127
	v_mov_b32_e32 v59, v127
	v_mov_b32_e32 v58, v127
	v_mov_b32_e32 v57, v127
	v_mov_b32_e32 v56, v127
	v_mov_b32_e32 v47, v127
	v_mov_b32_e32 v46, v127
	v_mov_b32_e32 v45, v127
	v_mov_b32_e32 v44, v127
	v_mov_b32_e32 v43, v127
	v_mov_b32_e32 v42, v127
	v_mov_b32_e32 v41, v127
	v_mov_b32_e32 v40, v127
	v_mov_b32_e32 v31, v127
	v_mov_b32_e32 v30, v127
	v_mov_b32_e32 v29, v127
	v_mov_b32_e32 v28, v127
	v_mov_b32_e32 v27, v127
	v_mov_b32_e32 v26, v127
	v_mov_b32_e32 v25, v127
	v_mov_b32_e32 v24, v127
	v_mov_b32_e32 v15, v127
	v_mov_b32_e32 v14, v127
	v_mov_b32_e32 v13, v127
	v_mov_b32_e32 v12, v127
	v_mov_b32_e32 v11, v127
	v_mov_b32_e32 v10, v127
	v_mov_b32_e32 v9, v127
	v_mov_b32_e32 v8, v127
	v_mov_b32_e32 v55, v127
	v_mov_b32_e32 v54, v127
	v_mov_b32_e32 v53, v127
	v_mov_b32_e32 v52, v127
	v_mov_b32_e32 v51, v127
	v_mov_b32_e32 v50, v127
	v_mov_b32_e32 v49, v127
	v_mov_b32_e32 v48, v127
	v_mov_b32_e32 v39, v127
	v_mov_b32_e32 v38, v127
	v_mov_b32_e32 v37, v127
	v_mov_b32_e32 v36, v127
	v_mov_b32_e32 v35, v127
	v_mov_b32_e32 v34, v127
	v_mov_b32_e32 v33, v127
	v_mov_b32_e32 v32, v127
	v_mov_b32_e32 v23, v127
	v_mov_b32_e32 v22, v127
	v_mov_b32_e32 v21, v127
	v_mov_b32_e32 v20, v127
	v_mov_b32_e32 v19, v127
	v_mov_b32_e32 v18, v127
	v_mov_b32_e32 v17, v127
	v_mov_b32_e32 v16, v127
	v_mov_b32_e32 v7, v127
	v_mov_b32_e32 v6, v127
	v_mov_b32_e32 v5, v127
	v_mov_b32_e32 v4, v127
	v_mov_b32_e32 v3, v127
	v_mov_b32_e32 v2, v127
	v_mov_b32_e32 v1, v127
	v_mov_b32_e32 v0, v127
	s_cbranch_vccnz .LBB0_446
	s_add_u32 s40, s40, 0x80
	s_addc_u32 s41, s41, 0
	s_add_u32 s71, s42, 0x100
	v_mov_b32_e32 v0, 0
	s_addc_u32 s72, s43, 0
	s_mov_b32 s42, 0
	v_mov_b32_e32 v1, v0
	v_mov_b32_e32 v2, v0
	v_mov_b32_e32 v3, v0
	v_mov_b32_e32 v4, v0
	v_mov_b32_e32 v5, v0
	v_mov_b32_e32 v6, v0
	v_mov_b32_e32 v7, v0
	v_mov_b32_e32 v16, v0
	v_mov_b32_e32 v17, v0
	v_mov_b32_e32 v18, v0
	v_mov_b32_e32 v19, v0
	v_mov_b32_e32 v20, v0
	v_mov_b32_e32 v21, v0
	v_mov_b32_e32 v22, v0
	v_mov_b32_e32 v23, v0
	v_mov_b32_e32 v32, v0
	v_mov_b32_e32 v33, v0
	v_mov_b32_e32 v34, v0
	v_mov_b32_e32 v35, v0
	v_mov_b32_e32 v36, v0
	v_mov_b32_e32 v37, v0
	v_mov_b32_e32 v38, v0
	v_mov_b32_e32 v39, v0
	v_mov_b32_e32 v48, v0
	v_mov_b32_e32 v49, v0
	v_mov_b32_e32 v50, v0
	v_mov_b32_e32 v51, v0
	v_mov_b32_e32 v52, v0
	v_mov_b32_e32 v53, v0
	v_mov_b32_e32 v54, v0
	v_mov_b32_e32 v55, v0
	v_mov_b32_e32 v8, v0
	v_mov_b32_e32 v9, v0
	v_mov_b32_e32 v10, v0
	v_mov_b32_e32 v11, v0
	v_mov_b32_e32 v12, v0
	v_mov_b32_e32 v13, v0
	v_mov_b32_e32 v14, v0
	v_mov_b32_e32 v15, v0
	v_mov_b32_e32 v24, v0
	v_mov_b32_e32 v25, v0
	v_mov_b32_e32 v26, v0
	v_mov_b32_e32 v27, v0
	v_mov_b32_e32 v28, v0
	v_mov_b32_e32 v29, v0
	v_mov_b32_e32 v30, v0
	v_mov_b32_e32 v31, v0
	v_mov_b32_e32 v40, v0
	v_mov_b32_e32 v41, v0
	v_mov_b32_e32 v42, v0
	v_mov_b32_e32 v43, v0
	v_mov_b32_e32 v44, v0
	v_mov_b32_e32 v45, v0
	v_mov_b32_e32 v46, v0
	v_mov_b32_e32 v47, v0
	v_mov_b32_e32 v56, v0
	v_mov_b32_e32 v57, v0
	v_mov_b32_e32 v58, v0
	v_mov_b32_e32 v59, v0
	v_mov_b32_e32 v60, v0
	v_mov_b32_e32 v61, v0
	v_mov_b32_e32 v62, v0
	v_mov_b32_e32 v63, v0
	v_mov_b32_e32 v64, v0
	v_mov_b32_e32 v65, v0
	v_mov_b32_e32 v66, v0
	v_mov_b32_e32 v67, v0
	v_mov_b32_e32 v68, v0
	v_mov_b32_e32 v69, v0
	v_mov_b32_e32 v70, v0
	v_mov_b32_e32 v71, v0
	v_mov_b32_e32 v80, v0
	v_mov_b32_e32 v81, v0
	v_mov_b32_e32 v82, v0
	v_mov_b32_e32 v83, v0
	v_mov_b32_e32 v84, v0
	v_mov_b32_e32 v85, v0
	v_mov_b32_e32 v86, v0
	v_mov_b32_e32 v87, v0
	v_mov_b32_e32 v96, v0
	v_mov_b32_e32 v97, v0
	v_mov_b32_e32 v98, v0
	v_mov_b32_e32 v99, v0
	v_mov_b32_e32 v100, v0
	v_mov_b32_e32 v101, v0
	v_mov_b32_e32 v102, v0
	v_mov_b32_e32 v103, v0
	v_mov_b32_e32 v112, v0
	v_mov_b32_e32 v113, v0
	v_mov_b32_e32 v114, v0
	v_mov_b32_e32 v115, v0
	v_mov_b32_e32 v116, v0
	v_mov_b32_e32 v117, v0
	v_mov_b32_e32 v118, v0
	v_mov_b32_e32 v119, v0
	v_mov_b32_e32 v72, v0
	v_mov_b32_e32 v73, v0
	v_mov_b32_e32 v74, v0
	v_mov_b32_e32 v75, v0
	v_mov_b32_e32 v76, v0
	v_mov_b32_e32 v77, v0
	v_mov_b32_e32 v78, v0
	v_mov_b32_e32 v79, v0
	v_mov_b32_e32 v88, v0
	v_mov_b32_e32 v89, v0
	v_mov_b32_e32 v90, v0
	v_mov_b32_e32 v91, v0
	v_mov_b32_e32 v92, v0
	v_mov_b32_e32 v93, v0
	v_mov_b32_e32 v94, v0
	v_mov_b32_e32 v95, v0
	v_mov_b32_e32 v104, v0
	v_mov_b32_e32 v105, v0
	v_mov_b32_e32 v106, v0
	v_mov_b32_e32 v107, v0
	v_mov_b32_e32 v108, v0
	v_mov_b32_e32 v109, v0
	v_mov_b32_e32 v110, v0
	v_mov_b32_e32 v111, v0
	v_mov_b32_e32 v120, v0
	v_mov_b32_e32 v121, v0
	v_mov_b32_e32 v122, v0
	v_mov_b32_e32 v123, v0
	v_mov_b32_e32 v124, v0
	v_mov_b32_e32 v125, v0
	v_mov_b32_e32 v126, v0
	v_mov_b32_e32 v127, v0
	s_and_b64 vcc, exec, s[22:23]
	s_cbranch_vccnz .Lmy_pr_1
	s_setprio 1
.Lmy_pr_1:
.LBB0_445:
	ds_read_b128 v[150:153], v147
	ds_read_b128 v[154:157], v147 offset:1024
	ds_read_b128 v[158:161], v147 offset:2048
	ds_read_b128 v[162:165], v147 offset:3072
	ds_read_b128 v[166:169], v148
	ds_read_b128 v[170:173], v148 offset:1024
	ds_read_b128 v[174:177], v148 offset:2048
	ds_read_b128 v[178:181], v148 offset:3072
	s_add_i32 s73, s42, 2
	s_add_u32 s74, s40, 0x80
	s_addc_u32 s43, s41, 0
	s_cmp_eq_u32 s61, s42
	s_cselect_b32 s42, s6, s74
	s_cselect_b32 s43, s7, s43
	s_cselect_b32 s75, s39, s72
	s_cselect_b32 s74, s38, s71
	v_lshl_add_u64 v[214:215], s[40:41], 0, v[136:137]
	s_add_i32 m0, s9, 0xc000
	ds_read_b128 v[182:185], v149
	ds_read_b128 v[186:189], v149 offset:1024
	ds_read_b128 v[190:193], v149 offset:2048
	ds_read_b128 v[194:197], v149 offset:3072
	ds_read_b128 v[198:201], v149 offset:4096
	ds_read_b128 v[202:205], v149 offset:5120
	ds_read_b128 v[206:209], v149 offset:6144
	ds_read_b128 v[210:213], v149 offset:7168
	global_load_lds_dwordx4 v[214:215], off
	v_lshl_add_u64 v[214:215], s[40:41], 0, v[138:139]
	s_add_i32 m0, s9, 0xe000
	s_nop 0
	global_load_lds_dwordx4 v[214:215], off
	s_waitcnt vmcnt(8)
	s_waitcnt lgkmcnt(0)
	s_barrier
	s_waitcnt lgkmcnt(0)
	v_mfma_f32_16x16x32_bf16 v[124:127], v[150:153], v[182:185], v[124:127]
	v_mfma_f32_16x16x32_bf16 v[120:123], v[158:161], v[182:185], v[120:123]
	v_mfma_f32_16x16x32_bf16 v[108:111], v[150:153], v[190:193], v[108:111]
	v_mfma_f32_16x16x32_bf16 v[104:107], v[158:161], v[190:193], v[104:107]
	v_mfma_f32_16x16x32_bf16 v[92:95], v[150:153], v[198:201], v[92:95]
	v_mfma_f32_16x16x32_bf16 v[88:91], v[158:161], v[198:201], v[88:91]
	v_mfma_f32_16x16x32_bf16 v[76:79], v[150:153], v[206:209], v[76:79]
	v_mfma_f32_16x16x32_bf16 v[72:75], v[158:161], v[206:209], v[72:75]
	v_mfma_f32_16x16x32_bf16 v[124:127], v[154:157], v[186:189], v[124:127]
	v_mfma_f32_16x16x32_bf16 v[120:123], v[162:165], v[186:189], v[120:123]
	v_mfma_f32_16x16x32_bf16 v[108:111], v[154:157], v[194:197], v[108:111]
	v_mfma_f32_16x16x32_bf16 v[104:107], v[162:165], v[194:197], v[104:107]
	v_mfma_f32_16x16x32_bf16 v[92:95], v[154:157], v[202:205], v[92:95]
	v_mfma_f32_16x16x32_bf16 v[88:91], v[162:165], v[202:205], v[88:91]
	v_mfma_f32_16x16x32_bf16 v[76:79], v[154:157], v[210:213], v[76:79]
	v_mfma_f32_16x16x32_bf16 v[72:75], v[162:165], v[210:213], v[72:75]
	v_mfma_f32_16x16x32_bf16 v[116:119], v[166:169], v[182:185], v[116:119]
	v_mfma_f32_16x16x32_bf16 v[112:115], v[174:177], v[182:185], v[112:115]
	v_mfma_f32_16x16x32_bf16 v[100:103], v[166:169], v[190:193], v[100:103]
	v_mfma_f32_16x16x32_bf16 v[96:99], v[174:177], v[190:193], v[96:99]
	v_mfma_f32_16x16x32_bf16 v[84:87], v[166:169], v[198:201], v[84:87]
	v_mfma_f32_16x16x32_bf16 v[80:83], v[174:177], v[198:201], v[80:83]
	v_mfma_f32_16x16x32_bf16 v[68:71], v[166:169], v[206:209], v[68:71]
	v_mfma_f32_16x16x32_bf16 v[64:67], v[174:177], v[206:209], v[64:67]
	v_mfma_f32_16x16x32_bf16 v[116:119], v[170:173], v[186:189], v[116:119]
	v_mfma_f32_16x16x32_bf16 v[112:115], v[178:181], v[186:189], v[112:115]
	v_mfma_f32_16x16x32_bf16 v[100:103], v[170:173], v[194:197], v[100:103]
	v_mfma_f32_16x16x32_bf16 v[96:99], v[178:181], v[194:197], v[96:99]
	v_mfma_f32_16x16x32_bf16 v[84:87], v[170:173], v[202:205], v[84:87]
	v_mfma_f32_16x16x32_bf16 v[80:83], v[178:181], v[202:205], v[80:83]
	v_mfma_f32_16x16x32_bf16 v[68:71], v[170:173], v[210:213], v[68:71]
	v_mfma_f32_16x16x32_bf16 v[64:67], v[178:181], v[210:213], v[64:67]
	s_barrier
	s_add_i32 s76, s64, s49
	v_lshl_add_u64 v[214:215], s[74:75], 0, v[132:133]
	s_mov_b32 m0, s76
	ds_read_b128 v[182:185], v149 offset:16384
	ds_read_b128 v[186:189], v149 offset:17408
	ds_read_b128 v[190:193], v149 offset:18432
	ds_read_b128 v[194:197], v149 offset:19456
	ds_read_b128 v[198:201], v149 offset:20480
	ds_read_b128 v[202:205], v149 offset:21504
	ds_read_b128 v[206:209], v149 offset:22528
	ds_read_b128 v[210:213], v149 offset:23552
	global_load_lds_dwordx4 v[214:215], off
	s_add_i32 m0, s76, 0x2000
	v_lshl_add_u64 v[216:217], s[74:75], 0, v[128:129]
	s_add_u32 s74, s74, s12
	s_addc_u32 s75, s75, s13
	s_add_i32 s76, s65, s49
	global_load_lds_dwordx4 v[216:217], off
	v_lshl_add_u64 v[218:219], s[74:75], 0, v[132:133]
	s_mov_b32 m0, s76
	v_lshl_add_u64 v[220:221], s[74:75], 0, v[128:129]
	global_load_lds_dwordx4 v[218:219], off
	s_add_i32 m0, s76, 0x2000
	v_lshl_add_u64 v[222:223], s[42:43], 0, v[134:135]
	global_load_lds_dwordx4 v[220:221], off
	s_mov_b32 m0, s9
	v_lshl_add_u64 v[224:225], s[42:43], 0, v[130:131]
	global_load_lds_dwordx4 v[222:223], off
	s_mov_b32 m0, s54
	s_nop 0
	global_load_lds_dwordx4 v[224:225], off
	s_waitcnt vmcnt(8)
	s_waitcnt lgkmcnt(0)
	s_barrier
	s_waitcnt lgkmcnt(0)
	v_mfma_f32_16x16x32_bf16 v[60:63], v[150:153], v[182:185], v[60:63]
	v_mfma_f32_16x16x32_bf16 v[56:59], v[158:161], v[182:185], v[56:59]
	v_mfma_f32_16x16x32_bf16 v[44:47], v[150:153], v[190:193], v[44:47]
	v_mfma_f32_16x16x32_bf16 v[40:43], v[158:161], v[190:193], v[40:43]
	v_mfma_f32_16x16x32_bf16 v[28:31], v[150:153], v[198:201], v[28:31]
	v_mfma_f32_16x16x32_bf16 v[24:27], v[158:161], v[198:201], v[24:27]
	v_mfma_f32_16x16x32_bf16 v[12:15], v[150:153], v[206:209], v[12:15]
	v_mfma_f32_16x16x32_bf16 v[8:11], v[158:161], v[206:209], v[8:11]
	v_mfma_f32_16x16x32_bf16 v[60:63], v[154:157], v[186:189], v[60:63]
	v_mfma_f32_16x16x32_bf16 v[56:59], v[162:165], v[186:189], v[56:59]
	v_mfma_f32_16x16x32_bf16 v[44:47], v[154:157], v[194:197], v[44:47]
	v_mfma_f32_16x16x32_bf16 v[40:43], v[162:165], v[194:197], v[40:43]
	v_mfma_f32_16x16x32_bf16 v[28:31], v[154:157], v[202:205], v[28:31]
	v_mfma_f32_16x16x32_bf16 v[24:27], v[162:165], v[202:205], v[24:27]
	v_mfma_f32_16x16x32_bf16 v[12:15], v[154:157], v[210:213], v[12:15]
	v_mfma_f32_16x16x32_bf16 v[8:11], v[162:165], v[210:213], v[8:11]
	v_mfma_f32_16x16x32_bf16 v[52:55], v[166:169], v[182:185], v[52:55]
	v_mfma_f32_16x16x32_bf16 v[48:51], v[174:177], v[182:185], v[48:51]
	v_mfma_f32_16x16x32_bf16 v[36:39], v[166:169], v[190:193], v[36:39]
	v_mfma_f32_16x16x32_bf16 v[32:35], v[174:177], v[190:193], v[32:35]
	v_mfma_f32_16x16x32_bf16 v[20:23], v[166:169], v[198:201], v[20:23]
	v_mfma_f32_16x16x32_bf16 v[16:19], v[174:177], v[198:201], v[16:19]
	v_mfma_f32_16x16x32_bf16 v[4:7], v[166:169], v[206:209], v[4:7]
	v_mfma_f32_16x16x32_bf16 v[0:3], v[174:177], v[206:209], v[0:3]
	v_mfma_f32_16x16x32_bf16 v[52:55], v[170:173], v[186:189], v[52:55]
	v_mfma_f32_16x16x32_bf16 v[48:51], v[178:181], v[186:189], v[48:51]
	v_mfma_f32_16x16x32_bf16 v[36:39], v[170:173], v[194:197], v[36:39]
	v_mfma_f32_16x16x32_bf16 v[32:35], v[178:181], v[194:197], v[32:35]
	v_mfma_f32_16x16x32_bf16 v[20:23], v[170:173], v[202:205], v[20:23]
	v_mfma_f32_16x16x32_bf16 v[16:19], v[178:181], v[202:205], v[16:19]
	v_mfma_f32_16x16x32_bf16 v[4:7], v[170:173], v[210:213], v[4:7]
	v_mfma_f32_16x16x32_bf16 v[0:3], v[178:181], v[210:213], v[0:3]
	s_barrier
	s_add_i32 s74, 0, 0x18000
	s_add_i32 s75, 0, 0x1c000
	v_add_u32_e32 v162, s74, v145
	v_add_u32_e32 v178, s75, v145
	ds_read_b128 v[150:153], v162
	ds_read_b128 v[154:157], v162 offset:1024
	ds_read_b128 v[158:161], v162 offset:2048
	ds_read_b128 v[162:165], v162 offset:3072
	ds_read_b128 v[166:169], v178
	ds_read_b128 v[170:173], v178 offset:1024
	ds_read_b128 v[174:177], v178 offset:2048
	ds_read_b128 v[178:181], v178 offset:3072
	s_add_u32 s42, s42, s12
	s_addc_u32 s43, s43, s13
	s_mov_b32 m0, s55
	v_lshl_add_u64 v[226:227], s[42:43], 0, v[134:135]
	ds_read_b128 v[182:185], v149 offset:32768
	ds_read_b128 v[186:189], v149 offset:33792
	ds_read_b128 v[190:193], v149 offset:34816
	ds_read_b128 v[194:197], v149 offset:35840
	ds_read_b128 v[198:201], v149 offset:36864
	ds_read_b128 v[202:205], v149 offset:37888
	ds_read_b128 v[206:209], v149 offset:38912
	ds_read_b128 v[210:213], v149 offset:39936
	global_load_lds_dwordx4 v[226:227], off
	v_lshl_add_u64 v[226:227], s[42:43], 0, v[130:131]
	s_mov_b32 m0, s56
	s_nop 0
	global_load_lds_dwordx4 v[226:227], off
	s_waitcnt vmcnt(8)
	s_waitcnt lgkmcnt(0)
	s_barrier
	s_waitcnt lgkmcnt(0)
	v_mfma_f32_16x16x32_bf16 v[124:127], v[150:153], v[182:185], v[124:127]
	v_mfma_f32_16x16x32_bf16 v[120:123], v[158:161], v[182:185], v[120:123]
	v_mfma_f32_16x16x32_bf16 v[108:111], v[150:153], v[190:193], v[108:111]
	v_mfma_f32_16x16x32_bf16 v[104:107], v[158:161], v[190:193], v[104:107]
	v_mfma_f32_16x16x32_bf16 v[92:95], v[150:153], v[198:201], v[92:95]
	v_mfma_f32_16x16x32_bf16 v[88:91], v[158:161], v[198:201], v[88:91]
	v_mfma_f32_16x16x32_bf16 v[76:79], v[150:153], v[206:209], v[76:79]
	v_mfma_f32_16x16x32_bf16 v[72:75], v[158:161], v[206:209], v[72:75]
	v_mfma_f32_16x16x32_bf16 v[124:127], v[154:157], v[186:189], v[124:127]
	v_mfma_f32_16x16x32_bf16 v[120:123], v[162:165], v[186:189], v[120:123]
	v_mfma_f32_16x16x32_bf16 v[108:111], v[154:157], v[194:197], v[108:111]
	v_mfma_f32_16x16x32_bf16 v[104:107], v[162:165], v[194:197], v[104:107]
	v_mfma_f32_16x16x32_bf16 v[92:95], v[154:157], v[202:205], v[92:95]
	v_mfma_f32_16x16x32_bf16 v[88:91], v[162:165], v[202:205], v[88:91]
	v_mfma_f32_16x16x32_bf16 v[76:79], v[154:157], v[210:213], v[76:79]
	v_mfma_f32_16x16x32_bf16 v[72:75], v[162:165], v[210:213], v[72:75]
	v_mfma_f32_16x16x32_bf16 v[116:119], v[166:169], v[182:185], v[116:119]
	v_mfma_f32_16x16x32_bf16 v[112:115], v[174:177], v[182:185], v[112:115]
	v_mfma_f32_16x16x32_bf16 v[100:103], v[166:169], v[190:193], v[100:103]
	v_mfma_f32_16x16x32_bf16 v[96:99], v[174:177], v[190:193], v[96:99]
	v_mfma_f32_16x16x32_bf16 v[84:87], v[166:169], v[198:201], v[84:87]
	v_mfma_f32_16x16x32_bf16 v[80:83], v[174:177], v[198:201], v[80:83]
	v_mfma_f32_16x16x32_bf16 v[68:71], v[166:169], v[206:209], v[68:71]
	v_mfma_f32_16x16x32_bf16 v[64:67], v[174:177], v[206:209], v[64:67]
	v_mfma_f32_16x16x32_bf16 v[116:119], v[170:173], v[186:189], v[116:119]
	v_mfma_f32_16x16x32_bf16 v[112:115], v[178:181], v[186:189], v[112:115]
	v_mfma_f32_16x16x32_bf16 v[100:103], v[170:173], v[194:197], v[100:103]
	v_mfma_f32_16x16x32_bf16 v[96:99], v[178:181], v[194:197], v[96:99]
	v_mfma_f32_16x16x32_bf16 v[84:87], v[170:173], v[202:205], v[84:87]
	v_mfma_f32_16x16x32_bf16 v[80:83], v[178:181], v[202:205], v[80:83]
	v_mfma_f32_16x16x32_bf16 v[68:71], v[170:173], v[210:213], v[68:71]
	v_mfma_f32_16x16x32_bf16 v[64:67], v[178:181], v[210:213], v[64:67]
	s_barrier
	s_add_i32 s42, s74, s49
	v_lshl_add_u64 v[214:215], v[214:215], 0, s[20:21]
	s_mov_b32 m0, s42
	ds_read_b128 v[182:185], v149 offset:49152
	ds_read_b128 v[186:189], v149 offset:50176
	ds_read_b128 v[190:193], v149 offset:51200
	ds_read_b128 v[194:197], v149 offset:52224
	ds_read_b128 v[198:201], v149 offset:53248
	ds_read_b128 v[202:205], v149 offset:54272
	ds_read_b128 v[206:209], v149 offset:55296
	ds_read_b128 v[210:213], v149 offset:56320
	global_load_lds_dwordx4 v[214:215], off
	v_lshl_add_u64 v[214:215], v[216:217], 0, s[20:21]
	s_add_i32 m0, s42, 0x2000
	s_add_i32 s42, s75, s49
	global_load_lds_dwordx4 v[214:215], off
	v_lshl_add_u64 v[214:215], v[218:219], 0, s[20:21]
	s_mov_b32 m0, s42
	s_nop 0
	global_load_lds_dwordx4 v[214:215], off
	v_lshl_add_u64 v[214:215], v[220:221], 0, s[20:21]
	s_add_i32 m0, s42, 0x2000
	s_nop 0
	global_load_lds_dwordx4 v[214:215], off
	v_lshl_add_u64 v[214:215], v[222:223], 0, s[20:21]
	s_mov_b32 m0, s58
	s_nop 0
	global_load_lds_dwordx4 v[214:215], off
	v_lshl_add_u64 v[214:215], v[224:225], 0, s[20:21]
	s_mov_b32 m0, s59
	s_nop 0
	global_load_lds_dwordx4 v[214:215], off
	s_waitcnt vmcnt(8)
	s_waitcnt lgkmcnt(0)
	s_barrier
	s_waitcnt lgkmcnt(0)
	v_mfma_f32_16x16x32_bf16 v[60:63], v[150:153], v[182:185], v[60:63]
	v_mfma_f32_16x16x32_bf16 v[56:59], v[158:161], v[182:185], v[56:59]
	v_mfma_f32_16x16x32_bf16 v[44:47], v[150:153], v[190:193], v[44:47]
	v_mfma_f32_16x16x32_bf16 v[40:43], v[158:161], v[190:193], v[40:43]
	v_mfma_f32_16x16x32_bf16 v[28:31], v[150:153], v[198:201], v[28:31]
	v_mfma_f32_16x16x32_bf16 v[24:27], v[158:161], v[198:201], v[24:27]
	v_mfma_f32_16x16x32_bf16 v[12:15], v[150:153], v[206:209], v[12:15]
	v_mfma_f32_16x16x32_bf16 v[8:11], v[158:161], v[206:209], v[8:11]
	v_mfma_f32_16x16x32_bf16 v[60:63], v[154:157], v[186:189], v[60:63]
	v_mfma_f32_16x16x32_bf16 v[56:59], v[162:165], v[186:189], v[56:59]
	v_mfma_f32_16x16x32_bf16 v[44:47], v[154:157], v[194:197], v[44:47]
	v_mfma_f32_16x16x32_bf16 v[40:43], v[162:165], v[194:197], v[40:43]
	v_mfma_f32_16x16x32_bf16 v[28:31], v[154:157], v[202:205], v[28:31]
	v_mfma_f32_16x16x32_bf16 v[24:27], v[162:165], v[202:205], v[24:27]
	v_mfma_f32_16x16x32_bf16 v[12:15], v[154:157], v[210:213], v[12:15]
	v_mfma_f32_16x16x32_bf16 v[8:11], v[162:165], v[210:213], v[8:11]
	v_mfma_f32_16x16x32_bf16 v[52:55], v[166:169], v[182:185], v[52:55]
	v_mfma_f32_16x16x32_bf16 v[48:51], v[174:177], v[182:185], v[48:51]
	v_mfma_f32_16x16x32_bf16 v[36:39], v[166:169], v[190:193], v[36:39]
	v_mfma_f32_16x16x32_bf16 v[32:35], v[174:177], v[190:193], v[32:35]
	v_mfma_f32_16x16x32_bf16 v[20:23], v[166:169], v[198:201], v[20:23]
	v_mfma_f32_16x16x32_bf16 v[16:19], v[174:177], v[198:201], v[16:19]
	v_mfma_f32_16x16x32_bf16 v[4:7], v[166:169], v[206:209], v[4:7]
	v_mfma_f32_16x16x32_bf16 v[0:3], v[174:177], v[206:209], v[0:3]
	v_mfma_f32_16x16x32_bf16 v[52:55], v[170:173], v[186:189], v[52:55]
	v_mfma_f32_16x16x32_bf16 v[48:51], v[178:181], v[186:189], v[48:51]
	v_mfma_f32_16x16x32_bf16 v[36:39], v[170:173], v[194:197], v[36:39]
	v_mfma_f32_16x16x32_bf16 v[32:35], v[178:181], v[194:197], v[32:35]
	v_mfma_f32_16x16x32_bf16 v[20:23], v[170:173], v[202:205], v[20:23]
	v_mfma_f32_16x16x32_bf16 v[16:19], v[178:181], v[202:205], v[16:19]
	v_mfma_f32_16x16x32_bf16 v[4:7], v[170:173], v[210:213], v[4:7]
	v_mfma_f32_16x16x32_bf16 v[0:3], v[178:181], v[210:213], v[0:3]
	s_barrier
	s_add_u32 s40, s40, 0x100
	s_addc_u32 s41, s41, 0
	s_add_u32 s71, s71, 0x100
	s_addc_u32 s72, s72, 0
	s_cmp_ge_i32 s73, s60
	s_mov_b32 s42, s73
	s_cbranch_scc0 .LBB0_445
	s_setprio 0

.LBB0_472:
	v_mov_b32_e32 v123, 0
	s_andn2_b64 vcc, exec, s[40:41]
	v_mov_b32_e32 v122, v123
	v_mov_b32_e32 v121, v123
	v_mov_b32_e32 v120, v123
	v_mov_b32_e32 v127, v123
	v_mov_b32_e32 v126, v123
	v_mov_b32_e32 v125, v123
	v_mov_b32_e32 v124, v123
	v_mov_b32_e32 v111, v123
	v_mov_b32_e32 v110, v123
	v_mov_b32_e32 v109, v123
	v_mov_b32_e32 v108, v123
	v_mov_b32_e32 v107, v123
	v_mov_b32_e32 v106, v123
	v_mov_b32_e32 v105, v123
	v_mov_b32_e32 v104, v123
	v_mov_b32_e32 v95, v123
	v_mov_b32_e32 v94, v123
	v_mov_b32_e32 v93, v123
	v_mov_b32_e32 v92, v123
	v_mov_b32_e32 v91, v123
	v_mov_b32_e32 v90, v123
	v_mov_b32_e32 v89, v123
	v_mov_b32_e32 v88, v123
	v_mov_b32_e32 v79, v123
	v_mov_b32_e32 v78, v123
	v_mov_b32_e32 v77, v123
	v_mov_b32_e32 v76, v123
	v_mov_b32_e32 v75, v123
	v_mov_b32_e32 v74, v123
	v_mov_b32_e32 v73, v123
	v_mov_b32_e32 v72, v123
	v_mov_b32_e32 v119, v123
	v_mov_b32_e32 v118, v123
	v_mov_b32_e32 v117, v123
	v_mov_b32_e32 v116, v123
	v_mov_b32_e32 v115, v123
	v_mov_b32_e32 v114, v123
	v_mov_b32_e32 v113, v123
	v_mov_b32_e32 v112, v123
	v_mov_b32_e32 v103, v123
	v_mov_b32_e32 v102, v123
	v_mov_b32_e32 v101, v123
	v_mov_b32_e32 v100, v123
	v_mov_b32_e32 v99, v123
	v_mov_b32_e32 v98, v123
	v_mov_b32_e32 v97, v123
	v_mov_b32_e32 v96, v123
	v_mov_b32_e32 v87, v123
	v_mov_b32_e32 v86, v123
	v_mov_b32_e32 v85, v123
	v_mov_b32_e32 v84, v123
	v_mov_b32_e32 v83, v123
	v_mov_b32_e32 v82, v123
	v_mov_b32_e32 v81, v123
	v_mov_b32_e32 v80, v123
	v_mov_b32_e32 v71, v123
	v_mov_b32_e32 v70, v123
	v_mov_b32_e32 v69, v123
	v_mov_b32_e32 v68, v123
	v_mov_b32_e32 v67, v123
	v_mov_b32_e32 v66, v123
	v_mov_b32_e32 v65, v123
	v_mov_b32_e32 v64, v123
	v_mov_b32_e32 v63, v123
	v_mov_b32_e32 v62, v123
	v_mov_b32_e32 v61, v123
	v_mov_b32_e32 v60, v123
	v_mov_b32_e32 v59, v123
	v_mov_b32_e32 v58, v123
	v_mov_b32_e32 v57, v123
	v_mov_b32_e32 v56, v123
	v_mov_b32_e32 v47, v123
	v_mov_b32_e32 v46, v123
	v_mov_b32_e32 v45, v123
	v_mov_b32_e32 v44, v123
	v_mov_b32_e32 v43, v123
	v_mov_b32_e32 v42, v123
	v_mov_b32_e32 v41, v123
	v_mov_b32_e32 v40, v123
	v_mov_b32_e32 v31, v123
	v_mov_b32_e32 v30, v123
	v_mov_b32_e32 v29, v123
	v_mov_b32_e32 v28, v123
	v_mov_b32_e32 v27, v123
	v_mov_b32_e32 v26, v123
	v_mov_b32_e32 v25, v123
	v_mov_b32_e32 v24, v123
	v_mov_b32_e32 v15, v123
	v_mov_b32_e32 v14, v123
	v_mov_b32_e32 v13, v123
	v_mov_b32_e32 v12, v123
	v_mov_b32_e32 v11, v123
	v_mov_b32_e32 v10, v123
	v_mov_b32_e32 v9, v123
	v_mov_b32_e32 v8, v123
	v_mov_b32_e32 v55, v123
	v_mov_b32_e32 v54, v123
	v_mov_b32_e32 v53, v123
	v_mov_b32_e32 v52, v123
	v_mov_b32_e32 v51, v123
	v_mov_b32_e32 v50, v123
	v_mov_b32_e32 v49, v123
	v_mov_b32_e32 v48, v123
	v_mov_b32_e32 v39, v123
	v_mov_b32_e32 v38, v123
	v_mov_b32_e32 v37, v123
	v_mov_b32_e32 v36, v123
	v_mov_b32_e32 v35, v123
	v_mov_b32_e32 v34, v123
	v_mov_b32_e32 v33, v123
	v_mov_b32_e32 v32, v123
	v_mov_b32_e32 v23, v123
	v_mov_b32_e32 v22, v123
	v_mov_b32_e32 v21, v123
	v_mov_b32_e32 v20, v123
	v_mov_b32_e32 v19, v123
	v_mov_b32_e32 v18, v123
	v_mov_b32_e32 v17, v123
	v_mov_b32_e32 v16, v123
	v_mov_b32_e32 v7, v123
	v_mov_b32_e32 v6, v123
	v_mov_b32_e32 v5, v123
	v_mov_b32_e32 v4, v123
	v_mov_b32_e32 v3, v123
	v_mov_b32_e32 v2, v123
	v_mov_b32_e32 v1, v123
	v_mov_b32_e32 v0, v123
	s_cbranch_vccnz .LBB0_475
	s_add_u32 s62, s62, 0x80
	s_addc_u32 s63, s63, 0
	s_add_u32 s91, s64, 0x100
	v_mov_b32_e32 v0, 0
	s_addc_u32 s92, s65, 0
	s_mov_b32 s64, 0
	v_mov_b32_e32 v1, v0
	v_mov_b32_e32 v2, v0
	v_mov_b32_e32 v3, v0
	v_mov_b32_e32 v4, v0
	v_mov_b32_e32 v5, v0
	v_mov_b32_e32 v6, v0
	v_mov_b32_e32 v7, v0
	v_mov_b32_e32 v16, v0
	v_mov_b32_e32 v17, v0
	v_mov_b32_e32 v18, v0
	v_mov_b32_e32 v19, v0
	v_mov_b32_e32 v20, v0
	v_mov_b32_e32 v21, v0
	v_mov_b32_e32 v22, v0
	v_mov_b32_e32 v23, v0
	v_mov_b32_e32 v32, v0
	v_mov_b32_e32 v33, v0
	v_mov_b32_e32 v34, v0
	v_mov_b32_e32 v35, v0
	v_mov_b32_e32 v36, v0
	v_mov_b32_e32 v37, v0
	v_mov_b32_e32 v38, v0
	v_mov_b32_e32 v39, v0
	v_mov_b32_e32 v48, v0
	v_mov_b32_e32 v49, v0
	v_mov_b32_e32 v50, v0
	v_mov_b32_e32 v51, v0
	v_mov_b32_e32 v52, v0
	v_mov_b32_e32 v53, v0
	v_mov_b32_e32 v54, v0
	v_mov_b32_e32 v55, v0
	v_mov_b32_e32 v8, v0
	v_mov_b32_e32 v9, v0
	v_mov_b32_e32 v10, v0
	v_mov_b32_e32 v11, v0
	v_mov_b32_e32 v12, v0
	v_mov_b32_e32 v13, v0
	v_mov_b32_e32 v14, v0
	v_mov_b32_e32 v15, v0
	v_mov_b32_e32 v24, v0
	v_mov_b32_e32 v25, v0
	v_mov_b32_e32 v26, v0
	v_mov_b32_e32 v27, v0
	v_mov_b32_e32 v28, v0
	v_mov_b32_e32 v29, v0
	v_mov_b32_e32 v30, v0
	v_mov_b32_e32 v31, v0
	v_mov_b32_e32 v40, v0
	v_mov_b32_e32 v41, v0
	v_mov_b32_e32 v42, v0
	v_mov_b32_e32 v43, v0
	v_mov_b32_e32 v44, v0
	v_mov_b32_e32 v45, v0
	v_mov_b32_e32 v46, v0
	v_mov_b32_e32 v47, v0
	v_mov_b32_e32 v56, v0
	v_mov_b32_e32 v57, v0
	v_mov_b32_e32 v58, v0
	v_mov_b32_e32 v59, v0
	v_mov_b32_e32 v60, v0
	v_mov_b32_e32 v61, v0
	v_mov_b32_e32 v62, v0
	v_mov_b32_e32 v63, v0
	v_mov_b32_e32 v64, v0
	v_mov_b32_e32 v65, v0
	v_mov_b32_e32 v66, v0
	v_mov_b32_e32 v67, v0
	v_mov_b32_e32 v68, v0
	v_mov_b32_e32 v69, v0
	v_mov_b32_e32 v70, v0
	v_mov_b32_e32 v71, v0
	v_mov_b32_e32 v80, v0
	v_mov_b32_e32 v81, v0
	v_mov_b32_e32 v82, v0
	v_mov_b32_e32 v83, v0
	v_mov_b32_e32 v84, v0
	v_mov_b32_e32 v85, v0
	v_mov_b32_e32 v86, v0
	v_mov_b32_e32 v87, v0
	v_mov_b32_e32 v96, v0
	v_mov_b32_e32 v97, v0
	v_mov_b32_e32 v98, v0
	v_mov_b32_e32 v99, v0
	v_mov_b32_e32 v100, v0
	v_mov_b32_e32 v101, v0
	v_mov_b32_e32 v102, v0
	v_mov_b32_e32 v103, v0
	v_mov_b32_e32 v112, v0
	v_mov_b32_e32 v113, v0
	v_mov_b32_e32 v114, v0
	v_mov_b32_e32 v115, v0
	v_mov_b32_e32 v116, v0
	v_mov_b32_e32 v117, v0
	v_mov_b32_e32 v118, v0
	v_mov_b32_e32 v119, v0
	v_mov_b32_e32 v72, v0
	v_mov_b32_e32 v73, v0
	v_mov_b32_e32 v74, v0
	v_mov_b32_e32 v75, v0
	v_mov_b32_e32 v76, v0
	v_mov_b32_e32 v77, v0
	v_mov_b32_e32 v78, v0
	v_mov_b32_e32 v79, v0
	v_mov_b32_e32 v88, v0
	v_mov_b32_e32 v89, v0
	v_mov_b32_e32 v90, v0
	v_mov_b32_e32 v91, v0
	v_mov_b32_e32 v92, v0
	v_mov_b32_e32 v93, v0
	v_mov_b32_e32 v94, v0
	v_mov_b32_e32 v95, v0
	v_mov_b32_e32 v104, v0
	v_mov_b32_e32 v105, v0
	v_mov_b32_e32 v106, v0
	v_mov_b32_e32 v107, v0
	v_mov_b32_e32 v108, v0
	v_mov_b32_e32 v109, v0
	v_mov_b32_e32 v110, v0
	v_mov_b32_e32 v111, v0
	v_mov_b32_e32 v124, v0
	v_mov_b32_e32 v125, v0
	v_mov_b32_e32 v126, v0
	v_mov_b32_e32 v127, v0
	v_mov_b32_e32 v120, v0
	v_mov_b32_e32 v121, v0
	v_mov_b32_e32 v122, v0
	v_mov_b32_e32 v123, v0
	s_and_b64 vcc, exec, s[42:43]
	s_cbranch_vccnz .Lmy_pr_2
	s_setprio 1
.Lmy_pr_2:
.LBB0_474:
	ds_read_b128 v[150:153], v147
	ds_read_b128 v[154:157], v147 offset:1024
	ds_read_b128 v[158:161], v147 offset:2048
	ds_read_b128 v[162:165], v147 offset:3072
	ds_read_b128 v[166:169], v148
	ds_read_b128 v[170:173], v148 offset:1024
	ds_read_b128 v[174:177], v148 offset:2048
	ds_read_b128 v[178:181], v148 offset:3072
	s_add_i32 s93, s64, 2
	s_add_u32 s94, s62, 0x80
	s_addc_u32 s65, s63, 0
	s_cmp_eq_u32 s75, s64
	s_cselect_b32 s64, s4, s94
	s_cselect_b32 s65, s5, s65
	s_cselect_b32 s95, s61, s92
	s_cselect_b32 s94, s60, s91
	v_lshl_add_u64 v[214:215], s[62:63], 0, v[136:137]
	s_add_i32 m0, s69, 0xc000
	ds_read_b128 v[182:185], v149
	ds_read_b128 v[186:189], v149 offset:1024
	ds_read_b128 v[190:193], v149 offset:2048
	ds_read_b128 v[194:197], v149 offset:3072
	ds_read_b128 v[198:201], v149 offset:4096
	ds_read_b128 v[202:205], v149 offset:5120
	ds_read_b128 v[206:209], v149 offset:6144
	ds_read_b128 v[210:213], v149 offset:7168
	global_load_lds_dwordx4 v[214:215], off
	v_lshl_add_u64 v[214:215], s[62:63], 0, v[138:139]
	s_add_i32 m0, s69, 0xe000
	s_nop 0
	global_load_lds_dwordx4 v[214:215], off
	s_waitcnt vmcnt(8)
	s_waitcnt lgkmcnt(0)
	s_barrier
	s_waitcnt lgkmcnt(0)
	v_mfma_f32_16x16x32_bf16 v[120:123], v[150:153], v[182:185], v[120:123]
	v_mfma_f32_16x16x32_bf16 v[124:127], v[158:161], v[182:185], v[124:127]
	v_mfma_f32_16x16x32_bf16 v[108:111], v[150:153], v[190:193], v[108:111]
	v_mfma_f32_16x16x32_bf16 v[104:107], v[158:161], v[190:193], v[104:107]
	v_mfma_f32_16x16x32_bf16 v[92:95], v[150:153], v[198:201], v[92:95]
	v_mfma_f32_16x16x32_bf16 v[88:91], v[158:161], v[198:201], v[88:91]
	v_mfma_f32_16x16x32_bf16 v[76:79], v[150:153], v[206:209], v[76:79]
	v_mfma_f32_16x16x32_bf16 v[72:75], v[158:161], v[206:209], v[72:75]
	v_mfma_f32_16x16x32_bf16 v[120:123], v[154:157], v[186:189], v[120:123]
	v_mfma_f32_16x16x32_bf16 v[124:127], v[162:165], v[186:189], v[124:127]
	v_mfma_f32_16x16x32_bf16 v[108:111], v[154:157], v[194:197], v[108:111]
	v_mfma_f32_16x16x32_bf16 v[104:107], v[162:165], v[194:197], v[104:107]
	v_mfma_f32_16x16x32_bf16 v[92:95], v[154:157], v[202:205], v[92:95]
	v_mfma_f32_16x16x32_bf16 v[88:91], v[162:165], v[202:205], v[88:91]
	v_mfma_f32_16x16x32_bf16 v[76:79], v[154:157], v[210:213], v[76:79]
	v_mfma_f32_16x16x32_bf16 v[72:75], v[162:165], v[210:213], v[72:75]
	v_mfma_f32_16x16x32_bf16 v[116:119], v[166:169], v[182:185], v[116:119]
	v_mfma_f32_16x16x32_bf16 v[112:115], v[174:177], v[182:185], v[112:115]
	v_mfma_f32_16x16x32_bf16 v[100:103], v[166:169], v[190:193], v[100:103]
	v_mfma_f32_16x16x32_bf16 v[96:99], v[174:177], v[190:193], v[96:99]
	v_mfma_f32_16x16x32_bf16 v[84:87], v[166:169], v[198:201], v[84:87]
	v_mfma_f32_16x16x32_bf16 v[80:83], v[174:177], v[198:201], v[80:83]
	v_mfma_f32_16x16x32_bf16 v[68:71], v[166:169], v[206:209], v[68:71]
	v_mfma_f32_16x16x32_bf16 v[64:67], v[174:177], v[206:209], v[64:67]
	v_mfma_f32_16x16x32_bf16 v[116:119], v[170:173], v[186:189], v[116:119]
	v_mfma_f32_16x16x32_bf16 v[112:115], v[178:181], v[186:189], v[112:115]
	v_mfma_f32_16x16x32_bf16 v[100:103], v[170:173], v[194:197], v[100:103]
	v_mfma_f32_16x16x32_bf16 v[96:99], v[178:181], v[194:197], v[96:99]
	v_mfma_f32_16x16x32_bf16 v[84:87], v[170:173], v[202:205], v[84:87]
	v_mfma_f32_16x16x32_bf16 v[80:83], v[178:181], v[202:205], v[80:83]
	v_mfma_f32_16x16x32_bf16 v[68:71], v[170:173], v[210:213], v[68:71]
	v_mfma_f32_16x16x32_bf16 v[64:67], v[178:181], v[210:213], v[64:67]
	s_barrier
	s_add_i32 s96, s80, s68
	v_lshl_add_u64 v[214:215], s[94:95], 0, v[130:131]
	s_mov_b32 m0, s96
	ds_read_b128 v[182:185], v149 offset:16384
	ds_read_b128 v[186:189], v149 offset:17408
	ds_read_b128 v[190:193], v149 offset:18432
	ds_read_b128 v[194:197], v149 offset:19456
	ds_read_b128 v[198:201], v149 offset:20480
	ds_read_b128 v[202:205], v149 offset:21504
	ds_read_b128 v[206:209], v149 offset:22528
	ds_read_b128 v[210:213], v149 offset:23552
	global_load_lds_dwordx4 v[214:215], off
	s_add_i32 m0, s96, 0x2000
	v_lshl_add_u64 v[216:217], s[94:95], 0, v[134:135]
	s_add_u32 s94, s94, s6
	s_addc_u32 s95, s95, s7
	s_add_i32 s96, s81, s68
	global_load_lds_dwordx4 v[216:217], off
	v_lshl_add_u64 v[218:219], s[94:95], 0, v[130:131]
	s_mov_b32 m0, s96
	v_lshl_add_u64 v[220:221], s[94:95], 0, v[134:135]
	global_load_lds_dwordx4 v[218:219], off
	s_add_i32 m0, s96, 0x2000
	v_lshl_add_u64 v[222:223], s[64:65], 0, v[128:129]
	global_load_lds_dwordx4 v[220:221], off
	s_mov_b32 m0, s69
	v_lshl_add_u64 v[224:225], s[64:65], 0, v[132:133]
	global_load_lds_dwordx4 v[222:223], off
	s_mov_b32 m0, s8
	s_nop 0
	global_load_lds_dwordx4 v[224:225], off
	s_waitcnt vmcnt(8)
	s_waitcnt lgkmcnt(0)
	s_barrier
	s_waitcnt lgkmcnt(0)
	v_mfma_f32_16x16x32_bf16 v[60:63], v[150:153], v[182:185], v[60:63]
	v_mfma_f32_16x16x32_bf16 v[56:59], v[158:161], v[182:185], v[56:59]
	v_mfma_f32_16x16x32_bf16 v[44:47], v[150:153], v[190:193], v[44:47]
	v_mfma_f32_16x16x32_bf16 v[40:43], v[158:161], v[190:193], v[40:43]
	v_mfma_f32_16x16x32_bf16 v[28:31], v[150:153], v[198:201], v[28:31]
	v_mfma_f32_16x16x32_bf16 v[24:27], v[158:161], v[198:201], v[24:27]
	v_mfma_f32_16x16x32_bf16 v[12:15], v[150:153], v[206:209], v[12:15]
	v_mfma_f32_16x16x32_bf16 v[8:11], v[158:161], v[206:209], v[8:11]
	v_mfma_f32_16x16x32_bf16 v[60:63], v[154:157], v[186:189], v[60:63]
	v_mfma_f32_16x16x32_bf16 v[56:59], v[162:165], v[186:189], v[56:59]
	v_mfma_f32_16x16x32_bf16 v[44:47], v[154:157], v[194:197], v[44:47]
	v_mfma_f32_16x16x32_bf16 v[40:43], v[162:165], v[194:197], v[40:43]
	v_mfma_f32_16x16x32_bf16 v[28:31], v[154:157], v[202:205], v[28:31]
	v_mfma_f32_16x16x32_bf16 v[24:27], v[162:165], v[202:205], v[24:27]
	v_mfma_f32_16x16x32_bf16 v[12:15], v[154:157], v[210:213], v[12:15]
	v_mfma_f32_16x16x32_bf16 v[8:11], v[162:165], v[210:213], v[8:11]
	v_mfma_f32_16x16x32_bf16 v[52:55], v[166:169], v[182:185], v[52:55]
	v_mfma_f32_16x16x32_bf16 v[48:51], v[174:177], v[182:185], v[48:51]
	v_mfma_f32_16x16x32_bf16 v[36:39], v[166:169], v[190:193], v[36:39]
	v_mfma_f32_16x16x32_bf16 v[32:35], v[174:177], v[190:193], v[32:35]
	v_mfma_f32_16x16x32_bf16 v[20:23], v[166:169], v[198:201], v[20:23]
	v_mfma_f32_16x16x32_bf16 v[16:19], v[174:177], v[198:201], v[16:19]
	v_mfma_f32_16x16x32_bf16 v[4:7], v[166:169], v[206:209], v[4:7]
	v_mfma_f32_16x16x32_bf16 v[0:3], v[174:177], v[206:209], v[0:3]
	v_mfma_f32_16x16x32_bf16 v[52:55], v[170:173], v[186:189], v[52:55]
	v_mfma_f32_16x16x32_bf16 v[48:51], v[178:181], v[186:189], v[48:51]
	v_mfma_f32_16x16x32_bf16 v[36:39], v[170:173], v[194:197], v[36:39]
	v_mfma_f32_16x16x32_bf16 v[32:35], v[178:181], v[194:197], v[32:35]
	v_mfma_f32_16x16x32_bf16 v[20:23], v[170:173], v[202:205], v[20:23]
	v_mfma_f32_16x16x32_bf16 v[16:19], v[178:181], v[202:205], v[16:19]
	v_mfma_f32_16x16x32_bf16 v[4:7], v[170:173], v[210:213], v[4:7]
	v_mfma_f32_16x16x32_bf16 v[0:3], v[178:181], v[210:213], v[0:3]
	s_barrier
	s_add_i32 s94, 0, 0x18000
	s_add_i32 s95, 0, 0x1c000
	v_add_u32_e32 v162, s94, v145
	v_add_u32_e32 v178, s95, v145
	ds_read_b128 v[150:153], v162
	ds_read_b128 v[154:157], v162 offset:1024
	ds_read_b128 v[158:161], v162 offset:2048
	ds_read_b128 v[162:165], v162 offset:3072
	ds_read_b128 v[166:169], v178
	ds_read_b128 v[170:173], v178 offset:1024
	ds_read_b128 v[174:177], v178 offset:2048
	ds_read_b128 v[178:181], v178 offset:3072
	s_add_u32 s64, s64, s6
	s_addc_u32 s65, s65, s7
	s_mov_b32 m0, s9
	v_lshl_add_u64 v[226:227], s[64:65], 0, v[128:129]
	ds_read_b128 v[182:185], v149 offset:32768
	ds_read_b128 v[186:189], v149 offset:33792
	ds_read_b128 v[190:193], v149 offset:34816
	ds_read_b128 v[194:197], v149 offset:35840
	ds_read_b128 v[198:201], v149 offset:36864
	ds_read_b128 v[202:205], v149 offset:37888
	ds_read_b128 v[206:209], v149 offset:38912
	ds_read_b128 v[210:213], v149 offset:39936
	global_load_lds_dwordx4 v[226:227], off
	v_lshl_add_u64 v[226:227], s[64:65], 0, v[132:133]
	s_mov_b32 m0, s70
	s_nop 0
	global_load_lds_dwordx4 v[226:227], off
	s_waitcnt vmcnt(8)
	s_waitcnt lgkmcnt(0)
	s_barrier
	s_waitcnt lgkmcnt(0)
	v_mfma_f32_16x16x32_bf16 v[120:123], v[150:153], v[182:185], v[120:123]
	v_mfma_f32_16x16x32_bf16 v[124:127], v[158:161], v[182:185], v[124:127]
	v_mfma_f32_16x16x32_bf16 v[108:111], v[150:153], v[190:193], v[108:111]
	v_mfma_f32_16x16x32_bf16 v[104:107], v[158:161], v[190:193], v[104:107]
	v_mfma_f32_16x16x32_bf16 v[92:95], v[150:153], v[198:201], v[92:95]
	v_mfma_f32_16x16x32_bf16 v[88:91], v[158:161], v[198:201], v[88:91]
	v_mfma_f32_16x16x32_bf16 v[76:79], v[150:153], v[206:209], v[76:79]
	v_mfma_f32_16x16x32_bf16 v[72:75], v[158:161], v[206:209], v[72:75]
	v_mfma_f32_16x16x32_bf16 v[120:123], v[154:157], v[186:189], v[120:123]
	v_mfma_f32_16x16x32_bf16 v[124:127], v[162:165], v[186:189], v[124:127]
	v_mfma_f32_16x16x32_bf16 v[108:111], v[154:157], v[194:197], v[108:111]
	v_mfma_f32_16x16x32_bf16 v[104:107], v[162:165], v[194:197], v[104:107]
	v_mfma_f32_16x16x32_bf16 v[92:95], v[154:157], v[202:205], v[92:95]
	v_mfma_f32_16x16x32_bf16 v[88:91], v[162:165], v[202:205], v[88:91]
	v_mfma_f32_16x16x32_bf16 v[76:79], v[154:157], v[210:213], v[76:79]
	v_mfma_f32_16x16x32_bf16 v[72:75], v[162:165], v[210:213], v[72:75]
	v_mfma_f32_16x16x32_bf16 v[116:119], v[166:169], v[182:185], v[116:119]
	v_mfma_f32_16x16x32_bf16 v[112:115], v[174:177], v[182:185], v[112:115]
	v_mfma_f32_16x16x32_bf16 v[100:103], v[166:169], v[190:193], v[100:103]
	v_mfma_f32_16x16x32_bf16 v[96:99], v[174:177], v[190:193], v[96:99]
	v_mfma_f32_16x16x32_bf16 v[84:87], v[166:169], v[198:201], v[84:87]
	v_mfma_f32_16x16x32_bf16 v[80:83], v[174:177], v[198:201], v[80:83]
	v_mfma_f32_16x16x32_bf16 v[68:71], v[166:169], v[206:209], v[68:71]
	v_mfma_f32_16x16x32_bf16 v[64:67], v[174:177], v[206:209], v[64:67]
	v_mfma_f32_16x16x32_bf16 v[116:119], v[170:173], v[186:189], v[116:119]
	v_mfma_f32_16x16x32_bf16 v[112:115], v[178:181], v[186:189], v[112:115]
	v_mfma_f32_16x16x32_bf16 v[100:103], v[170:173], v[194:197], v[100:103]
	v_mfma_f32_16x16x32_bf16 v[96:99], v[178:181], v[194:197], v[96:99]
	v_mfma_f32_16x16x32_bf16 v[84:87], v[170:173], v[202:205], v[84:87]
	v_mfma_f32_16x16x32_bf16 v[80:83], v[178:181], v[202:205], v[80:83]
	v_mfma_f32_16x16x32_bf16 v[68:71], v[170:173], v[210:213], v[68:71]
	v_mfma_f32_16x16x32_bf16 v[64:67], v[178:181], v[210:213], v[64:67]
	s_barrier
	s_add_i32 s64, s94, s68
	v_lshl_add_u64 v[214:215], v[214:215], 0, s[38:39]
	s_mov_b32 m0, s64
	ds_read_b128 v[182:185], v149 offset:49152
	ds_read_b128 v[186:189], v149 offset:50176
	ds_read_b128 v[190:193], v149 offset:51200
	ds_read_b128 v[194:197], v149 offset:52224
	ds_read_b128 v[198:201], v149 offset:53248
	ds_read_b128 v[202:205], v149 offset:54272
	ds_read_b128 v[206:209], v149 offset:55296
	ds_read_b128 v[210:213], v149 offset:56320
	global_load_lds_dwordx4 v[214:215], off
	v_lshl_add_u64 v[214:215], v[216:217], 0, s[38:39]
	s_add_i32 m0, s64, 0x2000
	s_add_i32 s64, s95, s68
	global_load_lds_dwordx4 v[214:215], off
	v_lshl_add_u64 v[214:215], v[218:219], 0, s[38:39]
	s_mov_b32 m0, s64
	s_nop 0
	global_load_lds_dwordx4 v[214:215], off
	v_lshl_add_u64 v[214:215], v[220:221], 0, s[38:39]
	s_add_i32 m0, s64, 0x2000
	s_nop 0
	global_load_lds_dwordx4 v[214:215], off
	v_lshl_add_u64 v[214:215], v[222:223], 0, s[38:39]
	s_mov_b32 m0, s72
	s_nop 0
	global_load_lds_dwordx4 v[214:215], off
	v_lshl_add_u64 v[214:215], v[224:225], 0, s[38:39]
	s_mov_b32 m0, s73
	s_nop 0
	global_load_lds_dwordx4 v[214:215], off
	s_waitcnt vmcnt(8)
	s_waitcnt lgkmcnt(0)
	s_barrier
	s_waitcnt lgkmcnt(0)
	v_mfma_f32_16x16x32_bf16 v[60:63], v[150:153], v[182:185], v[60:63]
	v_mfma_f32_16x16x32_bf16 v[56:59], v[158:161], v[182:185], v[56:59]
	v_mfma_f32_16x16x32_bf16 v[44:47], v[150:153], v[190:193], v[44:47]
	v_mfma_f32_16x16x32_bf16 v[40:43], v[158:161], v[190:193], v[40:43]
	v_mfma_f32_16x16x32_bf16 v[28:31], v[150:153], v[198:201], v[28:31]
	v_mfma_f32_16x16x32_bf16 v[24:27], v[158:161], v[198:201], v[24:27]
	v_mfma_f32_16x16x32_bf16 v[12:15], v[150:153], v[206:209], v[12:15]
	v_mfma_f32_16x16x32_bf16 v[8:11], v[158:161], v[206:209], v[8:11]
	v_mfma_f32_16x16x32_bf16 v[60:63], v[154:157], v[186:189], v[60:63]
	v_mfma_f32_16x16x32_bf16 v[56:59], v[162:165], v[186:189], v[56:59]
	v_mfma_f32_16x16x32_bf16 v[44:47], v[154:157], v[194:197], v[44:47]
	v_mfma_f32_16x16x32_bf16 v[40:43], v[162:165], v[194:197], v[40:43]
	v_mfma_f32_16x16x32_bf16 v[28:31], v[154:157], v[202:205], v[28:31]
	v_mfma_f32_16x16x32_bf16 v[24:27], v[162:165], v[202:205], v[24:27]
	v_mfma_f32_16x16x32_bf16 v[12:15], v[154:157], v[210:213], v[12:15]
	v_mfma_f32_16x16x32_bf16 v[8:11], v[162:165], v[210:213], v[8:11]
	v_mfma_f32_16x16x32_bf16 v[52:55], v[166:169], v[182:185], v[52:55]
	v_mfma_f32_16x16x32_bf16 v[48:51], v[174:177], v[182:185], v[48:51]
	v_mfma_f32_16x16x32_bf16 v[36:39], v[166:169], v[190:193], v[36:39]
	v_mfma_f32_16x16x32_bf16 v[32:35], v[174:177], v[190:193], v[32:35]
	v_mfma_f32_16x16x32_bf16 v[20:23], v[166:169], v[198:201], v[20:23]
	v_mfma_f32_16x16x32_bf16 v[16:19], v[174:177], v[198:201], v[16:19]
	v_mfma_f32_16x16x32_bf16 v[4:7], v[166:169], v[206:209], v[4:7]
	v_mfma_f32_16x16x32_bf16 v[0:3], v[174:177], v[206:209], v[0:3]
	v_mfma_f32_16x16x32_bf16 v[52:55], v[170:173], v[186:189], v[52:55]
	v_mfma_f32_16x16x32_bf16 v[48:51], v[178:181], v[186:189], v[48:51]
	v_mfma_f32_16x16x32_bf16 v[36:39], v[170:173], v[194:197], v[36:39]
	v_mfma_f32_16x16x32_bf16 v[32:35], v[178:181], v[194:197], v[32:35]
	v_mfma_f32_16x16x32_bf16 v[20:23], v[170:173], v[202:205], v[20:23]
	v_mfma_f32_16x16x32_bf16 v[16:19], v[178:181], v[202:205], v[16:19]
	v_mfma_f32_16x16x32_bf16 v[4:7], v[170:173], v[210:213], v[4:7]
	v_mfma_f32_16x16x32_bf16 v[0:3], v[178:181], v[210:213], v[0:3]
	s_barrier
	s_add_u32 s62, s62, 0x100
	s_addc_u32 s63, s63, 0
	s_add_u32 s91, s91, 0x100
	s_addc_u32 s92, s92, 0
	s_cmp_ge_i32 s93, s74
	s_mov_b32 s64, s93
	s_cbranch_scc0 .LBB0_474
	s_setprio 0

.LBB0_656:
	s_ashr_i32 s47, s46, 31
	s_lshl_b64 s[8:9], s[46:47], 19
	s_add_u32 s48, s78, s8
	s_addc_u32 s49, s79, s9
	s_and_b64 s[8:9], s[6:7], exec
	s_cselect_b32 s8, s49, s59
	s_cselect_b32 s9, s48, s58
	s_ashr_i32 s45, s44, 31
	s_lshl_b64 s[54:55], s[44:45], 19
	s_add_u32 s54, s35, s54
	s_addc_u32 s55, s68, s55
	s_and_b64 s[62:63], s[6:7], exec
	s_cselect_b32 s45, s55, s61
	s_cselect_b32 s47, s54, s60
	s_add_u32 s58, s58, 0x40080
	s_addc_u32 s59, s59, 0
	s_add_u32 s57, s60, 0x100
	v_mov_b32_e32 v0, 0
	s_addc_u32 s64, s61, 0
	s_mov_b32 s65, -2
	v_mov_b32_e32 v1, v0
	v_mov_b32_e32 v2, v0
	v_mov_b32_e32 v3, v0
	v_mov_b32_e32 v4, v0
	v_mov_b32_e32 v5, v0
	v_mov_b32_e32 v6, v0
	v_mov_b32_e32 v7, v0
	v_mov_b32_e32 v16, v0
	v_mov_b32_e32 v17, v0
	v_mov_b32_e32 v18, v0
	v_mov_b32_e32 v19, v0
	v_mov_b32_e32 v20, v0
	v_mov_b32_e32 v21, v0
	v_mov_b32_e32 v22, v0
	v_mov_b32_e32 v23, v0
	v_mov_b32_e32 v32, v0
	v_mov_b32_e32 v33, v0
	v_mov_b32_e32 v34, v0
	v_mov_b32_e32 v35, v0
	v_mov_b32_e32 v36, v0
	v_mov_b32_e32 v37, v0
	v_mov_b32_e32 v38, v0
	v_mov_b32_e32 v39, v0
	v_mov_b32_e32 v48, v0
	v_mov_b32_e32 v49, v0
	v_mov_b32_e32 v50, v0
	v_mov_b32_e32 v51, v0
	v_mov_b32_e32 v52, v0
	v_mov_b32_e32 v53, v0
	v_mov_b32_e32 v54, v0
	v_mov_b32_e32 v55, v0
	v_mov_b32_e32 v8, v0
	v_mov_b32_e32 v9, v0
	v_mov_b32_e32 v10, v0
	v_mov_b32_e32 v11, v0
	v_mov_b32_e32 v12, v0
	v_mov_b32_e32 v13, v0
	v_mov_b32_e32 v14, v0
	v_mov_b32_e32 v15, v0
	v_mov_b32_e32 v24, v0
	v_mov_b32_e32 v25, v0
	v_mov_b32_e32 v26, v0
	v_mov_b32_e32 v27, v0
	v_mov_b32_e32 v28, v0
	v_mov_b32_e32 v29, v0
	v_mov_b32_e32 v30, v0
	v_mov_b32_e32 v31, v0
	v_mov_b32_e32 v40, v0
	v_mov_b32_e32 v41, v0
	v_mov_b32_e32 v42, v0
	v_mov_b32_e32 v43, v0
	v_mov_b32_e32 v44, v0
	v_mov_b32_e32 v45, v0
	v_mov_b32_e32 v46, v0
	v_mov_b32_e32 v47, v0
	v_mov_b32_e32 v56, v0
	v_mov_b32_e32 v57, v0
	v_mov_b32_e32 v58, v0
	v_mov_b32_e32 v59, v0
	v_mov_b32_e32 v60, v0
	v_mov_b32_e32 v61, v0
	v_mov_b32_e32 v62, v0
	v_mov_b32_e32 v63, v0
	v_mov_b32_e32 v64, v0
	v_mov_b32_e32 v65, v0
	v_mov_b32_e32 v66, v0
	v_mov_b32_e32 v67, v0
	v_mov_b32_e32 v68, v0
	v_mov_b32_e32 v69, v0
	v_mov_b32_e32 v70, v0
	v_mov_b32_e32 v71, v0
	v_mov_b32_e32 v80, v0
	v_mov_b32_e32 v81, v0
	v_mov_b32_e32 v82, v0
	v_mov_b32_e32 v83, v0
	v_mov_b32_e32 v84, v0
	v_mov_b32_e32 v85, v0
	v_mov_b32_e32 v86, v0
	v_mov_b32_e32 v87, v0
	v_mov_b32_e32 v96, v0
	v_mov_b32_e32 v97, v0
	v_mov_b32_e32 v98, v0
	v_mov_b32_e32 v99, v0
	v_mov_b32_e32 v100, v0
	v_mov_b32_e32 v101, v0
	v_mov_b32_e32 v102, v0
	v_mov_b32_e32 v103, v0
	v_mov_b32_e32 v112, v0
	v_mov_b32_e32 v113, v0
	v_mov_b32_e32 v114, v0
	v_mov_b32_e32 v115, v0
	v_mov_b32_e32 v116, v0
	v_mov_b32_e32 v117, v0
	v_mov_b32_e32 v118, v0
	v_mov_b32_e32 v119, v0
	v_mov_b32_e32 v72, v0
	v_mov_b32_e32 v73, v0
	v_mov_b32_e32 v74, v0
	v_mov_b32_e32 v75, v0
	v_mov_b32_e32 v76, v0
	v_mov_b32_e32 v77, v0
	v_mov_b32_e32 v78, v0
	v_mov_b32_e32 v79, v0
	v_mov_b32_e32 v88, v0
	v_mov_b32_e32 v89, v0
	v_mov_b32_e32 v90, v0
	v_mov_b32_e32 v91, v0
	v_mov_b32_e32 v92, v0
	v_mov_b32_e32 v93, v0
	v_mov_b32_e32 v94, v0
	v_mov_b32_e32 v95, v0
	v_mov_b32_e32 v104, v0
	v_mov_b32_e32 v105, v0
	v_mov_b32_e32 v106, v0
	v_mov_b32_e32 v107, v0
	v_mov_b32_e32 v108, v0
	v_mov_b32_e32 v109, v0
	v_mov_b32_e32 v110, v0
	v_mov_b32_e32 v111, v0
	v_mov_b32_e32 v120, v0
	v_mov_b32_e32 v121, v0
	v_mov_b32_e32 v122, v0
	v_mov_b32_e32 v123, v0
	v_mov_b32_e32 v124, v0
	v_mov_b32_e32 v125, v0
	v_mov_b32_e32 v126, v0
	v_mov_b32_e32 v127, v0
	s_and_b64 vcc, exec, s[18:19]
	s_cbranch_vccnz .Lmy_pr_3
	s_setprio 1
.Lmy_pr_3:
.LBB0_657:
	ds_read_b128 v[128:131], v185
	ds_read_b128 v[132:135], v185 offset:1024
	ds_read_b128 v[136:139], v185 offset:2048
	ds_read_b128 v[140:143], v185 offset:3072
	ds_read_b128 v[144:147], v186
	ds_read_b128 v[148:151], v186 offset:1024
	ds_read_b128 v[172:175], v186 offset:2048
	ds_read_b128 v[176:179], v186 offset:3072
	s_add_u32 s60, s58, 0xfffc0080
	s_addc_u32 s61, s59, -1
	s_cmp_eq_u32 s65, 12
	s_cselect_b32 s63, s8, s61
	s_cselect_b32 s62, s9, s60
	s_cselect_b32 s61, s45, s64
	s_cselect_b32 s60, s47, s57
	v_lshl_add_u64 v[180:181], s[58:59], 0, v[164:165]
	s_add_i32 m0, s70, 0xc000
	ds_read_b128 v[190:193], v187
	ds_read_b128 v[194:197], v187 offset:1024
	ds_read_b128 v[198:201], v187 offset:2048
	ds_read_b128 v[202:205], v187 offset:3072
	ds_read_b128 v[206:209], v187 offset:4096
	ds_read_b128 v[210:213], v187 offset:5120
	ds_read_b128 v[214:217], v187 offset:6144
	ds_read_b128 v[218:221], v187 offset:7168
	global_load_lds_dwordx4 v[180:181], off
	v_lshl_add_u64 v[180:181], s[58:59], 0, v[166:167]
	s_add_i32 m0, s70, 0xe000
	s_nop 0
	global_load_lds_dwordx4 v[180:181], off
	s_waitcnt vmcnt(8)
	s_waitcnt lgkmcnt(0)
	s_barrier
	s_waitcnt lgkmcnt(0)
	v_mfma_f32_16x16x32_bf16 v[124:127], v[128:131], v[190:193], v[124:127]
	v_mfma_f32_16x16x32_bf16 v[120:123], v[136:139], v[190:193], v[120:123]
	v_mfma_f32_16x16x32_bf16 v[108:111], v[128:131], v[198:201], v[108:111]
	v_mfma_f32_16x16x32_bf16 v[104:107], v[136:139], v[198:201], v[104:107]
	v_mfma_f32_16x16x32_bf16 v[92:95], v[128:131], v[206:209], v[92:95]
	v_mfma_f32_16x16x32_bf16 v[88:91], v[136:139], v[206:209], v[88:91]
	v_mfma_f32_16x16x32_bf16 v[76:79], v[128:131], v[214:217], v[76:79]
	v_mfma_f32_16x16x32_bf16 v[72:75], v[136:139], v[214:217], v[72:75]
	v_mfma_f32_16x16x32_bf16 v[124:127], v[132:135], v[194:197], v[124:127]
	v_mfma_f32_16x16x32_bf16 v[120:123], v[140:143], v[194:197], v[120:123]
	v_mfma_f32_16x16x32_bf16 v[108:111], v[132:135], v[202:205], v[108:111]
	v_mfma_f32_16x16x32_bf16 v[104:107], v[140:143], v[202:205], v[104:107]
	v_mfma_f32_16x16x32_bf16 v[92:95], v[132:135], v[210:213], v[92:95]
	v_mfma_f32_16x16x32_bf16 v[88:91], v[140:143], v[210:213], v[88:91]
	v_mfma_f32_16x16x32_bf16 v[76:79], v[132:135], v[218:221], v[76:79]
	v_mfma_f32_16x16x32_bf16 v[72:75], v[140:143], v[218:221], v[72:75]
	v_mfma_f32_16x16x32_bf16 v[116:119], v[144:147], v[190:193], v[116:119]
	v_mfma_f32_16x16x32_bf16 v[112:115], v[172:175], v[190:193], v[112:115]
	v_mfma_f32_16x16x32_bf16 v[100:103], v[144:147], v[198:201], v[100:103]
	v_mfma_f32_16x16x32_bf16 v[96:99], v[172:175], v[198:201], v[96:99]
	v_mfma_f32_16x16x32_bf16 v[84:87], v[144:147], v[206:209], v[84:87]
	v_mfma_f32_16x16x32_bf16 v[80:83], v[172:175], v[206:209], v[80:83]
	v_mfma_f32_16x16x32_bf16 v[68:71], v[144:147], v[214:217], v[68:71]
	v_mfma_f32_16x16x32_bf16 v[64:67], v[172:175], v[214:217], v[64:67]
	v_mfma_f32_16x16x32_bf16 v[116:119], v[148:151], v[194:197], v[116:119]
	v_mfma_f32_16x16x32_bf16 v[112:115], v[176:179], v[194:197], v[112:115]
	v_mfma_f32_16x16x32_bf16 v[100:103], v[148:151], v[202:205], v[100:103]
	v_mfma_f32_16x16x32_bf16 v[96:99], v[176:179], v[202:205], v[96:99]
	v_mfma_f32_16x16x32_bf16 v[84:87], v[148:151], v[210:213], v[84:87]
	v_mfma_f32_16x16x32_bf16 v[80:83], v[176:179], v[210:213], v[80:83]
	v_mfma_f32_16x16x32_bf16 v[68:71], v[148:151], v[218:221], v[68:71]
	v_mfma_f32_16x16x32_bf16 v[64:67], v[176:179], v[218:221], v[64:67]
	s_barrier
	s_add_i32 s66, s83, s69
	v_lshl_add_u64 v[180:181], s[60:61], 0, v[154:155]
	s_mov_b32 m0, s66
	ds_read_b128 v[190:193], v187 offset:16384
	ds_read_b128 v[194:197], v187 offset:17408
	ds_read_b128 v[198:201], v187 offset:18432
	ds_read_b128 v[202:205], v187 offset:19456
	ds_read_b128 v[206:209], v187 offset:20480
	ds_read_b128 v[210:213], v187 offset:21504
	ds_read_b128 v[214:217], v187 offset:22528
	ds_read_b128 v[218:221], v187 offset:23552
	global_load_lds_dwordx4 v[180:181], off
	s_add_i32 m0, s66, 0x2000
	s_add_u32 s66, s60, 0x40000
	v_lshl_add_u64 v[222:223], s[60:61], 0, v[158:159]
	s_addc_u32 s67, s61, 0
	s_add_i32 s85, s86, s69
	global_load_lds_dwordx4 v[222:223], off
	v_lshl_add_u64 v[224:225], s[66:67], 0, v[154:155]
	s_mov_b32 m0, s85
	v_lshl_add_u64 v[226:227], s[62:63], 0, v[156:157]
	global_load_lds_dwordx4 v[224:225], off
	v_lshl_add_u64 v[224:225], s[66:67], 0, v[158:159]
	s_add_i32 m0, s85, 0x2000
	s_nop 0
	global_load_lds_dwordx4 v[224:225], off
	v_lshl_add_u64 v[224:225], s[62:63], 0, v[152:153]
	s_mov_b32 m0, s70
	s_nop 0
	global_load_lds_dwordx4 v[224:225], off
	s_mov_b32 m0, s71
	s_nop 0
	global_load_lds_dwordx4 v[226:227], off
	s_waitcnt vmcnt(8)
	s_waitcnt lgkmcnt(0)
	s_barrier
	s_waitcnt lgkmcnt(0)
	v_mfma_f32_16x16x32_bf16 v[60:63], v[128:131], v[190:193], v[60:63]
	v_mfma_f32_16x16x32_bf16 v[56:59], v[136:139], v[190:193], v[56:59]
	v_mfma_f32_16x16x32_bf16 v[44:47], v[128:131], v[198:201], v[44:47]
	v_mfma_f32_16x16x32_bf16 v[40:43], v[136:139], v[198:201], v[40:43]
	v_mfma_f32_16x16x32_bf16 v[28:31], v[128:131], v[206:209], v[28:31]
	v_mfma_f32_16x16x32_bf16 v[24:27], v[136:139], v[206:209], v[24:27]
	v_mfma_f32_16x16x32_bf16 v[12:15], v[128:131], v[214:217], v[12:15]
	v_mfma_f32_16x16x32_bf16 v[8:11], v[136:139], v[214:217], v[8:11]
	v_mfma_f32_16x16x32_bf16 v[60:63], v[132:135], v[194:197], v[60:63]
	v_mfma_f32_16x16x32_bf16 v[56:59], v[140:143], v[194:197], v[56:59]
	v_mfma_f32_16x16x32_bf16 v[44:47], v[132:135], v[202:205], v[44:47]
	v_mfma_f32_16x16x32_bf16 v[40:43], v[140:143], v[202:205], v[40:43]
	v_mfma_f32_16x16x32_bf16 v[28:31], v[132:135], v[210:213], v[28:31]
	v_mfma_f32_16x16x32_bf16 v[24:27], v[140:143], v[210:213], v[24:27]
	v_mfma_f32_16x16x32_bf16 v[12:15], v[132:135], v[218:221], v[12:15]
	v_mfma_f32_16x16x32_bf16 v[8:11], v[140:143], v[218:221], v[8:11]
	v_mfma_f32_16x16x32_bf16 v[52:55], v[144:147], v[190:193], v[52:55]
	v_mfma_f32_16x16x32_bf16 v[48:51], v[172:175], v[190:193], v[48:51]
	v_mfma_f32_16x16x32_bf16 v[36:39], v[144:147], v[198:201], v[36:39]
	v_mfma_f32_16x16x32_bf16 v[32:35], v[172:175], v[198:201], v[32:35]
	v_mfma_f32_16x16x32_bf16 v[20:23], v[144:147], v[206:209], v[20:23]
	v_mfma_f32_16x16x32_bf16 v[16:19], v[172:175], v[206:209], v[16:19]
	v_mfma_f32_16x16x32_bf16 v[4:7], v[144:147], v[214:217], v[4:7]
	v_mfma_f32_16x16x32_bf16 v[0:3], v[172:175], v[214:217], v[0:3]
	v_mfma_f32_16x16x32_bf16 v[52:55], v[148:151], v[194:197], v[52:55]
	v_mfma_f32_16x16x32_bf16 v[48:51], v[176:179], v[194:197], v[48:51]
	v_mfma_f32_16x16x32_bf16 v[36:39], v[148:151], v[202:205], v[36:39]
	v_mfma_f32_16x16x32_bf16 v[32:35], v[176:179], v[202:205], v[32:35]
	v_mfma_f32_16x16x32_bf16 v[20:23], v[148:151], v[210:213], v[20:23]
	v_mfma_f32_16x16x32_bf16 v[16:19], v[176:179], v[210:213], v[16:19]
	v_mfma_f32_16x16x32_bf16 v[4:7], v[148:151], v[218:221], v[4:7]
	v_mfma_f32_16x16x32_bf16 v[0:3], v[176:179], v[218:221], v[0:3]
	s_barrier
	s_add_i32 s66, 0, 0x18000
	s_add_i32 s67, 0, 0x1c000
	v_add_u32_e32 v140, s66, v182
	v_add_u32_e32 v160, s67, v182
	ds_read_b128 v[128:131], v140
	ds_read_b128 v[132:135], v140 offset:1024
	ds_read_b128 v[136:139], v140 offset:2048
	ds_read_b128 v[140:143], v140 offset:3072
	ds_read_b128 v[144:147], v160
	ds_read_b128 v[148:151], v160 offset:1024
	ds_read_b128 v[172:175], v160 offset:2048
	ds_read_b128 v[176:179], v160 offset:3072
	s_add_u32 s62, s62, 0x40000
	s_addc_u32 s63, s63, 0
	s_mov_b32 m0, s72
	v_lshl_add_u64 v[228:229], s[62:63], 0, v[152:153]
	ds_read_b128 v[190:193], v187 offset:32768
	ds_read_b128 v[194:197], v187 offset:33792
	ds_read_b128 v[198:201], v187 offset:34816
	ds_read_b128 v[202:205], v187 offset:35840
	ds_read_b128 v[206:209], v187 offset:36864
	ds_read_b128 v[210:213], v187 offset:37888
	ds_read_b128 v[214:217], v187 offset:38912
	ds_read_b128 v[218:221], v187 offset:39936
	global_load_lds_dwordx4 v[228:229], off
	v_lshl_add_u64 v[228:229], s[62:63], 0, v[156:157]
	s_mov_b32 m0, s73
	s_nop 0
	global_load_lds_dwordx4 v[228:229], off
	s_waitcnt vmcnt(8)
	s_waitcnt lgkmcnt(0)
	s_barrier
	s_waitcnt lgkmcnt(0)
	v_mfma_f32_16x16x32_bf16 v[124:127], v[128:131], v[190:193], v[124:127]
	v_mfma_f32_16x16x32_bf16 v[120:123], v[136:139], v[190:193], v[120:123]
	v_mfma_f32_16x16x32_bf16 v[108:111], v[128:131], v[198:201], v[108:111]
	v_mfma_f32_16x16x32_bf16 v[104:107], v[136:139], v[198:201], v[104:107]
	v_mfma_f32_16x16x32_bf16 v[92:95], v[128:131], v[206:209], v[92:95]
	v_mfma_f32_16x16x32_bf16 v[88:91], v[136:139], v[206:209], v[88:91]
	v_mfma_f32_16x16x32_bf16 v[76:79], v[128:131], v[214:217], v[76:79]
	v_mfma_f32_16x16x32_bf16 v[72:75], v[136:139], v[214:217], v[72:75]
	v_mfma_f32_16x16x32_bf16 v[124:127], v[132:135], v[194:197], v[124:127]
	v_mfma_f32_16x16x32_bf16 v[120:123], v[140:143], v[194:197], v[120:123]
	v_mfma_f32_16x16x32_bf16 v[108:111], v[132:135], v[202:205], v[108:111]
	v_mfma_f32_16x16x32_bf16 v[104:107], v[140:143], v[202:205], v[104:107]
	v_mfma_f32_16x16x32_bf16 v[92:95], v[132:135], v[210:213], v[92:95]
	v_mfma_f32_16x16x32_bf16 v[88:91], v[140:143], v[210:213], v[88:91]
	v_mfma_f32_16x16x32_bf16 v[76:79], v[132:135], v[218:221], v[76:79]
	v_mfma_f32_16x16x32_bf16 v[72:75], v[140:143], v[218:221], v[72:75]
	v_mfma_f32_16x16x32_bf16 v[116:119], v[144:147], v[190:193], v[116:119]
	v_mfma_f32_16x16x32_bf16 v[112:115], v[172:175], v[190:193], v[112:115]
	v_mfma_f32_16x16x32_bf16 v[100:103], v[144:147], v[198:201], v[100:103]
	v_mfma_f32_16x16x32_bf16 v[96:99], v[172:175], v[198:201], v[96:99]
	v_mfma_f32_16x16x32_bf16 v[84:87], v[144:147], v[206:209], v[84:87]
	v_mfma_f32_16x16x32_bf16 v[80:83], v[172:175], v[206:209], v[80:83]
	v_mfma_f32_16x16x32_bf16 v[68:71], v[144:147], v[214:217], v[68:71]
	v_mfma_f32_16x16x32_bf16 v[64:67], v[172:175], v[214:217], v[64:67]
	v_mfma_f32_16x16x32_bf16 v[116:119], v[148:151], v[194:197], v[116:119]
	v_mfma_f32_16x16x32_bf16 v[112:115], v[176:179], v[194:197], v[112:115]
	v_mfma_f32_16x16x32_bf16 v[100:103], v[148:151], v[202:205], v[100:103]
	v_mfma_f32_16x16x32_bf16 v[96:99], v[176:179], v[202:205], v[96:99]
	v_mfma_f32_16x16x32_bf16 v[84:87], v[148:151], v[210:213], v[84:87]
	v_mfma_f32_16x16x32_bf16 v[80:83], v[176:179], v[210:213], v[80:83]
	v_mfma_f32_16x16x32_bf16 v[68:71], v[148:151], v[218:221], v[68:71]
	v_mfma_f32_16x16x32_bf16 v[64:67], v[176:179], v[218:221], v[64:67]
	s_barrier
	s_add_i32 s62, s66, s69
	v_lshl_add_u64 v[180:181], v[180:181], 0, s[16:17]
	s_mov_b32 m0, s62
	ds_read_b128 v[190:193], v187 offset:49152
	ds_read_b128 v[194:197], v187 offset:50176
	ds_read_b128 v[198:201], v187 offset:51200
	ds_read_b128 v[202:205], v187 offset:52224
	ds_read_b128 v[206:209], v187 offset:53248
	ds_read_b128 v[210:213], v187 offset:54272
	ds_read_b128 v[214:217], v187 offset:55296
	ds_read_b128 v[218:221], v187 offset:56320
	global_load_lds_dwordx4 v[180:181], off
	s_add_i32 m0, s62, 0x2000
	s_add_u32 s60, s60, 0x40080
	v_lshl_add_u64 v[180:181], v[222:223], 0, s[16:17]
	s_addc_u32 s61, s61, 0
	s_add_i32 s62, s67, s69
	global_load_lds_dwordx4 v[180:181], off
	v_lshl_add_u64 v[180:181], s[60:61], 0, v[154:155]
	s_mov_b32 m0, s62
	s_nop 0
	global_load_lds_dwordx4 v[180:181], off
	v_lshl_add_u64 v[180:181], s[60:61], 0, v[158:159]
	s_add_i32 m0, s62, 0x2000
	s_nop 0
	global_load_lds_dwordx4 v[180:181], off
	v_lshl_add_u64 v[180:181], v[224:225], 0, s[16:17]
	s_mov_b32 m0, s75
	s_nop 0
	global_load_lds_dwordx4 v[180:181], off
	v_lshl_add_u64 v[180:181], v[226:227], 0, s[16:17]
	s_mov_b32 m0, s76
	s_nop 0
	global_load_lds_dwordx4 v[180:181], off
	s_waitcnt vmcnt(8)
	s_waitcnt lgkmcnt(0)
	s_barrier
	s_waitcnt lgkmcnt(0)
	v_mfma_f32_16x16x32_bf16 v[60:63], v[128:131], v[190:193], v[60:63]
	v_mfma_f32_16x16x32_bf16 v[56:59], v[136:139], v[190:193], v[56:59]
	v_mfma_f32_16x16x32_bf16 v[44:47], v[128:131], v[198:201], v[44:47]
	v_mfma_f32_16x16x32_bf16 v[40:43], v[136:139], v[198:201], v[40:43]
	v_mfma_f32_16x16x32_bf16 v[28:31], v[128:131], v[206:209], v[28:31]
	v_mfma_f32_16x16x32_bf16 v[24:27], v[136:139], v[206:209], v[24:27]
	v_mfma_f32_16x16x32_bf16 v[12:15], v[128:131], v[214:217], v[12:15]
	v_mfma_f32_16x16x32_bf16 v[8:11], v[136:139], v[214:217], v[8:11]
	v_mfma_f32_16x16x32_bf16 v[60:63], v[132:135], v[194:197], v[60:63]
	v_mfma_f32_16x16x32_bf16 v[56:59], v[140:143], v[194:197], v[56:59]
	v_mfma_f32_16x16x32_bf16 v[44:47], v[132:135], v[202:205], v[44:47]
	v_mfma_f32_16x16x32_bf16 v[40:43], v[140:143], v[202:205], v[40:43]
	v_mfma_f32_16x16x32_bf16 v[28:31], v[132:135], v[210:213], v[28:31]
	v_mfma_f32_16x16x32_bf16 v[24:27], v[140:143], v[210:213], v[24:27]
	v_mfma_f32_16x16x32_bf16 v[12:15], v[132:135], v[218:221], v[12:15]
	v_mfma_f32_16x16x32_bf16 v[8:11], v[140:143], v[218:221], v[8:11]
	v_mfma_f32_16x16x32_bf16 v[52:55], v[144:147], v[190:193], v[52:55]
	v_mfma_f32_16x16x32_bf16 v[48:51], v[172:175], v[190:193], v[48:51]
	v_mfma_f32_16x16x32_bf16 v[36:39], v[144:147], v[198:201], v[36:39]
	v_mfma_f32_16x16x32_bf16 v[32:35], v[172:175], v[198:201], v[32:35]
	v_mfma_f32_16x16x32_bf16 v[20:23], v[144:147], v[206:209], v[20:23]
	v_mfma_f32_16x16x32_bf16 v[16:19], v[172:175], v[206:209], v[16:19]
	v_mfma_f32_16x16x32_bf16 v[4:7], v[144:147], v[214:217], v[4:7]
	v_mfma_f32_16x16x32_bf16 v[0:3], v[172:175], v[214:217], v[0:3]
	v_mfma_f32_16x16x32_bf16 v[52:55], v[148:151], v[194:197], v[52:55]
	v_mfma_f32_16x16x32_bf16 v[48:51], v[176:179], v[194:197], v[48:51]
	v_mfma_f32_16x16x32_bf16 v[36:39], v[148:151], v[202:205], v[36:39]
	v_mfma_f32_16x16x32_bf16 v[32:35], v[176:179], v[202:205], v[32:35]
	v_mfma_f32_16x16x32_bf16 v[20:23], v[148:151], v[210:213], v[20:23]
	v_mfma_f32_16x16x32_bf16 v[16:19], v[176:179], v[210:213], v[16:19]
	v_mfma_f32_16x16x32_bf16 v[4:7], v[148:151], v[218:221], v[4:7]
	v_mfma_f32_16x16x32_bf16 v[0:3], v[176:179], v[218:221], v[0:3]
	s_barrier
	s_add_i32 s65, s65, 2
	s_add_u32 s58, s58, 0x100
	s_addc_u32 s59, s59, 0
	s_add_u32 s57, s57, 0x100
	s_addc_u32 s64, s64, 0
	s_cmp_gt_u32 s65, 13
	s_cbranch_scc0 .LBB0_657
	s_setprio 0
	s_and_b64 vcc, exec, s[18:19]
	s_cbranch_vccz .LBB0_660
	s_barrier

.LBB0_939:
	s_ashr_i32 s51, s50, 31
	s_lshl_b64 s[52:53], s[50:51], 18
	s_add_u32 s52, s8, s52
	s_addc_u32 s53, s9, s53
	s_and_b64 s[54:55], s[0:1], exec
	s_cselect_b32 s51, s53, s57
	s_cselect_b32 s82, s52, s56
	s_ashr_i32 s49, s48, 31
	s_lshl_b64 s[54:55], s[48:49], 18
	s_add_u32 s54, s62, s54
	s_addc_u32 s55, s63, s55
	s_and_b64 s[60:61], s[0:1], exec
	s_cselect_b32 s49, s55, s59
	s_cselect_b32 s83, s54, s58
	s_add_u32 s56, s56, 0x20080
	s_addc_u32 s57, s57, 0
	s_add_u32 s85, s58, 0x100
	v_mov_b32_e32 v0, 0
	s_addc_u32 s86, s59, 0
	s_mov_b32 s87, -2
	v_mov_b32_e32 v1, v0
	v_mov_b32_e32 v2, v0
	v_mov_b32_e32 v3, v0
	v_mov_b32_e32 v4, v0
	v_mov_b32_e32 v5, v0
	v_mov_b32_e32 v6, v0
	v_mov_b32_e32 v7, v0
	v_mov_b32_e32 v8, v0
	v_mov_b32_e32 v9, v0
	v_mov_b32_e32 v10, v0
	v_mov_b32_e32 v11, v0
	v_mov_b32_e32 v12, v0
	v_mov_b32_e32 v13, v0
	v_mov_b32_e32 v14, v0
	v_mov_b32_e32 v15, v0
	v_mov_b32_e32 v24, v0
	v_mov_b32_e32 v25, v0
	v_mov_b32_e32 v26, v0
	v_mov_b32_e32 v27, v0
	v_mov_b32_e32 v28, v0
	v_mov_b32_e32 v29, v0
	v_mov_b32_e32 v30, v0
	v_mov_b32_e32 v31, v0
	v_mov_b32_e32 v40, v0
	v_mov_b32_e32 v41, v0
	v_mov_b32_e32 v42, v0
	v_mov_b32_e32 v43, v0
	v_mov_b32_e32 v44, v0
	v_mov_b32_e32 v45, v0
	v_mov_b32_e32 v46, v0
	v_mov_b32_e32 v47, v0
	v_mov_b32_e32 v16, v0
	v_mov_b32_e32 v17, v0
	v_mov_b32_e32 v18, v0
	v_mov_b32_e32 v19, v0
	v_mov_b32_e32 v20, v0
	v_mov_b32_e32 v21, v0
	v_mov_b32_e32 v22, v0
	v_mov_b32_e32 v23, v0
	v_mov_b32_e32 v32, v0
	v_mov_b32_e32 v33, v0
	v_mov_b32_e32 v34, v0
	v_mov_b32_e32 v35, v0
	v_mov_b32_e32 v36, v0
	v_mov_b32_e32 v37, v0
	v_mov_b32_e32 v38, v0
	v_mov_b32_e32 v39, v0
	v_mov_b32_e32 v48, v0
	v_mov_b32_e32 v49, v0
	v_mov_b32_e32 v50, v0
	v_mov_b32_e32 v51, v0
	v_mov_b32_e32 v52, v0
	v_mov_b32_e32 v53, v0
	v_mov_b32_e32 v54, v0
	v_mov_b32_e32 v55, v0
	v_mov_b32_e32 v56, v0
	v_mov_b32_e32 v57, v0
	v_mov_b32_e32 v58, v0
	v_mov_b32_e32 v59, v0
	v_mov_b32_e32 v60, v0
	v_mov_b32_e32 v61, v0
	v_mov_b32_e32 v62, v0
	v_mov_b32_e32 v63, v0
	v_mov_b32_e32 v64, v0
	v_mov_b32_e32 v65, v0
	v_mov_b32_e32 v66, v0
	v_mov_b32_e32 v67, v0
	v_mov_b32_e32 v68, v0
	v_mov_b32_e32 v69, v0
	v_mov_b32_e32 v70, v0
	v_mov_b32_e32 v71, v0
	v_mov_b32_e32 v72, v0
	v_mov_b32_e32 v73, v0
	v_mov_b32_e32 v74, v0
	v_mov_b32_e32 v75, v0
	v_mov_b32_e32 v76, v0
	v_mov_b32_e32 v77, v0
	v_mov_b32_e32 v78, v0
	v_mov_b32_e32 v79, v0
	v_mov_b32_e32 v88, v0
	v_mov_b32_e32 v89, v0
	v_mov_b32_e32 v90, v0
	v_mov_b32_e32 v91, v0
	v_mov_b32_e32 v92, v0
	v_mov_b32_e32 v93, v0
	v_mov_b32_e32 v94, v0
	v_mov_b32_e32 v95, v0
	v_mov_b32_e32 v104, v0
	v_mov_b32_e32 v105, v0
	v_mov_b32_e32 v106, v0
	v_mov_b32_e32 v107, v0
	v_mov_b32_e32 v108, v0
	v_mov_b32_e32 v109, v0
	v_mov_b32_e32 v110, v0
	v_mov_b32_e32 v111, v0
	v_mov_b32_e32 v80, v0
	v_mov_b32_e32 v81, v0
	v_mov_b32_e32 v82, v0
	v_mov_b32_e32 v83, v0
	v_mov_b32_e32 v84, v0
	v_mov_b32_e32 v85, v0
	v_mov_b32_e32 v86, v0
	v_mov_b32_e32 v87, v0
	v_mov_b32_e32 v96, v0
	v_mov_b32_e32 v97, v0
	v_mov_b32_e32 v98, v0
	v_mov_b32_e32 v99, v0
	v_mov_b32_e32 v100, v0
	v_mov_b32_e32 v101, v0
	v_mov_b32_e32 v102, v0
	v_mov_b32_e32 v103, v0
	v_mov_b32_e32 v112, v0
	v_mov_b32_e32 v113, v0
	v_mov_b32_e32 v114, v0
	v_mov_b32_e32 v115, v0
	v_mov_b32_e32 v116, v0
	v_mov_b32_e32 v117, v0
	v_mov_b32_e32 v118, v0
	v_mov_b32_e32 v119, v0
	v_mov_b32_e32 v120, v0
	v_mov_b32_e32 v121, v0
	v_mov_b32_e32 v122, v0
	v_mov_b32_e32 v123, v0
	v_mov_b32_e32 v124, v0
	v_mov_b32_e32 v125, v0
	v_mov_b32_e32 v126, v0
	v_mov_b32_e32 v127, v0
	s_and_b64 vcc, exec, s[34:35]
	s_cbranch_vccnz .Lmy_pr_4
	s_setprio 1
.Lmy_pr_4:
.LBB0_940:
	ds_read_b128 v[150:153], v147
	ds_read_b128 v[154:157], v147 offset:1024
	ds_read_b128 v[158:161], v147 offset:2048
	ds_read_b128 v[162:165], v147 offset:3072
	ds_read_b128 v[166:169], v148
	ds_read_b128 v[170:173], v148 offset:1024
	ds_read_b128 v[174:177], v148 offset:2048
	ds_read_b128 v[178:181], v148 offset:3072
	s_add_u32 s58, s56, 0xfffe0080
	s_addc_u32 s59, s57, -1
	s_cmp_eq_u32 s87, 4
	s_cselect_b32 s61, s51, s59
	s_cselect_b32 s60, s82, s58
	s_cselect_b32 s59, s49, s86
	s_cselect_b32 s58, s83, s85
	v_lshl_add_u64 v[214:215], s[56:57], 0, v[136:137]
	s_add_i32 m0, s47, 0xc000
	ds_read_b128 v[182:185], v149
	ds_read_b128 v[186:189], v149 offset:1024
	ds_read_b128 v[190:193], v149 offset:2048
	ds_read_b128 v[194:197], v149 offset:3072
	ds_read_b128 v[198:201], v149 offset:4096
	ds_read_b128 v[202:205], v149 offset:5120
	ds_read_b128 v[206:209], v149 offset:6144
	ds_read_b128 v[210:213], v149 offset:7168
	global_load_lds_dwordx4 v[214:215], off
	v_lshl_add_u64 v[214:215], s[56:57], 0, v[138:139]
	s_add_i32 m0, s47, 0xe000
	s_nop 0
	global_load_lds_dwordx4 v[214:215], off
	s_waitcnt vmcnt(8)
	s_waitcnt lgkmcnt(0)
	s_barrier
	s_waitcnt lgkmcnt(0)
	v_mfma_f32_16x16x32_bf16 v[124:127], v[150:153], v[182:185], v[124:127]
	v_mfma_f32_16x16x32_bf16 v[120:123], v[158:161], v[182:185], v[120:123]
	v_mfma_f32_16x16x32_bf16 v[116:119], v[150:153], v[190:193], v[116:119]
	v_mfma_f32_16x16x32_bf16 v[112:115], v[158:161], v[190:193], v[112:115]
	v_mfma_f32_16x16x32_bf16 v[100:103], v[150:153], v[198:201], v[100:103]
	v_mfma_f32_16x16x32_bf16 v[96:99], v[158:161], v[198:201], v[96:99]
	v_mfma_f32_16x16x32_bf16 v[84:87], v[150:153], v[206:209], v[84:87]
	v_mfma_f32_16x16x32_bf16 v[80:83], v[158:161], v[206:209], v[80:83]
	v_mfma_f32_16x16x32_bf16 v[124:127], v[154:157], v[186:189], v[124:127]
	v_mfma_f32_16x16x32_bf16 v[120:123], v[162:165], v[186:189], v[120:123]
	v_mfma_f32_16x16x32_bf16 v[116:119], v[154:157], v[194:197], v[116:119]
	v_mfma_f32_16x16x32_bf16 v[112:115], v[162:165], v[194:197], v[112:115]
	v_mfma_f32_16x16x32_bf16 v[100:103], v[154:157], v[202:205], v[100:103]
	v_mfma_f32_16x16x32_bf16 v[96:99], v[162:165], v[202:205], v[96:99]
	v_mfma_f32_16x16x32_bf16 v[84:87], v[154:157], v[210:213], v[84:87]
	v_mfma_f32_16x16x32_bf16 v[80:83], v[162:165], v[210:213], v[80:83]
	v_mfma_f32_16x16x32_bf16 v[108:111], v[166:169], v[182:185], v[108:111]
	v_mfma_f32_16x16x32_bf16 v[104:107], v[174:177], v[182:185], v[104:107]
	v_mfma_f32_16x16x32_bf16 v[92:95], v[166:169], v[190:193], v[92:95]
	v_mfma_f32_16x16x32_bf16 v[88:91], v[174:177], v[190:193], v[88:91]
	v_mfma_f32_16x16x32_bf16 v[76:79], v[166:169], v[198:201], v[76:79]
	v_mfma_f32_16x16x32_bf16 v[72:75], v[174:177], v[198:201], v[72:75]
	v_mfma_f32_16x16x32_bf16 v[68:71], v[166:169], v[206:209], v[68:71]
	v_mfma_f32_16x16x32_bf16 v[64:67], v[174:177], v[206:209], v[64:67]
	v_mfma_f32_16x16x32_bf16 v[108:111], v[170:173], v[186:189], v[108:111]
	v_mfma_f32_16x16x32_bf16 v[104:107], v[178:181], v[186:189], v[104:107]
	v_mfma_f32_16x16x32_bf16 v[92:95], v[170:173], v[194:197], v[92:95]
	v_mfma_f32_16x16x32_bf16 v[88:91], v[178:181], v[194:197], v[88:91]
	v_mfma_f32_16x16x32_bf16 v[76:79], v[170:173], v[202:205], v[76:79]
	v_mfma_f32_16x16x32_bf16 v[72:75], v[178:181], v[202:205], v[72:75]
	v_mfma_f32_16x16x32_bf16 v[68:71], v[170:173], v[210:213], v[68:71]
	v_mfma_f32_16x16x32_bf16 v[64:67], v[178:181], v[210:213], v[64:67]
	s_barrier
	s_add_i32 s88, s73, s64
	v_lshl_add_u64 v[214:215], s[58:59], 0, v[130:131]
	s_mov_b32 m0, s88
	ds_read_b128 v[182:185], v149 offset:16384
	ds_read_b128 v[186:189], v149 offset:17408
	ds_read_b128 v[190:193], v149 offset:18432
	ds_read_b128 v[194:197], v149 offset:19456
	ds_read_b128 v[198:201], v149 offset:20480
	ds_read_b128 v[202:205], v149 offset:21504
	ds_read_b128 v[206:209], v149 offset:22528
	ds_read_b128 v[210:213], v149 offset:23552
	global_load_lds_dwordx4 v[214:215], off
	s_add_i32 m0, s88, 0x2000
	s_add_u32 s88, s58, 0x20000
	v_lshl_add_u64 v[216:217], s[58:59], 0, v[134:135]
	s_addc_u32 s89, s59, 0
	s_add_i32 s90, s74, s64
	global_load_lds_dwordx4 v[216:217], off
	v_lshl_add_u64 v[218:219], s[88:89], 0, v[130:131]
	s_mov_b32 m0, s90
	v_lshl_add_u64 v[220:221], s[60:61], 0, v[132:133]
	global_load_lds_dwordx4 v[218:219], off
	v_lshl_add_u64 v[218:219], s[88:89], 0, v[134:135]
	s_add_i32 m0, s90, 0x2000
	s_nop 0
	global_load_lds_dwordx4 v[218:219], off
	v_lshl_add_u64 v[218:219], s[60:61], 0, v[128:129]
	s_mov_b32 m0, s47
	s_nop 0
	global_load_lds_dwordx4 v[218:219], off
	s_mov_b32 m0, s65
	s_nop 0
	global_load_lds_dwordx4 v[220:221], off
	s_waitcnt vmcnt(8)
	s_waitcnt lgkmcnt(0)
	s_barrier
	s_waitcnt lgkmcnt(0)
	v_mfma_f32_16x16x32_bf16 v[60:63], v[150:153], v[182:185], v[60:63]
	v_mfma_f32_16x16x32_bf16 v[56:59], v[158:161], v[182:185], v[56:59]
	v_mfma_f32_16x16x32_bf16 v[52:55], v[150:153], v[190:193], v[52:55]
	v_mfma_f32_16x16x32_bf16 v[48:51], v[158:161], v[190:193], v[48:51]
	v_mfma_f32_16x16x32_bf16 v[36:39], v[150:153], v[198:201], v[36:39]
	v_mfma_f32_16x16x32_bf16 v[32:35], v[158:161], v[198:201], v[32:35]
	v_mfma_f32_16x16x32_bf16 v[20:23], v[150:153], v[206:209], v[20:23]
	v_mfma_f32_16x16x32_bf16 v[16:19], v[158:161], v[206:209], v[16:19]
	v_mfma_f32_16x16x32_bf16 v[60:63], v[154:157], v[186:189], v[60:63]
	v_mfma_f32_16x16x32_bf16 v[56:59], v[162:165], v[186:189], v[56:59]
	v_mfma_f32_16x16x32_bf16 v[52:55], v[154:157], v[194:197], v[52:55]
	v_mfma_f32_16x16x32_bf16 v[48:51], v[162:165], v[194:197], v[48:51]
	v_mfma_f32_16x16x32_bf16 v[36:39], v[154:157], v[202:205], v[36:39]
	v_mfma_f32_16x16x32_bf16 v[32:35], v[162:165], v[202:205], v[32:35]
	v_mfma_f32_16x16x32_bf16 v[20:23], v[154:157], v[210:213], v[20:23]
	v_mfma_f32_16x16x32_bf16 v[16:19], v[162:165], v[210:213], v[16:19]
	v_mfma_f32_16x16x32_bf16 v[44:47], v[166:169], v[182:185], v[44:47]
	v_mfma_f32_16x16x32_bf16 v[40:43], v[174:177], v[182:185], v[40:43]
	v_mfma_f32_16x16x32_bf16 v[28:31], v[166:169], v[190:193], v[28:31]
	v_mfma_f32_16x16x32_bf16 v[24:27], v[174:177], v[190:193], v[24:27]
	v_mfma_f32_16x16x32_bf16 v[12:15], v[166:169], v[198:201], v[12:15]
	v_mfma_f32_16x16x32_bf16 v[8:11], v[174:177], v[198:201], v[8:11]
	v_mfma_f32_16x16x32_bf16 v[4:7], v[166:169], v[206:209], v[4:7]
	v_mfma_f32_16x16x32_bf16 v[0:3], v[174:177], v[206:209], v[0:3]
	v_mfma_f32_16x16x32_bf16 v[44:47], v[170:173], v[186:189], v[44:47]
	v_mfma_f32_16x16x32_bf16 v[40:43], v[178:181], v[186:189], v[40:43]
	v_mfma_f32_16x16x32_bf16 v[28:31], v[170:173], v[194:197], v[28:31]
	v_mfma_f32_16x16x32_bf16 v[24:27], v[178:181], v[194:197], v[24:27]
	v_mfma_f32_16x16x32_bf16 v[12:15], v[170:173], v[202:205], v[12:15]
	v_mfma_f32_16x16x32_bf16 v[8:11], v[178:181], v[202:205], v[8:11]
	v_mfma_f32_16x16x32_bf16 v[4:7], v[170:173], v[210:213], v[4:7]
	v_mfma_f32_16x16x32_bf16 v[0:3], v[178:181], v[210:213], v[0:3]
	s_barrier
	s_add_i32 s88, 0, 0x18000
	s_add_i32 s89, 0, 0x1c000
	v_add_u32_e32 v162, s88, v145
	v_add_u32_e32 v178, s89, v145
	ds_read_b128 v[150:153], v162
	ds_read_b128 v[154:157], v162 offset:1024
	ds_read_b128 v[158:161], v162 offset:2048
	ds_read_b128 v[162:165], v162 offset:3072
	ds_read_b128 v[166:169], v178
	ds_read_b128 v[170:173], v178 offset:1024
	ds_read_b128 v[174:177], v178 offset:2048
	ds_read_b128 v[178:181], v178 offset:3072
	s_add_u32 s60, s60, 0x20000
	s_addc_u32 s61, s61, 0
	s_mov_b32 m0, s66
	v_lshl_add_u64 v[222:223], s[60:61], 0, v[128:129]
	ds_read_b128 v[182:185], v149 offset:32768
	ds_read_b128 v[186:189], v149 offset:33792
	ds_read_b128 v[190:193], v149 offset:34816
	ds_read_b128 v[194:197], v149 offset:35840
	ds_read_b128 v[198:201], v149 offset:36864
	ds_read_b128 v[202:205], v149 offset:37888
	ds_read_b128 v[206:209], v149 offset:38912
	ds_read_b128 v[210:213], v149 offset:39936
	global_load_lds_dwordx4 v[222:223], off
	v_lshl_add_u64 v[222:223], s[60:61], 0, v[132:133]
	s_mov_b32 m0, s67
	s_nop 0
	global_load_lds_dwordx4 v[222:223], off
	s_waitcnt vmcnt(8)
	s_waitcnt lgkmcnt(0)
	s_barrier
	s_waitcnt lgkmcnt(0)
	v_mfma_f32_16x16x32_bf16 v[124:127], v[150:153], v[182:185], v[124:127]
	v_mfma_f32_16x16x32_bf16 v[120:123], v[158:161], v[182:185], v[120:123]
	v_mfma_f32_16x16x32_bf16 v[116:119], v[150:153], v[190:193], v[116:119]
	v_mfma_f32_16x16x32_bf16 v[112:115], v[158:161], v[190:193], v[112:115]
	v_mfma_f32_16x16x32_bf16 v[100:103], v[150:153], v[198:201], v[100:103]
	v_mfma_f32_16x16x32_bf16 v[96:99], v[158:161], v[198:201], v[96:99]
	v_mfma_f32_16x16x32_bf16 v[84:87], v[150:153], v[206:209], v[84:87]
	v_mfma_f32_16x16x32_bf16 v[80:83], v[158:161], v[206:209], v[80:83]
	v_mfma_f32_16x16x32_bf16 v[124:127], v[154:157], v[186:189], v[124:127]
	v_mfma_f32_16x16x32_bf16 v[120:123], v[162:165], v[186:189], v[120:123]
	v_mfma_f32_16x16x32_bf16 v[116:119], v[154:157], v[194:197], v[116:119]
	v_mfma_f32_16x16x32_bf16 v[112:115], v[162:165], v[194:197], v[112:115]
	v_mfma_f32_16x16x32_bf16 v[100:103], v[154:157], v[202:205], v[100:103]
	v_mfma_f32_16x16x32_bf16 v[96:99], v[162:165], v[202:205], v[96:99]
	v_mfma_f32_16x16x32_bf16 v[84:87], v[154:157], v[210:213], v[84:87]
	v_mfma_f32_16x16x32_bf16 v[80:83], v[162:165], v[210:213], v[80:83]
	v_mfma_f32_16x16x32_bf16 v[108:111], v[166:169], v[182:185], v[108:111]
	v_mfma_f32_16x16x32_bf16 v[104:107], v[174:177], v[182:185], v[104:107]
	v_mfma_f32_16x16x32_bf16 v[92:95], v[166:169], v[190:193], v[92:95]
	v_mfma_f32_16x16x32_bf16 v[88:91], v[174:177], v[190:193], v[88:91]
	v_mfma_f32_16x16x32_bf16 v[76:79], v[166:169], v[198:201], v[76:79]
	v_mfma_f32_16x16x32_bf16 v[72:75], v[174:177], v[198:201], v[72:75]
	v_mfma_f32_16x16x32_bf16 v[68:71], v[166:169], v[206:209], v[68:71]
	v_mfma_f32_16x16x32_bf16 v[64:67], v[174:177], v[206:209], v[64:67]
	v_mfma_f32_16x16x32_bf16 v[108:111], v[170:173], v[186:189], v[108:111]
	v_mfma_f32_16x16x32_bf16 v[104:107], v[178:181], v[186:189], v[104:107]
	v_mfma_f32_16x16x32_bf16 v[92:95], v[170:173], v[194:197], v[92:95]
	v_mfma_f32_16x16x32_bf16 v[88:91], v[178:181], v[194:197], v[88:91]
	v_mfma_f32_16x16x32_bf16 v[76:79], v[170:173], v[202:205], v[76:79]
	v_mfma_f32_16x16x32_bf16 v[72:75], v[178:181], v[202:205], v[72:75]
	v_mfma_f32_16x16x32_bf16 v[68:71], v[170:173], v[210:213], v[68:71]
	v_mfma_f32_16x16x32_bf16 v[64:67], v[178:181], v[210:213], v[64:67]
	s_barrier
	s_add_i32 s60, s88, s64
	v_lshl_add_u64 v[214:215], v[214:215], 0, s[22:23]
	s_mov_b32 m0, s60
	ds_read_b128 v[182:185], v149 offset:49152
	ds_read_b128 v[186:189], v149 offset:50176
	ds_read_b128 v[190:193], v149 offset:51200
	ds_read_b128 v[194:197], v149 offset:52224
	ds_read_b128 v[198:201], v149 offset:53248
	ds_read_b128 v[202:205], v149 offset:54272
	ds_read_b128 v[206:209], v149 offset:55296
	ds_read_b128 v[210:213], v149 offset:56320
	global_load_lds_dwordx4 v[214:215], off
	s_add_i32 m0, s60, 0x2000
	s_add_u32 s58, s58, 0x20080
	v_lshl_add_u64 v[214:215], v[216:217], 0, s[22:23]
	s_addc_u32 s59, s59, 0
	s_add_i32 s60, s89, s64
	global_load_lds_dwordx4 v[214:215], off
	v_lshl_add_u64 v[214:215], s[58:59], 0, v[130:131]
	s_mov_b32 m0, s60
	s_nop 0
	global_load_lds_dwordx4 v[214:215], off
	v_lshl_add_u64 v[214:215], s[58:59], 0, v[134:135]
	s_add_i32 m0, s60, 0x2000
	s_nop 0
	global_load_lds_dwordx4 v[214:215], off
	v_lshl_add_u64 v[214:215], v[218:219], 0, s[22:23]
	s_mov_b32 m0, s69
	s_nop 0
	global_load_lds_dwordx4 v[214:215], off
	v_lshl_add_u64 v[214:215], v[220:221], 0, s[22:23]
	s_mov_b32 m0, s70
	s_nop 0
	global_load_lds_dwordx4 v[214:215], off
	s_waitcnt vmcnt(8)
	s_waitcnt lgkmcnt(0)
	s_barrier
	s_waitcnt lgkmcnt(0)
	v_mfma_f32_16x16x32_bf16 v[60:63], v[150:153], v[182:185], v[60:63]
	v_mfma_f32_16x16x32_bf16 v[56:59], v[158:161], v[182:185], v[56:59]
	v_mfma_f32_16x16x32_bf16 v[52:55], v[150:153], v[190:193], v[52:55]
	v_mfma_f32_16x16x32_bf16 v[48:51], v[158:161], v[190:193], v[48:51]
	v_mfma_f32_16x16x32_bf16 v[36:39], v[150:153], v[198:201], v[36:39]
	v_mfma_f32_16x16x32_bf16 v[32:35], v[158:161], v[198:201], v[32:35]
	v_mfma_f32_16x16x32_bf16 v[20:23], v[150:153], v[206:209], v[20:23]
	v_mfma_f32_16x16x32_bf16 v[16:19], v[158:161], v[206:209], v[16:19]
	v_mfma_f32_16x16x32_bf16 v[60:63], v[154:157], v[186:189], v[60:63]
	v_mfma_f32_16x16x32_bf16 v[56:59], v[162:165], v[186:189], v[56:59]
	v_mfma_f32_16x16x32_bf16 v[52:55], v[154:157], v[194:197], v[52:55]
	v_mfma_f32_16x16x32_bf16 v[48:51], v[162:165], v[194:197], v[48:51]
	v_mfma_f32_16x16x32_bf16 v[36:39], v[154:157], v[202:205], v[36:39]
	v_mfma_f32_16x16x32_bf16 v[32:35], v[162:165], v[202:205], v[32:35]
	v_mfma_f32_16x16x32_bf16 v[20:23], v[154:157], v[210:213], v[20:23]
	v_mfma_f32_16x16x32_bf16 v[16:19], v[162:165], v[210:213], v[16:19]
	v_mfma_f32_16x16x32_bf16 v[44:47], v[166:169], v[182:185], v[44:47]
	v_mfma_f32_16x16x32_bf16 v[40:43], v[174:177], v[182:185], v[40:43]
	v_mfma_f32_16x16x32_bf16 v[28:31], v[166:169], v[190:193], v[28:31]
	v_mfma_f32_16x16x32_bf16 v[24:27], v[174:177], v[190:193], v[24:27]
	v_mfma_f32_16x16x32_bf16 v[12:15], v[166:169], v[198:201], v[12:15]
	v_mfma_f32_16x16x32_bf16 v[8:11], v[174:177], v[198:201], v[8:11]
	v_mfma_f32_16x16x32_bf16 v[4:7], v[166:169], v[206:209], v[4:7]
	v_mfma_f32_16x16x32_bf16 v[0:3], v[174:177], v[206:209], v[0:3]
	v_mfma_f32_16x16x32_bf16 v[44:47], v[170:173], v[186:189], v[44:47]
	v_mfma_f32_16x16x32_bf16 v[40:43], v[178:181], v[186:189], v[40:43]
	v_mfma_f32_16x16x32_bf16 v[28:31], v[170:173], v[194:197], v[28:31]
	v_mfma_f32_16x16x32_bf16 v[24:27], v[178:181], v[194:197], v[24:27]
	v_mfma_f32_16x16x32_bf16 v[12:15], v[170:173], v[202:205], v[12:15]
	v_mfma_f32_16x16x32_bf16 v[8:11], v[178:181], v[202:205], v[8:11]
	v_mfma_f32_16x16x32_bf16 v[4:7], v[170:173], v[210:213], v[4:7]
	v_mfma_f32_16x16x32_bf16 v[0:3], v[178:181], v[210:213], v[0:3]
	s_barrier
	s_add_i32 s87, s87, 2
	s_add_u32 s56, s56, 0x100
	s_addc_u32 s57, s57, 0
	s_add_u32 s85, s85, 0x100
	s_addc_u32 s86, s86, 0
	s_cmp_gt_u32 s87, 5
	s_cbranch_scc0 .LBB0_940
	s_setprio 0
	s_and_b64 vcc, exec, s[34:35]
	s_cbranch_vccz .LBB0_943
	s_barrier

.LBB0_963:
	s_ashr_i32 s51, s50, 31
	s_lshl_b64 s[52:53], s[50:51], 19
	s_add_u32 s52, s20, s52
	s_addc_u32 s53, s21, s53
	s_and_b64 s[54:55], s[0:1], exec
	s_cselect_b32 s51, s53, s57
	s_cselect_b32 s80, s52, s56
	s_ashr_i32 s49, s48, 31
	s_lshl_b64 s[54:55], s[48:49], 19
	s_add_u32 s54, s8, s54
	s_addc_u32 s55, s9, s55
	s_and_b64 s[60:61], s[0:1], exec
	s_cselect_b32 s49, s55, s59
	s_cselect_b32 s81, s54, s58
	s_add_u32 s56, s56, 0x40080
	s_addc_u32 s57, s57, 0
	s_add_u32 s82, s58, 0x100
	v_mov_b32_e32 v0, 0
	s_addc_u32 s83, s59, 0
	s_mov_b32 s85, -2
	v_mov_b32_e32 v1, v0
	v_mov_b32_e32 v2, v0
	v_mov_b32_e32 v3, v0
	v_mov_b32_e32 v4, v0
	v_mov_b32_e32 v5, v0
	v_mov_b32_e32 v6, v0
	v_mov_b32_e32 v7, v0
	v_mov_b32_e32 v8, v0
	v_mov_b32_e32 v9, v0
	v_mov_b32_e32 v10, v0
	v_mov_b32_e32 v11, v0
	v_mov_b32_e32 v12, v0
	v_mov_b32_e32 v13, v0
	v_mov_b32_e32 v14, v0
	v_mov_b32_e32 v15, v0
	v_mov_b32_e32 v24, v0
	v_mov_b32_e32 v25, v0
	v_mov_b32_e32 v26, v0
	v_mov_b32_e32 v27, v0
	v_mov_b32_e32 v28, v0
	v_mov_b32_e32 v29, v0
	v_mov_b32_e32 v30, v0
	v_mov_b32_e32 v31, v0
	v_mov_b32_e32 v40, v0
	v_mov_b32_e32 v41, v0
	v_mov_b32_e32 v42, v0
	v_mov_b32_e32 v43, v0
	v_mov_b32_e32 v44, v0
	v_mov_b32_e32 v45, v0
	v_mov_b32_e32 v46, v0
	v_mov_b32_e32 v47, v0
	v_mov_b32_e32 v16, v0
	v_mov_b32_e32 v17, v0
	v_mov_b32_e32 v18, v0
	v_mov_b32_e32 v19, v0
	v_mov_b32_e32 v20, v0
	v_mov_b32_e32 v21, v0
	v_mov_b32_e32 v22, v0
	v_mov_b32_e32 v23, v0
	v_mov_b32_e32 v32, v0
	v_mov_b32_e32 v33, v0
	v_mov_b32_e32 v34, v0
	v_mov_b32_e32 v35, v0
	v_mov_b32_e32 v36, v0
	v_mov_b32_e32 v37, v0
	v_mov_b32_e32 v38, v0
	v_mov_b32_e32 v39, v0
	v_mov_b32_e32 v48, v0
	v_mov_b32_e32 v49, v0
	v_mov_b32_e32 v50, v0
	v_mov_b32_e32 v51, v0
	v_mov_b32_e32 v52, v0
	v_mov_b32_e32 v53, v0
	v_mov_b32_e32 v54, v0
	v_mov_b32_e32 v55, v0
	v_mov_b32_e32 v56, v0
	v_mov_b32_e32 v57, v0
	v_mov_b32_e32 v58, v0
	v_mov_b32_e32 v59, v0
	v_mov_b32_e32 v60, v0
	v_mov_b32_e32 v61, v0
	v_mov_b32_e32 v62, v0
	v_mov_b32_e32 v63, v0
	v_mov_b32_e32 v64, v0
	v_mov_b32_e32 v65, v0
	v_mov_b32_e32 v66, v0
	v_mov_b32_e32 v67, v0
	v_mov_b32_e32 v68, v0
	v_mov_b32_e32 v69, v0
	v_mov_b32_e32 v70, v0
	v_mov_b32_e32 v71, v0
	v_mov_b32_e32 v72, v0
	v_mov_b32_e32 v73, v0
	v_mov_b32_e32 v74, v0
	v_mov_b32_e32 v75, v0
	v_mov_b32_e32 v76, v0
	v_mov_b32_e32 v77, v0
	v_mov_b32_e32 v78, v0
	v_mov_b32_e32 v79, v0
	v_mov_b32_e32 v88, v0
	v_mov_b32_e32 v89, v0
	v_mov_b32_e32 v90, v0
	v_mov_b32_e32 v91, v0
	v_mov_b32_e32 v92, v0
	v_mov_b32_e32 v93, v0
	v_mov_b32_e32 v94, v0
	v_mov_b32_e32 v95, v0
	v_mov_b32_e32 v104, v0
	v_mov_b32_e32 v105, v0
	v_mov_b32_e32 v106, v0
	v_mov_b32_e32 v107, v0
	v_mov_b32_e32 v108, v0
	v_mov_b32_e32 v109, v0
	v_mov_b32_e32 v110, v0
	v_mov_b32_e32 v111, v0
	v_mov_b32_e32 v80, v0
	v_mov_b32_e32 v81, v0
	v_mov_b32_e32 v82, v0
	v_mov_b32_e32 v83, v0
	v_mov_b32_e32 v84, v0
	v_mov_b32_e32 v85, v0
	v_mov_b32_e32 v86, v0
	v_mov_b32_e32 v87, v0
	v_mov_b32_e32 v96, v0
	v_mov_b32_e32 v97, v0
	v_mov_b32_e32 v98, v0
	v_mov_b32_e32 v99, v0
	v_mov_b32_e32 v100, v0
	v_mov_b32_e32 v101, v0
	v_mov_b32_e32 v102, v0
	v_mov_b32_e32 v103, v0
	v_mov_b32_e32 v112, v0
	v_mov_b32_e32 v113, v0
	v_mov_b32_e32 v114, v0
	v_mov_b32_e32 v115, v0
	v_mov_b32_e32 v116, v0
	v_mov_b32_e32 v117, v0
	v_mov_b32_e32 v118, v0
	v_mov_b32_e32 v119, v0
	v_mov_b32_e32 v120, v0
	v_mov_b32_e32 v121, v0
	v_mov_b32_e32 v122, v0
	v_mov_b32_e32 v123, v0
	v_mov_b32_e32 v124, v0
	v_mov_b32_e32 v125, v0
	v_mov_b32_e32 v126, v0
	v_mov_b32_e32 v127, v0
	s_and_b64 vcc, exec, s[38:39]
	s_cbranch_vccnz .Lmy_pr_5
	s_setprio 1
.Lmy_pr_5:
.LBB0_964:
	ds_read_b128 v[150:153], v147
	ds_read_b128 v[154:157], v147 offset:1024
	ds_read_b128 v[158:161], v147 offset:2048
	ds_read_b128 v[162:165], v147 offset:3072
	ds_read_b128 v[166:169], v148
	ds_read_b128 v[170:173], v148 offset:1024
	ds_read_b128 v[174:177], v148 offset:2048
	ds_read_b128 v[178:181], v148 offset:3072
	s_add_u32 s58, s56, 0xfffc0080
	s_addc_u32 s59, s57, -1
	s_cmp_eq_u32 s85, 12
	s_cselect_b32 s61, s51, s59
	s_cselect_b32 s60, s80, s58
	s_cselect_b32 s59, s49, s83
	s_cselect_b32 s58, s81, s82
	v_lshl_add_u64 v[214:215], s[56:57], 0, v[136:137]
	s_add_i32 m0, s47, 0xc000
	ds_read_b128 v[182:185], v149
	ds_read_b128 v[186:189], v149 offset:1024
	ds_read_b128 v[190:193], v149 offset:2048
	ds_read_b128 v[194:197], v149 offset:3072
	ds_read_b128 v[198:201], v149 offset:4096
	ds_read_b128 v[202:205], v149 offset:5120
	ds_read_b128 v[206:209], v149 offset:6144
	ds_read_b128 v[210:213], v149 offset:7168
	global_load_lds_dwordx4 v[214:215], off
	v_lshl_add_u64 v[214:215], s[56:57], 0, v[138:139]
	s_add_i32 m0, s47, 0xe000
	s_nop 0
	global_load_lds_dwordx4 v[214:215], off
	s_waitcnt vmcnt(8)
	s_waitcnt lgkmcnt(0)
	s_barrier
	s_waitcnt lgkmcnt(0)
	v_mfma_f32_16x16x32_bf16 v[124:127], v[150:153], v[182:185], v[124:127]
	v_mfma_f32_16x16x32_bf16 v[120:123], v[158:161], v[182:185], v[120:123]
	v_mfma_f32_16x16x32_bf16 v[116:119], v[150:153], v[190:193], v[116:119]
	v_mfma_f32_16x16x32_bf16 v[112:115], v[158:161], v[190:193], v[112:115]
	v_mfma_f32_16x16x32_bf16 v[100:103], v[150:153], v[198:201], v[100:103]
	v_mfma_f32_16x16x32_bf16 v[96:99], v[158:161], v[198:201], v[96:99]
	v_mfma_f32_16x16x32_bf16 v[84:87], v[150:153], v[206:209], v[84:87]
	v_mfma_f32_16x16x32_bf16 v[80:83], v[158:161], v[206:209], v[80:83]
	v_mfma_f32_16x16x32_bf16 v[124:127], v[154:157], v[186:189], v[124:127]
	v_mfma_f32_16x16x32_bf16 v[120:123], v[162:165], v[186:189], v[120:123]
	v_mfma_f32_16x16x32_bf16 v[116:119], v[154:157], v[194:197], v[116:119]
	v_mfma_f32_16x16x32_bf16 v[112:115], v[162:165], v[194:197], v[112:115]
	v_mfma_f32_16x16x32_bf16 v[100:103], v[154:157], v[202:205], v[100:103]
	v_mfma_f32_16x16x32_bf16 v[96:99], v[162:165], v[202:205], v[96:99]
	v_mfma_f32_16x16x32_bf16 v[84:87], v[154:157], v[210:213], v[84:87]
	v_mfma_f32_16x16x32_bf16 v[80:83], v[162:165], v[210:213], v[80:83]
	v_mfma_f32_16x16x32_bf16 v[108:111], v[166:169], v[182:185], v[108:111]
	v_mfma_f32_16x16x32_bf16 v[104:107], v[174:177], v[182:185], v[104:107]
	v_mfma_f32_16x16x32_bf16 v[92:95], v[166:169], v[190:193], v[92:95]
	v_mfma_f32_16x16x32_bf16 v[88:91], v[174:177], v[190:193], v[88:91]
	v_mfma_f32_16x16x32_bf16 v[76:79], v[166:169], v[198:201], v[76:79]
	v_mfma_f32_16x16x32_bf16 v[72:75], v[174:177], v[198:201], v[72:75]
	v_mfma_f32_16x16x32_bf16 v[68:71], v[166:169], v[206:209], v[68:71]
	v_mfma_f32_16x16x32_bf16 v[64:67], v[174:177], v[206:209], v[64:67]
	v_mfma_f32_16x16x32_bf16 v[108:111], v[170:173], v[186:189], v[108:111]
	v_mfma_f32_16x16x32_bf16 v[104:107], v[178:181], v[186:189], v[104:107]
	v_mfma_f32_16x16x32_bf16 v[92:95], v[170:173], v[194:197], v[92:95]
	v_mfma_f32_16x16x32_bf16 v[88:91], v[178:181], v[194:197], v[88:91]
	v_mfma_f32_16x16x32_bf16 v[76:79], v[170:173], v[202:205], v[76:79]
	v_mfma_f32_16x16x32_bf16 v[72:75], v[178:181], v[202:205], v[72:75]
	v_mfma_f32_16x16x32_bf16 v[68:71], v[170:173], v[210:213], v[68:71]
	v_mfma_f32_16x16x32_bf16 v[64:67], v[178:181], v[210:213], v[64:67]
	s_barrier
	s_add_i32 s86, s71, s62
	v_lshl_add_u64 v[214:215], s[58:59], 0, v[130:131]
	s_mov_b32 m0, s86
	ds_read_b128 v[182:185], v149 offset:16384
	ds_read_b128 v[186:189], v149 offset:17408
	ds_read_b128 v[190:193], v149 offset:18432
	ds_read_b128 v[194:197], v149 offset:19456
	ds_read_b128 v[198:201], v149 offset:20480
	ds_read_b128 v[202:205], v149 offset:21504
	ds_read_b128 v[206:209], v149 offset:22528
	ds_read_b128 v[210:213], v149 offset:23552
	global_load_lds_dwordx4 v[214:215], off
	s_add_i32 m0, s86, 0x2000
	s_add_u32 s86, s58, 0x40000
	v_lshl_add_u64 v[216:217], s[58:59], 0, v[134:135]
	s_addc_u32 s87, s59, 0
	s_add_i32 s88, s72, s62
	global_load_lds_dwordx4 v[216:217], off
	v_lshl_add_u64 v[218:219], s[86:87], 0, v[130:131]
	s_mov_b32 m0, s88
	v_lshl_add_u64 v[220:221], s[60:61], 0, v[132:133]
	global_load_lds_dwordx4 v[218:219], off
	v_lshl_add_u64 v[218:219], s[86:87], 0, v[134:135]
	s_add_i32 m0, s88, 0x2000
	s_nop 0
	global_load_lds_dwordx4 v[218:219], off
	v_lshl_add_u64 v[218:219], s[60:61], 0, v[128:129]
	s_mov_b32 m0, s47
	s_nop 0
	global_load_lds_dwordx4 v[218:219], off
	s_mov_b32 m0, s63
	s_nop 0
	global_load_lds_dwordx4 v[220:221], off
	s_waitcnt vmcnt(8)
	s_waitcnt lgkmcnt(0)
	s_barrier
	s_waitcnt lgkmcnt(0)
	v_mfma_f32_16x16x32_bf16 v[60:63], v[150:153], v[182:185], v[60:63]
	v_mfma_f32_16x16x32_bf16 v[56:59], v[158:161], v[182:185], v[56:59]
	v_mfma_f32_16x16x32_bf16 v[52:55], v[150:153], v[190:193], v[52:55]
	v_mfma_f32_16x16x32_bf16 v[48:51], v[158:161], v[190:193], v[48:51]
	v_mfma_f32_16x16x32_bf16 v[36:39], v[150:153], v[198:201], v[36:39]
	v_mfma_f32_16x16x32_bf16 v[32:35], v[158:161], v[198:201], v[32:35]
	v_mfma_f32_16x16x32_bf16 v[20:23], v[150:153], v[206:209], v[20:23]
	v_mfma_f32_16x16x32_bf16 v[16:19], v[158:161], v[206:209], v[16:19]
	v_mfma_f32_16x16x32_bf16 v[60:63], v[154:157], v[186:189], v[60:63]
	v_mfma_f32_16x16x32_bf16 v[56:59], v[162:165], v[186:189], v[56:59]
	v_mfma_f32_16x16x32_bf16 v[52:55], v[154:157], v[194:197], v[52:55]
	v_mfma_f32_16x16x32_bf16 v[48:51], v[162:165], v[194:197], v[48:51]
	v_mfma_f32_16x16x32_bf16 v[36:39], v[154:157], v[202:205], v[36:39]
	v_mfma_f32_16x16x32_bf16 v[32:35], v[162:165], v[202:205], v[32:35]
	v_mfma_f32_16x16x32_bf16 v[20:23], v[154:157], v[210:213], v[20:23]
	v_mfma_f32_16x16x32_bf16 v[16:19], v[162:165], v[210:213], v[16:19]
	v_mfma_f32_16x16x32_bf16 v[44:47], v[166:169], v[182:185], v[44:47]
	v_mfma_f32_16x16x32_bf16 v[40:43], v[174:177], v[182:185], v[40:43]
	v_mfma_f32_16x16x32_bf16 v[28:31], v[166:169], v[190:193], v[28:31]
	v_mfma_f32_16x16x32_bf16 v[24:27], v[174:177], v[190:193], v[24:27]
	v_mfma_f32_16x16x32_bf16 v[12:15], v[166:169], v[198:201], v[12:15]
	v_mfma_f32_16x16x32_bf16 v[8:11], v[174:177], v[198:201], v[8:11]
	v_mfma_f32_16x16x32_bf16 v[4:7], v[166:169], v[206:209], v[4:7]
	v_mfma_f32_16x16x32_bf16 v[0:3], v[174:177], v[206:209], v[0:3]
	v_mfma_f32_16x16x32_bf16 v[44:47], v[170:173], v[186:189], v[44:47]
	v_mfma_f32_16x16x32_bf16 v[40:43], v[178:181], v[186:189], v[40:43]
	v_mfma_f32_16x16x32_bf16 v[28:31], v[170:173], v[194:197], v[28:31]
	v_mfma_f32_16x16x32_bf16 v[24:27], v[178:181], v[194:197], v[24:27]
	v_mfma_f32_16x16x32_bf16 v[12:15], v[170:173], v[202:205], v[12:15]
	v_mfma_f32_16x16x32_bf16 v[8:11], v[178:181], v[202:205], v[8:11]
	v_mfma_f32_16x16x32_bf16 v[4:7], v[170:173], v[210:213], v[4:7]
	v_mfma_f32_16x16x32_bf16 v[0:3], v[178:181], v[210:213], v[0:3]
	s_barrier
	s_add_i32 s86, 0, 0x18000
	s_add_i32 s87, 0, 0x1c000
	v_add_u32_e32 v162, s86, v145
	v_add_u32_e32 v178, s87, v145
	ds_read_b128 v[150:153], v162
	ds_read_b128 v[154:157], v162 offset:1024
	ds_read_b128 v[158:161], v162 offset:2048
	ds_read_b128 v[162:165], v162 offset:3072
	ds_read_b128 v[166:169], v178
	ds_read_b128 v[170:173], v178 offset:1024
	ds_read_b128 v[174:177], v178 offset:2048
	ds_read_b128 v[178:181], v178 offset:3072
	s_add_u32 s60, s60, 0x40000
	s_addc_u32 s61, s61, 0
	s_mov_b32 m0, s64
	v_lshl_add_u64 v[222:223], s[60:61], 0, v[128:129]
	ds_read_b128 v[182:185], v149 offset:32768
	ds_read_b128 v[186:189], v149 offset:33792
	ds_read_b128 v[190:193], v149 offset:34816
	ds_read_b128 v[194:197], v149 offset:35840
	ds_read_b128 v[198:201], v149 offset:36864
	ds_read_b128 v[202:205], v149 offset:37888
	ds_read_b128 v[206:209], v149 offset:38912
	ds_read_b128 v[210:213], v149 offset:39936
	global_load_lds_dwordx4 v[222:223], off
	v_lshl_add_u64 v[222:223], s[60:61], 0, v[132:133]
	s_mov_b32 m0, s65
	s_nop 0
	global_load_lds_dwordx4 v[222:223], off
	s_waitcnt vmcnt(8)
	s_waitcnt lgkmcnt(0)
	s_barrier
	s_waitcnt lgkmcnt(0)
	v_mfma_f32_16x16x32_bf16 v[124:127], v[150:153], v[182:185], v[124:127]
	v_mfma_f32_16x16x32_bf16 v[120:123], v[158:161], v[182:185], v[120:123]
	v_mfma_f32_16x16x32_bf16 v[116:119], v[150:153], v[190:193], v[116:119]
	v_mfma_f32_16x16x32_bf16 v[112:115], v[158:161], v[190:193], v[112:115]
	v_mfma_f32_16x16x32_bf16 v[100:103], v[150:153], v[198:201], v[100:103]
	v_mfma_f32_16x16x32_bf16 v[96:99], v[158:161], v[198:201], v[96:99]
	v_mfma_f32_16x16x32_bf16 v[84:87], v[150:153], v[206:209], v[84:87]
	v_mfma_f32_16x16x32_bf16 v[80:83], v[158:161], v[206:209], v[80:83]
	v_mfma_f32_16x16x32_bf16 v[124:127], v[154:157], v[186:189], v[124:127]
	v_mfma_f32_16x16x32_bf16 v[120:123], v[162:165], v[186:189], v[120:123]
	v_mfma_f32_16x16x32_bf16 v[116:119], v[154:157], v[194:197], v[116:119]
	v_mfma_f32_16x16x32_bf16 v[112:115], v[162:165], v[194:197], v[112:115]
	v_mfma_f32_16x16x32_bf16 v[100:103], v[154:157], v[202:205], v[100:103]
	v_mfma_f32_16x16x32_bf16 v[96:99], v[162:165], v[202:205], v[96:99]
	v_mfma_f32_16x16x32_bf16 v[84:87], v[154:157], v[210:213], v[84:87]
	v_mfma_f32_16x16x32_bf16 v[80:83], v[162:165], v[210:213], v[80:83]
	v_mfma_f32_16x16x32_bf16 v[108:111], v[166:169], v[182:185], v[108:111]
	v_mfma_f32_16x16x32_bf16 v[104:107], v[174:177], v[182:185], v[104:107]
	v_mfma_f32_16x16x32_bf16 v[92:95], v[166:169], v[190:193], v[92:95]
	v_mfma_f32_16x16x32_bf16 v[88:91], v[174:177], v[190:193], v[88:91]
	v_mfma_f32_16x16x32_bf16 v[76:79], v[166:169], v[198:201], v[76:79]
	v_mfma_f32_16x16x32_bf16 v[72:75], v[174:177], v[198:201], v[72:75]
	v_mfma_f32_16x16x32_bf16 v[68:71], v[166:169], v[206:209], v[68:71]
	v_mfma_f32_16x16x32_bf16 v[64:67], v[174:177], v[206:209], v[64:67]
	v_mfma_f32_16x16x32_bf16 v[108:111], v[170:173], v[186:189], v[108:111]
	v_mfma_f32_16x16x32_bf16 v[104:107], v[178:181], v[186:189], v[104:107]
	v_mfma_f32_16x16x32_bf16 v[92:95], v[170:173], v[194:197], v[92:95]
	v_mfma_f32_16x16x32_bf16 v[88:91], v[178:181], v[194:197], v[88:91]
	v_mfma_f32_16x16x32_bf16 v[76:79], v[170:173], v[202:205], v[76:79]
	v_mfma_f32_16x16x32_bf16 v[72:75], v[178:181], v[202:205], v[72:75]
	v_mfma_f32_16x16x32_bf16 v[68:71], v[170:173], v[210:213], v[68:71]
	v_mfma_f32_16x16x32_bf16 v[64:67], v[178:181], v[210:213], v[64:67]
	s_barrier
	s_add_i32 s60, s86, s62
	v_lshl_add_u64 v[214:215], v[214:215], 0, s[34:35]
	s_mov_b32 m0, s60
	ds_read_b128 v[182:185], v149 offset:49152
	ds_read_b128 v[186:189], v149 offset:50176
	ds_read_b128 v[190:193], v149 offset:51200
	ds_read_b128 v[194:197], v149 offset:52224
	ds_read_b128 v[198:201], v149 offset:53248
	ds_read_b128 v[202:205], v149 offset:54272
	ds_read_b128 v[206:209], v149 offset:55296
	ds_read_b128 v[210:213], v149 offset:56320
	global_load_lds_dwordx4 v[214:215], off
	s_add_i32 m0, s60, 0x2000
	s_add_u32 s58, s58, 0x40080
	v_lshl_add_u64 v[214:215], v[216:217], 0, s[34:35]
	s_addc_u32 s59, s59, 0
	s_add_i32 s60, s87, s62
	global_load_lds_dwordx4 v[214:215], off
	v_lshl_add_u64 v[214:215], s[58:59], 0, v[130:131]
	s_mov_b32 m0, s60
	s_nop 0
	global_load_lds_dwordx4 v[214:215], off
	v_lshl_add_u64 v[214:215], s[58:59], 0, v[134:135]
	s_add_i32 m0, s60, 0x2000
	s_nop 0
	global_load_lds_dwordx4 v[214:215], off
	v_lshl_add_u64 v[214:215], v[218:219], 0, s[34:35]
	s_mov_b32 m0, s67
	s_nop 0
	global_load_lds_dwordx4 v[214:215], off
	v_lshl_add_u64 v[214:215], v[220:221], 0, s[34:35]
	s_mov_b32 m0, s68
	s_nop 0
	global_load_lds_dwordx4 v[214:215], off
	s_waitcnt vmcnt(8)
	s_waitcnt lgkmcnt(0)
	s_barrier
	s_waitcnt lgkmcnt(0)
	v_mfma_f32_16x16x32_bf16 v[60:63], v[150:153], v[182:185], v[60:63]
	v_mfma_f32_16x16x32_bf16 v[56:59], v[158:161], v[182:185], v[56:59]
	v_mfma_f32_16x16x32_bf16 v[52:55], v[150:153], v[190:193], v[52:55]
	v_mfma_f32_16x16x32_bf16 v[48:51], v[158:161], v[190:193], v[48:51]
	v_mfma_f32_16x16x32_bf16 v[36:39], v[150:153], v[198:201], v[36:39]
	v_mfma_f32_16x16x32_bf16 v[32:35], v[158:161], v[198:201], v[32:35]
	v_mfma_f32_16x16x32_bf16 v[20:23], v[150:153], v[206:209], v[20:23]
	v_mfma_f32_16x16x32_bf16 v[16:19], v[158:161], v[206:209], v[16:19]
	v_mfma_f32_16x16x32_bf16 v[60:63], v[154:157], v[186:189], v[60:63]
	v_mfma_f32_16x16x32_bf16 v[56:59], v[162:165], v[186:189], v[56:59]
	v_mfma_f32_16x16x32_bf16 v[52:55], v[154:157], v[194:197], v[52:55]
	v_mfma_f32_16x16x32_bf16 v[48:51], v[162:165], v[194:197], v[48:51]
	v_mfma_f32_16x16x32_bf16 v[36:39], v[154:157], v[202:205], v[36:39]
	v_mfma_f32_16x16x32_bf16 v[32:35], v[162:165], v[202:205], v[32:35]
	v_mfma_f32_16x16x32_bf16 v[20:23], v[154:157], v[210:213], v[20:23]
	v_mfma_f32_16x16x32_bf16 v[16:19], v[162:165], v[210:213], v[16:19]
	v_mfma_f32_16x16x32_bf16 v[44:47], v[166:169], v[182:185], v[44:47]
	v_mfma_f32_16x16x32_bf16 v[40:43], v[174:177], v[182:185], v[40:43]
	v_mfma_f32_16x16x32_bf16 v[28:31], v[166:169], v[190:193], v[28:31]
	v_mfma_f32_16x16x32_bf16 v[24:27], v[174:177], v[190:193], v[24:27]
	v_mfma_f32_16x16x32_bf16 v[12:15], v[166:169], v[198:201], v[12:15]
	v_mfma_f32_16x16x32_bf16 v[8:11], v[174:177], v[198:201], v[8:11]
	v_mfma_f32_16x16x32_bf16 v[4:7], v[166:169], v[206:209], v[4:7]
	v_mfma_f32_16x16x32_bf16 v[0:3], v[174:177], v[206:209], v[0:3]
	v_mfma_f32_16x16x32_bf16 v[44:47], v[170:173], v[186:189], v[44:47]
	v_mfma_f32_16x16x32_bf16 v[40:43], v[178:181], v[186:189], v[40:43]
	v_mfma_f32_16x16x32_bf16 v[28:31], v[170:173], v[194:197], v[28:31]
	v_mfma_f32_16x16x32_bf16 v[24:27], v[178:181], v[194:197], v[24:27]
	v_mfma_f32_16x16x32_bf16 v[12:15], v[170:173], v[202:205], v[12:15]
	v_mfma_f32_16x16x32_bf16 v[8:11], v[178:181], v[202:205], v[8:11]
	v_mfma_f32_16x16x32_bf16 v[4:7], v[170:173], v[210:213], v[4:7]
	v_mfma_f32_16x16x32_bf16 v[0:3], v[178:181], v[210:213], v[0:3]
	s_barrier
	s_add_i32 s85, s85, 2
	s_add_u32 s56, s56, 0x100
	s_addc_u32 s57, s57, 0
	s_add_u32 s82, s82, 0x100
	s_addc_u32 s83, s83, 0
	s_cmp_gt_u32 s85, 13
	s_cbranch_scc0 .LBB0_964
	s_setprio 0
	s_and_b64 vcc, exec, s[38:39]
	s_cbranch_vccz .LBB0_967
	s_barrier

.LBB0_1041:
	s_ashr_i32 s45, s44, 31
	s_lshl_b64 s[8:9], s[44:45], 19
	s_add_u32 s46, s78, s8
	s_addc_u32 s47, s79, s9
	s_and_b64 s[8:9], s[6:7], exec
	s_cselect_b32 s0, s47, s55
	s_cselect_b32 s8, s46, s54
	s_ashr_i32 s43, s42, 31
	s_lshl_b64 s[48:49], s[42:43], 19
	s_add_u32 s48, s3, s48
	s_addc_u32 s49, s62, s49
	s_and_b64 s[58:59], s[6:7], exec
	s_cselect_b32 s9, s49, s57
	s_cselect_b32 s43, s48, s56
	s_add_u32 s54, s54, 0x40080
	s_addc_u32 s55, s55, 0
	s_add_u32 s45, s56, 0x100
	v_mov_b32_e32 v0, 0
	s_addc_u32 s51, s57, 0
	s_mov_b32 s53, -2
	v_mov_b32_e32 v1, v0
	v_mov_b32_e32 v2, v0
	v_mov_b32_e32 v3, v0
	v_mov_b32_e32 v4, v0
	v_mov_b32_e32 v5, v0
	v_mov_b32_e32 v6, v0
	v_mov_b32_e32 v7, v0
	v_mov_b32_e32 v16, v0
	v_mov_b32_e32 v17, v0
	v_mov_b32_e32 v18, v0
	v_mov_b32_e32 v19, v0
	v_mov_b32_e32 v20, v0
	v_mov_b32_e32 v21, v0
	v_mov_b32_e32 v22, v0
	v_mov_b32_e32 v23, v0
	v_mov_b32_e32 v32, v0
	v_mov_b32_e32 v33, v0
	v_mov_b32_e32 v34, v0
	v_mov_b32_e32 v35, v0
	v_mov_b32_e32 v36, v0
	v_mov_b32_e32 v37, v0
	v_mov_b32_e32 v38, v0
	v_mov_b32_e32 v39, v0
	v_mov_b32_e32 v48, v0
	v_mov_b32_e32 v49, v0
	v_mov_b32_e32 v50, v0
	v_mov_b32_e32 v51, v0
	v_mov_b32_e32 v52, v0
	v_mov_b32_e32 v53, v0
	v_mov_b32_e32 v54, v0
	v_mov_b32_e32 v55, v0
	v_mov_b32_e32 v8, v0
	v_mov_b32_e32 v9, v0
	v_mov_b32_e32 v10, v0
	v_mov_b32_e32 v11, v0
	v_mov_b32_e32 v12, v0
	v_mov_b32_e32 v13, v0
	v_mov_b32_e32 v14, v0
	v_mov_b32_e32 v15, v0
	v_mov_b32_e32 v24, v0
	v_mov_b32_e32 v25, v0
	v_mov_b32_e32 v26, v0
	v_mov_b32_e32 v27, v0
	v_mov_b32_e32 v28, v0
	v_mov_b32_e32 v29, v0
	v_mov_b32_e32 v30, v0
	v_mov_b32_e32 v31, v0
	v_mov_b32_e32 v40, v0
	v_mov_b32_e32 v41, v0
	v_mov_b32_e32 v42, v0
	v_mov_b32_e32 v43, v0
	v_mov_b32_e32 v44, v0
	v_mov_b32_e32 v45, v0
	v_mov_b32_e32 v46, v0
	v_mov_b32_e32 v47, v0
	v_mov_b32_e32 v56, v0
	v_mov_b32_e32 v57, v0
	v_mov_b32_e32 v58, v0
	v_mov_b32_e32 v59, v0
	v_mov_b32_e32 v60, v0
	v_mov_b32_e32 v61, v0
	v_mov_b32_e32 v62, v0
	v_mov_b32_e32 v63, v0
	v_mov_b32_e32 v64, v0
	v_mov_b32_e32 v65, v0
	v_mov_b32_e32 v66, v0
	v_mov_b32_e32 v67, v0
	v_mov_b32_e32 v68, v0
	v_mov_b32_e32 v69, v0
	v_mov_b32_e32 v70, v0
	v_mov_b32_e32 v71, v0
	v_mov_b32_e32 v80, v0
	v_mov_b32_e32 v81, v0
	v_mov_b32_e32 v82, v0
	v_mov_b32_e32 v83, v0
	v_mov_b32_e32 v84, v0
	v_mov_b32_e32 v85, v0
	v_mov_b32_e32 v86, v0
	v_mov_b32_e32 v87, v0
	v_mov_b32_e32 v96, v0
	v_mov_b32_e32 v97, v0
	v_mov_b32_e32 v98, v0
	v_mov_b32_e32 v99, v0
	v_mov_b32_e32 v100, v0
	v_mov_b32_e32 v101, v0
	v_mov_b32_e32 v102, v0
	v_mov_b32_e32 v103, v0
	v_mov_b32_e32 v112, v0
	v_mov_b32_e32 v113, v0
	v_mov_b32_e32 v114, v0
	v_mov_b32_e32 v115, v0
	v_mov_b32_e32 v116, v0
	v_mov_b32_e32 v117, v0
	v_mov_b32_e32 v118, v0
	v_mov_b32_e32 v119, v0
	v_mov_b32_e32 v72, v0
	v_mov_b32_e32 v73, v0
	v_mov_b32_e32 v74, v0
	v_mov_b32_e32 v75, v0
	v_mov_b32_e32 v76, v0
	v_mov_b32_e32 v77, v0
	v_mov_b32_e32 v78, v0
	v_mov_b32_e32 v79, v0
	v_mov_b32_e32 v88, v0
	v_mov_b32_e32 v89, v0
	v_mov_b32_e32 v90, v0
	v_mov_b32_e32 v91, v0
	v_mov_b32_e32 v92, v0
	v_mov_b32_e32 v93, v0
	v_mov_b32_e32 v94, v0
	v_mov_b32_e32 v95, v0
	v_mov_b32_e32 v104, v0
	v_mov_b32_e32 v105, v0
	v_mov_b32_e32 v106, v0
	v_mov_b32_e32 v107, v0
	v_mov_b32_e32 v108, v0
	v_mov_b32_e32 v109, v0
	v_mov_b32_e32 v110, v0
	v_mov_b32_e32 v111, v0
	v_mov_b32_e32 v120, v0
	v_mov_b32_e32 v121, v0
	v_mov_b32_e32 v122, v0
	v_mov_b32_e32 v123, v0
	v_mov_b32_e32 v124, v0
	v_mov_b32_e32 v125, v0
	v_mov_b32_e32 v126, v0
	v_mov_b32_e32 v127, v0
	s_and_b64 vcc, exec, s[22:23]
	s_cbranch_vccnz .Lmy_pr_6
	s_setprio 1
.Lmy_pr_6:
.LBB0_1042:
	ds_read_b128 v[128:131], v185
	ds_read_b128 v[132:135], v185 offset:1024
	ds_read_b128 v[136:139], v185 offset:2048
	ds_read_b128 v[140:143], v185 offset:3072
	ds_read_b128 v[144:147], v186
	ds_read_b128 v[148:151], v186 offset:1024
	ds_read_b128 v[172:175], v186 offset:2048
	ds_read_b128 v[176:179], v186 offset:3072
	s_add_u32 s56, s54, 0xfffc0080
	s_addc_u32 s57, s55, -1
	s_cmp_eq_u32 s53, 12
	s_cselect_b32 s59, s0, s57
	s_cselect_b32 s58, s8, s56
	s_cselect_b32 s57, s9, s51
	s_cselect_b32 s56, s43, s45
	v_lshl_add_u64 v[180:181], s[54:55], 0, v[164:165]
	s_add_i32 m0, s64, 0xc000
	ds_read_b128 v[190:193], v187
	ds_read_b128 v[194:197], v187 offset:1024
	ds_read_b128 v[198:201], v187 offset:2048
	ds_read_b128 v[202:205], v187 offset:3072
	ds_read_b128 v[206:209], v187 offset:4096
	ds_read_b128 v[210:213], v187 offset:5120
	ds_read_b128 v[214:217], v187 offset:6144
	ds_read_b128 v[218:221], v187 offset:7168
	global_load_lds_dwordx4 v[180:181], off
	v_lshl_add_u64 v[180:181], s[54:55], 0, v[166:167]
	s_add_i32 m0, s64, 0xe000
	s_nop 0
	global_load_lds_dwordx4 v[180:181], off
	s_waitcnt vmcnt(8)
	s_waitcnt lgkmcnt(0)
	s_barrier
	s_waitcnt lgkmcnt(0)
	v_mfma_f32_16x16x32_bf16 v[124:127], v[128:131], v[190:193], v[124:127]
	v_mfma_f32_16x16x32_bf16 v[120:123], v[136:139], v[190:193], v[120:123]
	v_mfma_f32_16x16x32_bf16 v[108:111], v[128:131], v[198:201], v[108:111]
	v_mfma_f32_16x16x32_bf16 v[104:107], v[136:139], v[198:201], v[104:107]
	v_mfma_f32_16x16x32_bf16 v[92:95], v[128:131], v[206:209], v[92:95]
	v_mfma_f32_16x16x32_bf16 v[88:91], v[136:139], v[206:209], v[88:91]
	v_mfma_f32_16x16x32_bf16 v[76:79], v[128:131], v[214:217], v[76:79]
	v_mfma_f32_16x16x32_bf16 v[72:75], v[136:139], v[214:217], v[72:75]
	v_mfma_f32_16x16x32_bf16 v[124:127], v[132:135], v[194:197], v[124:127]
	v_mfma_f32_16x16x32_bf16 v[120:123], v[140:143], v[194:197], v[120:123]
	v_mfma_f32_16x16x32_bf16 v[108:111], v[132:135], v[202:205], v[108:111]
	v_mfma_f32_16x16x32_bf16 v[104:107], v[140:143], v[202:205], v[104:107]
	v_mfma_f32_16x16x32_bf16 v[92:95], v[132:135], v[210:213], v[92:95]
	v_mfma_f32_16x16x32_bf16 v[88:91], v[140:143], v[210:213], v[88:91]
	v_mfma_f32_16x16x32_bf16 v[76:79], v[132:135], v[218:221], v[76:79]
	v_mfma_f32_16x16x32_bf16 v[72:75], v[140:143], v[218:221], v[72:75]
	v_mfma_f32_16x16x32_bf16 v[116:119], v[144:147], v[190:193], v[116:119]
	v_mfma_f32_16x16x32_bf16 v[112:115], v[172:175], v[190:193], v[112:115]
	v_mfma_f32_16x16x32_bf16 v[100:103], v[144:147], v[198:201], v[100:103]
	v_mfma_f32_16x16x32_bf16 v[96:99], v[172:175], v[198:201], v[96:99]
	v_mfma_f32_16x16x32_bf16 v[84:87], v[144:147], v[206:209], v[84:87]
	v_mfma_f32_16x16x32_bf16 v[80:83], v[172:175], v[206:209], v[80:83]
	v_mfma_f32_16x16x32_bf16 v[68:71], v[144:147], v[214:217], v[68:71]
	v_mfma_f32_16x16x32_bf16 v[64:67], v[172:175], v[214:217], v[64:67]
	v_mfma_f32_16x16x32_bf16 v[116:119], v[148:151], v[194:197], v[116:119]
	v_mfma_f32_16x16x32_bf16 v[112:115], v[176:179], v[194:197], v[112:115]
	v_mfma_f32_16x16x32_bf16 v[100:103], v[148:151], v[202:205], v[100:103]
	v_mfma_f32_16x16x32_bf16 v[96:99], v[176:179], v[202:205], v[96:99]
	v_mfma_f32_16x16x32_bf16 v[84:87], v[148:151], v[210:213], v[84:87]
	v_mfma_f32_16x16x32_bf16 v[80:83], v[176:179], v[210:213], v[80:83]
	v_mfma_f32_16x16x32_bf16 v[68:71], v[148:151], v[218:221], v[68:71]
	v_mfma_f32_16x16x32_bf16 v[64:67], v[176:179], v[218:221], v[64:67]
	s_barrier
	s_add_i32 s60, s74, s63
	v_lshl_add_u64 v[180:181], s[56:57], 0, v[154:155]
	s_mov_b32 m0, s60
	ds_read_b128 v[190:193], v187 offset:16384
	ds_read_b128 v[194:197], v187 offset:17408
	ds_read_b128 v[198:201], v187 offset:18432
	ds_read_b128 v[202:205], v187 offset:19456
	ds_read_b128 v[206:209], v187 offset:20480
	ds_read_b128 v[210:213], v187 offset:21504
	ds_read_b128 v[214:217], v187 offset:22528
	ds_read_b128 v[218:221], v187 offset:23552
	global_load_lds_dwordx4 v[180:181], off
	s_add_i32 m0, s60, 0x2000
	s_add_u32 s60, s56, 0x40000
	v_lshl_add_u64 v[222:223], s[56:57], 0, v[158:159]
	s_addc_u32 s61, s57, 0
	s_add_i32 s82, s75, s63
	global_load_lds_dwordx4 v[222:223], off
	v_lshl_add_u64 v[224:225], s[60:61], 0, v[154:155]
	s_mov_b32 m0, s82
	v_lshl_add_u64 v[226:227], s[58:59], 0, v[156:157]
	global_load_lds_dwordx4 v[224:225], off
	v_lshl_add_u64 v[224:225], s[60:61], 0, v[158:159]
	s_add_i32 m0, s82, 0x2000
	s_nop 0
	global_load_lds_dwordx4 v[224:225], off
	v_lshl_add_u64 v[224:225], s[58:59], 0, v[152:153]
	s_mov_b32 m0, s64
	s_nop 0
	global_load_lds_dwordx4 v[224:225], off
	s_mov_b32 m0, s65
	s_nop 0
	global_load_lds_dwordx4 v[226:227], off
	s_waitcnt vmcnt(8)
	s_waitcnt lgkmcnt(0)
	s_barrier
	s_waitcnt lgkmcnt(0)
	v_mfma_f32_16x16x32_bf16 v[60:63], v[128:131], v[190:193], v[60:63]
	v_mfma_f32_16x16x32_bf16 v[56:59], v[136:139], v[190:193], v[56:59]
	v_mfma_f32_16x16x32_bf16 v[44:47], v[128:131], v[198:201], v[44:47]
	v_mfma_f32_16x16x32_bf16 v[40:43], v[136:139], v[198:201], v[40:43]
	v_mfma_f32_16x16x32_bf16 v[28:31], v[128:131], v[206:209], v[28:31]
	v_mfma_f32_16x16x32_bf16 v[24:27], v[136:139], v[206:209], v[24:27]
	v_mfma_f32_16x16x32_bf16 v[12:15], v[128:131], v[214:217], v[12:15]
	v_mfma_f32_16x16x32_bf16 v[8:11], v[136:139], v[214:217], v[8:11]
	v_mfma_f32_16x16x32_bf16 v[60:63], v[132:135], v[194:197], v[60:63]
	v_mfma_f32_16x16x32_bf16 v[56:59], v[140:143], v[194:197], v[56:59]
	v_mfma_f32_16x16x32_bf16 v[44:47], v[132:135], v[202:205], v[44:47]
	v_mfma_f32_16x16x32_bf16 v[40:43], v[140:143], v[202:205], v[40:43]
	v_mfma_f32_16x16x32_bf16 v[28:31], v[132:135], v[210:213], v[28:31]
	v_mfma_f32_16x16x32_bf16 v[24:27], v[140:143], v[210:213], v[24:27]
	v_mfma_f32_16x16x32_bf16 v[12:15], v[132:135], v[218:221], v[12:15]
	v_mfma_f32_16x16x32_bf16 v[8:11], v[140:143], v[218:221], v[8:11]
	v_mfma_f32_16x16x32_bf16 v[52:55], v[144:147], v[190:193], v[52:55]
	v_mfma_f32_16x16x32_bf16 v[48:51], v[172:175], v[190:193], v[48:51]
	v_mfma_f32_16x16x32_bf16 v[36:39], v[144:147], v[198:201], v[36:39]
	v_mfma_f32_16x16x32_bf16 v[32:35], v[172:175], v[198:201], v[32:35]
	v_mfma_f32_16x16x32_bf16 v[20:23], v[144:147], v[206:209], v[20:23]
	v_mfma_f32_16x16x32_bf16 v[16:19], v[172:175], v[206:209], v[16:19]
	v_mfma_f32_16x16x32_bf16 v[4:7], v[144:147], v[214:217], v[4:7]
	v_mfma_f32_16x16x32_bf16 v[0:3], v[172:175], v[214:217], v[0:3]
	v_mfma_f32_16x16x32_bf16 v[52:55], v[148:151], v[194:197], v[52:55]
	v_mfma_f32_16x16x32_bf16 v[48:51], v[176:179], v[194:197], v[48:51]
	v_mfma_f32_16x16x32_bf16 v[36:39], v[148:151], v[202:205], v[36:39]
	v_mfma_f32_16x16x32_bf16 v[32:35], v[176:179], v[202:205], v[32:35]
	v_mfma_f32_16x16x32_bf16 v[20:23], v[148:151], v[210:213], v[20:23]
	v_mfma_f32_16x16x32_bf16 v[16:19], v[176:179], v[210:213], v[16:19]
	v_mfma_f32_16x16x32_bf16 v[4:7], v[148:151], v[218:221], v[4:7]
	v_mfma_f32_16x16x32_bf16 v[0:3], v[176:179], v[218:221], v[0:3]
	s_barrier
	s_add_i32 s60, 0, 0x18000
	s_add_i32 s61, 0, 0x1c000
	v_add_u32_e32 v140, s60, v182
	v_add_u32_e32 v160, s61, v182
	ds_read_b128 v[128:131], v140
	ds_read_b128 v[132:135], v140 offset:1024
	ds_read_b128 v[136:139], v140 offset:2048
	ds_read_b128 v[140:143], v140 offset:3072
	ds_read_b128 v[144:147], v160
	ds_read_b128 v[148:151], v160 offset:1024
	ds_read_b128 v[172:175], v160 offset:2048
	ds_read_b128 v[176:179], v160 offset:3072
	s_add_u32 s58, s58, 0x40000
	s_addc_u32 s59, s59, 0
	s_mov_b32 m0, s66
	v_lshl_add_u64 v[228:229], s[58:59], 0, v[152:153]
	ds_read_b128 v[190:193], v187 offset:32768
	ds_read_b128 v[194:197], v187 offset:33792
	ds_read_b128 v[198:201], v187 offset:34816
	ds_read_b128 v[202:205], v187 offset:35840
	ds_read_b128 v[206:209], v187 offset:36864
	ds_read_b128 v[210:213], v187 offset:37888
	ds_read_b128 v[214:217], v187 offset:38912
	ds_read_b128 v[218:221], v187 offset:39936
	global_load_lds_dwordx4 v[228:229], off
	v_lshl_add_u64 v[228:229], s[58:59], 0, v[156:157]
	s_mov_b32 m0, s67
	s_nop 0
	global_load_lds_dwordx4 v[228:229], off
	s_waitcnt vmcnt(8)
	s_waitcnt lgkmcnt(0)
	s_barrier
	s_waitcnt lgkmcnt(0)
	v_mfma_f32_16x16x32_bf16 v[124:127], v[128:131], v[190:193], v[124:127]
	v_mfma_f32_16x16x32_bf16 v[120:123], v[136:139], v[190:193], v[120:123]
	v_mfma_f32_16x16x32_bf16 v[108:111], v[128:131], v[198:201], v[108:111]
	v_mfma_f32_16x16x32_bf16 v[104:107], v[136:139], v[198:201], v[104:107]
	v_mfma_f32_16x16x32_bf16 v[92:95], v[128:131], v[206:209], v[92:95]
	v_mfma_f32_16x16x32_bf16 v[88:91], v[136:139], v[206:209], v[88:91]
	v_mfma_f32_16x16x32_bf16 v[76:79], v[128:131], v[214:217], v[76:79]
	v_mfma_f32_16x16x32_bf16 v[72:75], v[136:139], v[214:217], v[72:75]
	v_mfma_f32_16x16x32_bf16 v[124:127], v[132:135], v[194:197], v[124:127]
	v_mfma_f32_16x16x32_bf16 v[120:123], v[140:143], v[194:197], v[120:123]
	v_mfma_f32_16x16x32_bf16 v[108:111], v[132:135], v[202:205], v[108:111]
	v_mfma_f32_16x16x32_bf16 v[104:107], v[140:143], v[202:205], v[104:107]
	v_mfma_f32_16x16x32_bf16 v[92:95], v[132:135], v[210:213], v[92:95]
	v_mfma_f32_16x16x32_bf16 v[88:91], v[140:143], v[210:213], v[88:91]
	v_mfma_f32_16x16x32_bf16 v[76:79], v[132:135], v[218:221], v[76:79]
	v_mfma_f32_16x16x32_bf16 v[72:75], v[140:143], v[218:221], v[72:75]
	v_mfma_f32_16x16x32_bf16 v[116:119], v[144:147], v[190:193], v[116:119]
	v_mfma_f32_16x16x32_bf16 v[112:115], v[172:175], v[190:193], v[112:115]
	v_mfma_f32_16x16x32_bf16 v[100:103], v[144:147], v[198:201], v[100:103]
	v_mfma_f32_16x16x32_bf16 v[96:99], v[172:175], v[198:201], v[96:99]
	v_mfma_f32_16x16x32_bf16 v[84:87], v[144:147], v[206:209], v[84:87]
	v_mfma_f32_16x16x32_bf16 v[80:83], v[172:175], v[206:209], v[80:83]
	v_mfma_f32_16x16x32_bf16 v[68:71], v[144:147], v[214:217], v[68:71]
	v_mfma_f32_16x16x32_bf16 v[64:67], v[172:175], v[214:217], v[64:67]
	v_mfma_f32_16x16x32_bf16 v[116:119], v[148:151], v[194:197], v[116:119]
	v_mfma_f32_16x16x32_bf16 v[112:115], v[176:179], v[194:197], v[112:115]
	v_mfma_f32_16x16x32_bf16 v[100:103], v[148:151], v[202:205], v[100:103]
	v_mfma_f32_16x16x32_bf16 v[96:99], v[176:179], v[202:205], v[96:99]
	v_mfma_f32_16x16x32_bf16 v[84:87], v[148:151], v[210:213], v[84:87]
	v_mfma_f32_16x16x32_bf16 v[80:83], v[176:179], v[210:213], v[80:83]
	v_mfma_f32_16x16x32_bf16 v[68:71], v[148:151], v[218:221], v[68:71]
	v_mfma_f32_16x16x32_bf16 v[64:67], v[176:179], v[218:221], v[64:67]
	s_barrier
	s_add_i32 s58, s60, s63
	v_lshl_add_u64 v[180:181], v[180:181], 0, s[20:21]
	s_mov_b32 m0, s58
	ds_read_b128 v[190:193], v187 offset:49152
	ds_read_b128 v[194:197], v187 offset:50176
	ds_read_b128 v[198:201], v187 offset:51200
	ds_read_b128 v[202:205], v187 offset:52224
	ds_read_b128 v[206:209], v187 offset:53248
	ds_read_b128 v[210:213], v187 offset:54272
	ds_read_b128 v[214:217], v187 offset:55296
	ds_read_b128 v[218:221], v187 offset:56320
	global_load_lds_dwordx4 v[180:181], off
	s_add_i32 m0, s58, 0x2000
	s_add_u32 s56, s56, 0x40080
	v_lshl_add_u64 v[180:181], v[222:223], 0, s[20:21]
	s_addc_u32 s57, s57, 0
	s_add_i32 s58, s61, s63
	global_load_lds_dwordx4 v[180:181], off
	v_lshl_add_u64 v[180:181], s[56:57], 0, v[154:155]
	s_mov_b32 m0, s58
	s_nop 0
	global_load_lds_dwordx4 v[180:181], off
	v_lshl_add_u64 v[180:181], s[56:57], 0, v[158:159]
	s_add_i32 m0, s58, 0x2000
	s_nop 0
	global_load_lds_dwordx4 v[180:181], off
	v_lshl_add_u64 v[180:181], v[224:225], 0, s[20:21]
	s_mov_b32 m0, s69
	s_nop 0
	global_load_lds_dwordx4 v[180:181], off
	v_lshl_add_u64 v[180:181], v[226:227], 0, s[20:21]
	s_mov_b32 m0, s70
	s_nop 0
	global_load_lds_dwordx4 v[180:181], off
	s_waitcnt vmcnt(8)
	s_waitcnt lgkmcnt(0)
	s_barrier
	s_waitcnt lgkmcnt(0)
	v_mfma_f32_16x16x32_bf16 v[60:63], v[128:131], v[190:193], v[60:63]
	v_mfma_f32_16x16x32_bf16 v[56:59], v[136:139], v[190:193], v[56:59]
	v_mfma_f32_16x16x32_bf16 v[44:47], v[128:131], v[198:201], v[44:47]
	v_mfma_f32_16x16x32_bf16 v[40:43], v[136:139], v[198:201], v[40:43]
	v_mfma_f32_16x16x32_bf16 v[28:31], v[128:131], v[206:209], v[28:31]
	v_mfma_f32_16x16x32_bf16 v[24:27], v[136:139], v[206:209], v[24:27]
	v_mfma_f32_16x16x32_bf16 v[12:15], v[128:131], v[214:217], v[12:15]
	v_mfma_f32_16x16x32_bf16 v[8:11], v[136:139], v[214:217], v[8:11]
	v_mfma_f32_16x16x32_bf16 v[60:63], v[132:135], v[194:197], v[60:63]
	v_mfma_f32_16x16x32_bf16 v[56:59], v[140:143], v[194:197], v[56:59]
	v_mfma_f32_16x16x32_bf16 v[44:47], v[132:135], v[202:205], v[44:47]
	v_mfma_f32_16x16x32_bf16 v[40:43], v[140:143], v[202:205], v[40:43]
	v_mfma_f32_16x16x32_bf16 v[28:31], v[132:135], v[210:213], v[28:31]
	v_mfma_f32_16x16x32_bf16 v[24:27], v[140:143], v[210:213], v[24:27]
	v_mfma_f32_16x16x32_bf16 v[12:15], v[132:135], v[218:221], v[12:15]
	v_mfma_f32_16x16x32_bf16 v[8:11], v[140:143], v[218:221], v[8:11]
	v_mfma_f32_16x16x32_bf16 v[52:55], v[144:147], v[190:193], v[52:55]
	v_mfma_f32_16x16x32_bf16 v[48:51], v[172:175], v[190:193], v[48:51]
	v_mfma_f32_16x16x32_bf16 v[36:39], v[144:147], v[198:201], v[36:39]
	v_mfma_f32_16x16x32_bf16 v[32:35], v[172:175], v[198:201], v[32:35]
	v_mfma_f32_16x16x32_bf16 v[20:23], v[144:147], v[206:209], v[20:23]
	v_mfma_f32_16x16x32_bf16 v[16:19], v[172:175], v[206:209], v[16:19]
	v_mfma_f32_16x16x32_bf16 v[4:7], v[144:147], v[214:217], v[4:7]
	v_mfma_f32_16x16x32_bf16 v[0:3], v[172:175], v[214:217], v[0:3]
	v_mfma_f32_16x16x32_bf16 v[52:55], v[148:151], v[194:197], v[52:55]
	v_mfma_f32_16x16x32_bf16 v[48:51], v[176:179], v[194:197], v[48:51]
	v_mfma_f32_16x16x32_bf16 v[36:39], v[148:151], v[202:205], v[36:39]
	v_mfma_f32_16x16x32_bf16 v[32:35], v[176:179], v[202:205], v[32:35]
	v_mfma_f32_16x16x32_bf16 v[20:23], v[148:151], v[210:213], v[20:23]
	v_mfma_f32_16x16x32_bf16 v[16:19], v[176:179], v[210:213], v[16:19]
	v_mfma_f32_16x16x32_bf16 v[4:7], v[148:151], v[218:221], v[4:7]
	v_mfma_f32_16x16x32_bf16 v[0:3], v[176:179], v[218:221], v[0:3]
	s_barrier
	s_add_i32 s53, s53, 2
	s_add_u32 s54, s54, 0x100
	s_addc_u32 s55, s55, 0
	s_add_u32 s45, s45, 0x100
	s_addc_u32 s51, s51, 0
	s_cmp_gt_u32 s53, 13
	s_cbranch_scc0 .LBB0_1042
	s_setprio 0
	s_and_b64 vcc, exec, s[22:23]
	s_cbranch_vccz .LBB0_1045
	s_barrier

.LBB0_1149:
	s_ashr_i32 s41, s40, 31
	s_lshl_b64 s[8:9], s[40:41], 19
	s_add_u32 s42, s16, s8
	s_addc_u32 s43, s17, s9
	s_and_b64 s[8:9], s[6:7], exec
	s_cselect_b32 s8, s43, s49
	s_cselect_b32 s9, s42, s48
	s_ashr_i32 s39, s38, 31
	s_lshl_b64 s[44:45], s[38:39], 19
	s_add_u32 s44, s3, s44
	s_addc_u32 s45, s54, s45
	s_and_b64 s[52:53], s[6:7], exec
	s_cselect_b32 s39, s45, s51
	s_cselect_b32 s41, s44, s50
	s_add_u32 s48, s48, 0x40080
	s_addc_u32 s49, s49, 0
	s_add_u32 s47, s50, 0x100
	v_mov_b32_e32 v0, 0
	s_addc_u32 s69, s51, 0
	s_mov_b32 s70, -2
	v_mov_b32_e32 v1, v0
	v_mov_b32_e32 v2, v0
	v_mov_b32_e32 v3, v0
	v_mov_b32_e32 v4, v0
	v_mov_b32_e32 v5, v0
	v_mov_b32_e32 v6, v0
	v_mov_b32_e32 v7, v0
	v_mov_b32_e32 v16, v0
	v_mov_b32_e32 v17, v0
	v_mov_b32_e32 v18, v0
	v_mov_b32_e32 v19, v0
	v_mov_b32_e32 v20, v0
	v_mov_b32_e32 v21, v0
	v_mov_b32_e32 v22, v0
	v_mov_b32_e32 v23, v0
	v_mov_b32_e32 v32, v0
	v_mov_b32_e32 v33, v0
	v_mov_b32_e32 v34, v0
	v_mov_b32_e32 v35, v0
	v_mov_b32_e32 v36, v0
	v_mov_b32_e32 v37, v0
	v_mov_b32_e32 v38, v0
	v_mov_b32_e32 v39, v0
	v_mov_b32_e32 v48, v0
	v_mov_b32_e32 v49, v0
	v_mov_b32_e32 v50, v0
	v_mov_b32_e32 v51, v0
	v_mov_b32_e32 v52, v0
	v_mov_b32_e32 v53, v0
	v_mov_b32_e32 v54, v0
	v_mov_b32_e32 v55, v0
	v_mov_b32_e32 v8, v0
	v_mov_b32_e32 v9, v0
	v_mov_b32_e32 v10, v0
	v_mov_b32_e32 v11, v0
	v_mov_b32_e32 v12, v0
	v_mov_b32_e32 v13, v0
	v_mov_b32_e32 v14, v0
	v_mov_b32_e32 v15, v0
	v_mov_b32_e32 v24, v0
	v_mov_b32_e32 v25, v0
	v_mov_b32_e32 v26, v0
	v_mov_b32_e32 v27, v0
	v_mov_b32_e32 v28, v0
	v_mov_b32_e32 v29, v0
	v_mov_b32_e32 v30, v0
	v_mov_b32_e32 v31, v0
	v_mov_b32_e32 v40, v0
	v_mov_b32_e32 v41, v0
	v_mov_b32_e32 v42, v0
	v_mov_b32_e32 v43, v0
	v_mov_b32_e32 v44, v0
	v_mov_b32_e32 v45, v0
	v_mov_b32_e32 v46, v0
	v_mov_b32_e32 v47, v0
	v_mov_b32_e32 v56, v0
	v_mov_b32_e32 v57, v0
	v_mov_b32_e32 v58, v0
	v_mov_b32_e32 v59, v0
	v_mov_b32_e32 v60, v0
	v_mov_b32_e32 v61, v0
	v_mov_b32_e32 v62, v0
	v_mov_b32_e32 v63, v0
	v_mov_b32_e32 v64, v0
	v_mov_b32_e32 v65, v0
	v_mov_b32_e32 v66, v0
	v_mov_b32_e32 v67, v0
	v_mov_b32_e32 v68, v0
	v_mov_b32_e32 v69, v0
	v_mov_b32_e32 v70, v0
	v_mov_b32_e32 v71, v0
	v_mov_b32_e32 v80, v0
	v_mov_b32_e32 v81, v0
	v_mov_b32_e32 v82, v0
	v_mov_b32_e32 v83, v0
	v_mov_b32_e32 v84, v0
	v_mov_b32_e32 v85, v0
	v_mov_b32_e32 v86, v0
	v_mov_b32_e32 v87, v0
	v_mov_b32_e32 v96, v0
	v_mov_b32_e32 v97, v0
	v_mov_b32_e32 v98, v0
	v_mov_b32_e32 v99, v0
	v_mov_b32_e32 v100, v0
	v_mov_b32_e32 v101, v0
	v_mov_b32_e32 v102, v0
	v_mov_b32_e32 v103, v0
	v_mov_b32_e32 v112, v0
	v_mov_b32_e32 v113, v0
	v_mov_b32_e32 v114, v0
	v_mov_b32_e32 v115, v0
	v_mov_b32_e32 v116, v0
	v_mov_b32_e32 v117, v0
	v_mov_b32_e32 v118, v0
	v_mov_b32_e32 v119, v0
	v_mov_b32_e32 v72, v0
	v_mov_b32_e32 v73, v0
	v_mov_b32_e32 v74, v0
	v_mov_b32_e32 v75, v0
	v_mov_b32_e32 v76, v0
	v_mov_b32_e32 v77, v0
	v_mov_b32_e32 v78, v0
	v_mov_b32_e32 v79, v0
	v_mov_b32_e32 v88, v0
	v_mov_b32_e32 v89, v0
	v_mov_b32_e32 v90, v0
	v_mov_b32_e32 v91, v0
	v_mov_b32_e32 v92, v0
	v_mov_b32_e32 v93, v0
	v_mov_b32_e32 v94, v0
	v_mov_b32_e32 v95, v0
	v_mov_b32_e32 v104, v0
	v_mov_b32_e32 v105, v0
	v_mov_b32_e32 v106, v0
	v_mov_b32_e32 v107, v0
	v_mov_b32_e32 v108, v0
	v_mov_b32_e32 v109, v0
	v_mov_b32_e32 v110, v0
	v_mov_b32_e32 v111, v0
	v_mov_b32_e32 v120, v0
	v_mov_b32_e32 v121, v0
	v_mov_b32_e32 v122, v0
	v_mov_b32_e32 v123, v0
	v_mov_b32_e32 v124, v0
	v_mov_b32_e32 v125, v0
	v_mov_b32_e32 v126, v0
	v_mov_b32_e32 v127, v0
	s_and_b64 vcc, exec, s[34:35]
	s_cbranch_vccnz .Lmy_pr_7
	s_setprio 1
.Lmy_pr_7:
.LBB0_1150:
	ds_read_b128 v[128:131], v167
	ds_read_b128 v[132:135], v167 offset:1024
	ds_read_b128 v[136:139], v167 offset:2048
	ds_read_b128 v[140:143], v167 offset:3072
	ds_read_b128 v[156:159], v168
	ds_read_b128 v[160:163], v168 offset:1024
	ds_read_b128 v[170:173], v168 offset:2048
	ds_read_b128 v[174:177], v168 offset:3072
	s_add_u32 s50, s48, 0xfffc0080
	s_addc_u32 s51, s49, -1
	s_cmp_eq_u32 s70, 12
	s_cselect_b32 s53, s8, s51
	s_cselect_b32 s52, s9, s50
	s_cselect_b32 s51, s39, s69
	s_cselect_b32 s50, s41, s47
	v_lshl_add_u64 v[210:211], s[48:49], 0, v[148:149]
	s_add_i32 m0, s56, 0xc000
	ds_read_b128 v[178:181], v169
	ds_read_b128 v[182:185], v169 offset:1024
	ds_read_b128 v[186:189], v169 offset:2048
	ds_read_b128 v[190:193], v169 offset:3072
	ds_read_b128 v[194:197], v169 offset:4096
	ds_read_b128 v[198:201], v169 offset:5120
	ds_read_b128 v[202:205], v169 offset:6144
	ds_read_b128 v[206:209], v169 offset:7168
	global_load_lds_dwordx4 v[210:211], off
	v_lshl_add_u64 v[210:211], s[48:49], 0, v[150:151]
	s_add_i32 m0, s56, 0xe000
	s_nop 0
	global_load_lds_dwordx4 v[210:211], off
	s_waitcnt vmcnt(8)
	s_waitcnt lgkmcnt(0)
	s_barrier
	s_waitcnt lgkmcnt(0)
	v_mfma_f32_16x16x32_bf16 v[124:127], v[128:131], v[178:181], v[124:127]
	v_mfma_f32_16x16x32_bf16 v[120:123], v[136:139], v[178:181], v[120:123]
	v_mfma_f32_16x16x32_bf16 v[108:111], v[128:131], v[186:189], v[108:111]
	v_mfma_f32_16x16x32_bf16 v[104:107], v[136:139], v[186:189], v[104:107]
	v_mfma_f32_16x16x32_bf16 v[92:95], v[128:131], v[194:197], v[92:95]
	v_mfma_f32_16x16x32_bf16 v[88:91], v[136:139], v[194:197], v[88:91]
	v_mfma_f32_16x16x32_bf16 v[76:79], v[128:131], v[202:205], v[76:79]
	v_mfma_f32_16x16x32_bf16 v[72:75], v[136:139], v[202:205], v[72:75]
	v_mfma_f32_16x16x32_bf16 v[124:127], v[132:135], v[182:185], v[124:127]
	v_mfma_f32_16x16x32_bf16 v[120:123], v[140:143], v[182:185], v[120:123]
	v_mfma_f32_16x16x32_bf16 v[108:111], v[132:135], v[190:193], v[108:111]
	v_mfma_f32_16x16x32_bf16 v[104:107], v[140:143], v[190:193], v[104:107]
	v_mfma_f32_16x16x32_bf16 v[92:95], v[132:135], v[198:201], v[92:95]
	v_mfma_f32_16x16x32_bf16 v[88:91], v[140:143], v[198:201], v[88:91]
	v_mfma_f32_16x16x32_bf16 v[76:79], v[132:135], v[206:209], v[76:79]
	v_mfma_f32_16x16x32_bf16 v[72:75], v[140:143], v[206:209], v[72:75]
	v_mfma_f32_16x16x32_bf16 v[116:119], v[156:159], v[178:181], v[116:119]
	v_mfma_f32_16x16x32_bf16 v[112:115], v[170:173], v[178:181], v[112:115]
	v_mfma_f32_16x16x32_bf16 v[100:103], v[156:159], v[186:189], v[100:103]
	v_mfma_f32_16x16x32_bf16 v[96:99], v[170:173], v[186:189], v[96:99]
	v_mfma_f32_16x16x32_bf16 v[84:87], v[156:159], v[194:197], v[84:87]
	v_mfma_f32_16x16x32_bf16 v[80:83], v[170:173], v[194:197], v[80:83]
	v_mfma_f32_16x16x32_bf16 v[68:71], v[156:159], v[202:205], v[68:71]
	v_mfma_f32_16x16x32_bf16 v[64:67], v[170:173], v[202:205], v[64:67]
	v_mfma_f32_16x16x32_bf16 v[116:119], v[160:163], v[182:185], v[116:119]
	v_mfma_f32_16x16x32_bf16 v[112:115], v[174:177], v[182:185], v[112:115]
	v_mfma_f32_16x16x32_bf16 v[100:103], v[160:163], v[190:193], v[100:103]
	v_mfma_f32_16x16x32_bf16 v[96:99], v[174:177], v[190:193], v[96:99]
	v_mfma_f32_16x16x32_bf16 v[84:87], v[160:163], v[198:201], v[84:87]
	v_mfma_f32_16x16x32_bf16 v[80:83], v[174:177], v[198:201], v[80:83]
	v_mfma_f32_16x16x32_bf16 v[68:71], v[160:163], v[206:209], v[68:71]
	v_mfma_f32_16x16x32_bf16 v[64:67], v[174:177], v[206:209], v[64:67]
	s_barrier
	s_add_i32 s71, s66, s55
	v_lshl_add_u64 v[210:211], s[50:51], 0, v[144:145]
	s_mov_b32 m0, s71
	ds_read_b128 v[178:181], v169 offset:16384
	ds_read_b128 v[182:185], v169 offset:17408
	ds_read_b128 v[186:189], v169 offset:18432
	ds_read_b128 v[190:193], v169 offset:19456
	ds_read_b128 v[194:197], v169 offset:20480
	ds_read_b128 v[198:201], v169 offset:21504
	ds_read_b128 v[202:205], v169 offset:22528
	ds_read_b128 v[206:209], v169 offset:23552
	global_load_lds_dwordx4 v[210:211], off
	s_add_i32 m0, s71, 0x2000
	s_add_u32 s72, s50, 0x40000
	v_lshl_add_u64 v[212:213], s[50:51], 0, v[146:147]
	s_addc_u32 s73, s51, 0
	s_add_i32 s71, s67, s55
	global_load_lds_dwordx4 v[212:213], off
	v_lshl_add_u64 v[214:215], s[72:73], 0, v[144:145]
	s_mov_b32 m0, s71
	v_lshl_add_u64 v[216:217], s[52:53], 0, v[146:147]
	global_load_lds_dwordx4 v[214:215], off
	v_lshl_add_u64 v[214:215], s[72:73], 0, v[146:147]
	s_add_i32 m0, s71, 0x2000
	s_nop 0
	global_load_lds_dwordx4 v[214:215], off
	v_lshl_add_u64 v[214:215], s[52:53], 0, v[144:145]
	s_mov_b32 m0, s56
	s_nop 0
	global_load_lds_dwordx4 v[214:215], off
	s_mov_b32 m0, s57
	s_nop 0
	global_load_lds_dwordx4 v[216:217], off
	s_waitcnt vmcnt(8)
	s_waitcnt lgkmcnt(0)
	s_barrier
	s_waitcnt lgkmcnt(0)
	v_mfma_f32_16x16x32_bf16 v[60:63], v[128:131], v[178:181], v[60:63]
	v_mfma_f32_16x16x32_bf16 v[56:59], v[136:139], v[178:181], v[56:59]
	v_mfma_f32_16x16x32_bf16 v[44:47], v[128:131], v[186:189], v[44:47]
	v_mfma_f32_16x16x32_bf16 v[40:43], v[136:139], v[186:189], v[40:43]
	v_mfma_f32_16x16x32_bf16 v[28:31], v[128:131], v[194:197], v[28:31]
	v_mfma_f32_16x16x32_bf16 v[24:27], v[136:139], v[194:197], v[24:27]
	v_mfma_f32_16x16x32_bf16 v[12:15], v[128:131], v[202:205], v[12:15]
	v_mfma_f32_16x16x32_bf16 v[8:11], v[136:139], v[202:205], v[8:11]
	v_mfma_f32_16x16x32_bf16 v[60:63], v[132:135], v[182:185], v[60:63]
	v_mfma_f32_16x16x32_bf16 v[56:59], v[140:143], v[182:185], v[56:59]
	v_mfma_f32_16x16x32_bf16 v[44:47], v[132:135], v[190:193], v[44:47]
	v_mfma_f32_16x16x32_bf16 v[40:43], v[140:143], v[190:193], v[40:43]
	v_mfma_f32_16x16x32_bf16 v[28:31], v[132:135], v[198:201], v[28:31]
	v_mfma_f32_16x16x32_bf16 v[24:27], v[140:143], v[198:201], v[24:27]
	v_mfma_f32_16x16x32_bf16 v[12:15], v[132:135], v[206:209], v[12:15]
	v_mfma_f32_16x16x32_bf16 v[8:11], v[140:143], v[206:209], v[8:11]
	v_mfma_f32_16x16x32_bf16 v[52:55], v[156:159], v[178:181], v[52:55]
	v_mfma_f32_16x16x32_bf16 v[48:51], v[170:173], v[178:181], v[48:51]
	v_mfma_f32_16x16x32_bf16 v[36:39], v[156:159], v[186:189], v[36:39]
	v_mfma_f32_16x16x32_bf16 v[32:35], v[170:173], v[186:189], v[32:35]
	v_mfma_f32_16x16x32_bf16 v[20:23], v[156:159], v[194:197], v[20:23]
	v_mfma_f32_16x16x32_bf16 v[16:19], v[170:173], v[194:197], v[16:19]
	v_mfma_f32_16x16x32_bf16 v[4:7], v[156:159], v[202:205], v[4:7]
	v_mfma_f32_16x16x32_bf16 v[0:3], v[170:173], v[202:205], v[0:3]
	v_mfma_f32_16x16x32_bf16 v[52:55], v[160:163], v[182:185], v[52:55]
	v_mfma_f32_16x16x32_bf16 v[48:51], v[174:177], v[182:185], v[48:51]
	v_mfma_f32_16x16x32_bf16 v[36:39], v[160:163], v[190:193], v[36:39]
	v_mfma_f32_16x16x32_bf16 v[32:35], v[174:177], v[190:193], v[32:35]
	v_mfma_f32_16x16x32_bf16 v[20:23], v[160:163], v[198:201], v[20:23]
	v_mfma_f32_16x16x32_bf16 v[16:19], v[174:177], v[198:201], v[16:19]
	v_mfma_f32_16x16x32_bf16 v[4:7], v[160:163], v[206:209], v[4:7]
	v_mfma_f32_16x16x32_bf16 v[0:3], v[174:177], v[206:209], v[0:3]
	s_barrier
	s_add_i32 s71, 0, 0x18000
	s_add_i32 s72, 0, 0x1c000
	v_add_u32_e32 v140, s71, v165
	v_add_u32_e32 v174, s72, v165
	ds_read_b128 v[128:131], v140
	ds_read_b128 v[132:135], v140 offset:1024
	ds_read_b128 v[136:139], v140 offset:2048
	ds_read_b128 v[140:143], v140 offset:3072
	ds_read_b128 v[156:159], v174
	ds_read_b128 v[160:163], v174 offset:1024
	ds_read_b128 v[170:173], v174 offset:2048
	ds_read_b128 v[174:177], v174 offset:3072
	s_add_u32 s52, s52, 0x40000
	s_addc_u32 s53, s53, 0
	s_mov_b32 m0, s58
	v_lshl_add_u64 v[218:219], s[52:53], 0, v[144:145]
	ds_read_b128 v[178:181], v169 offset:32768
	ds_read_b128 v[182:185], v169 offset:33792
	ds_read_b128 v[186:189], v169 offset:34816
	ds_read_b128 v[190:193], v169 offset:35840
	ds_read_b128 v[194:197], v169 offset:36864
	ds_read_b128 v[198:201], v169 offset:37888
	ds_read_b128 v[202:205], v169 offset:38912
	ds_read_b128 v[206:209], v169 offset:39936
	global_load_lds_dwordx4 v[218:219], off
	v_lshl_add_u64 v[218:219], s[52:53], 0, v[146:147]
	s_mov_b32 m0, s59
	s_nop 0
	global_load_lds_dwordx4 v[218:219], off
	s_waitcnt vmcnt(8)
	s_waitcnt lgkmcnt(0)
	s_barrier
	s_waitcnt lgkmcnt(0)
	v_mfma_f32_16x16x32_bf16 v[124:127], v[128:131], v[178:181], v[124:127]
	v_mfma_f32_16x16x32_bf16 v[120:123], v[136:139], v[178:181], v[120:123]
	v_mfma_f32_16x16x32_bf16 v[108:111], v[128:131], v[186:189], v[108:111]
	v_mfma_f32_16x16x32_bf16 v[104:107], v[136:139], v[186:189], v[104:107]
	v_mfma_f32_16x16x32_bf16 v[92:95], v[128:131], v[194:197], v[92:95]
	v_mfma_f32_16x16x32_bf16 v[88:91], v[136:139], v[194:197], v[88:91]
	v_mfma_f32_16x16x32_bf16 v[76:79], v[128:131], v[202:205], v[76:79]
	v_mfma_f32_16x16x32_bf16 v[72:75], v[136:139], v[202:205], v[72:75]
	v_mfma_f32_16x16x32_bf16 v[124:127], v[132:135], v[182:185], v[124:127]
	v_mfma_f32_16x16x32_bf16 v[120:123], v[140:143], v[182:185], v[120:123]
	v_mfma_f32_16x16x32_bf16 v[108:111], v[132:135], v[190:193], v[108:111]
	v_mfma_f32_16x16x32_bf16 v[104:107], v[140:143], v[190:193], v[104:107]
	v_mfma_f32_16x16x32_bf16 v[92:95], v[132:135], v[198:201], v[92:95]
	v_mfma_f32_16x16x32_bf16 v[88:91], v[140:143], v[198:201], v[88:91]
	v_mfma_f32_16x16x32_bf16 v[76:79], v[132:135], v[206:209], v[76:79]
	v_mfma_f32_16x16x32_bf16 v[72:75], v[140:143], v[206:209], v[72:75]
	v_mfma_f32_16x16x32_bf16 v[116:119], v[156:159], v[178:181], v[116:119]
	v_mfma_f32_16x16x32_bf16 v[112:115], v[170:173], v[178:181], v[112:115]
	v_mfma_f32_16x16x32_bf16 v[100:103], v[156:159], v[186:189], v[100:103]
	v_mfma_f32_16x16x32_bf16 v[96:99], v[170:173], v[186:189], v[96:99]
	v_mfma_f32_16x16x32_bf16 v[84:87], v[156:159], v[194:197], v[84:87]
	v_mfma_f32_16x16x32_bf16 v[80:83], v[170:173], v[194:197], v[80:83]
	v_mfma_f32_16x16x32_bf16 v[68:71], v[156:159], v[202:205], v[68:71]
	v_mfma_f32_16x16x32_bf16 v[64:67], v[170:173], v[202:205], v[64:67]
	v_mfma_f32_16x16x32_bf16 v[116:119], v[160:163], v[182:185], v[116:119]
	v_mfma_f32_16x16x32_bf16 v[112:115], v[174:177], v[182:185], v[112:115]
	v_mfma_f32_16x16x32_bf16 v[100:103], v[160:163], v[190:193], v[100:103]
	v_mfma_f32_16x16x32_bf16 v[96:99], v[174:177], v[190:193], v[96:99]
	v_mfma_f32_16x16x32_bf16 v[84:87], v[160:163], v[198:201], v[84:87]
	v_mfma_f32_16x16x32_bf16 v[80:83], v[174:177], v[198:201], v[80:83]
	v_mfma_f32_16x16x32_bf16 v[68:71], v[160:163], v[206:209], v[68:71]
	v_mfma_f32_16x16x32_bf16 v[64:67], v[174:177], v[206:209], v[64:67]
	s_barrier
	s_add_i32 s52, s71, s55
	v_lshl_add_u64 v[210:211], v[210:211], 0, s[22:23]
	s_mov_b32 m0, s52
	ds_read_b128 v[178:181], v169 offset:49152
	ds_read_b128 v[182:185], v169 offset:50176
	ds_read_b128 v[186:189], v169 offset:51200
	ds_read_b128 v[190:193], v169 offset:52224
	ds_read_b128 v[194:197], v169 offset:53248
	ds_read_b128 v[198:201], v169 offset:54272
	ds_read_b128 v[202:205], v169 offset:55296
	ds_read_b128 v[206:209], v169 offset:56320
	global_load_lds_dwordx4 v[210:211], off
	s_add_i32 m0, s52, 0x2000
	s_add_u32 s50, s50, 0x40080
	v_lshl_add_u64 v[210:211], v[212:213], 0, s[22:23]
	s_addc_u32 s51, s51, 0
	s_add_i32 s52, s72, s55
	global_load_lds_dwordx4 v[210:211], off
	v_lshl_add_u64 v[210:211], s[50:51], 0, v[144:145]
	s_mov_b32 m0, s52
	s_nop 0
	global_load_lds_dwordx4 v[210:211], off
	v_lshl_add_u64 v[210:211], s[50:51], 0, v[146:147]
	s_add_i32 m0, s52, 0x2000
	s_nop 0
	global_load_lds_dwordx4 v[210:211], off
	v_lshl_add_u64 v[210:211], v[214:215], 0, s[22:23]
	s_mov_b32 m0, s61
	s_nop 0
	global_load_lds_dwordx4 v[210:211], off
	v_lshl_add_u64 v[210:211], v[216:217], 0, s[22:23]
	s_mov_b32 m0, s62
	s_nop 0
	global_load_lds_dwordx4 v[210:211], off
	s_waitcnt vmcnt(8)
	s_waitcnt lgkmcnt(0)
	s_barrier
	s_waitcnt lgkmcnt(0)
	v_mfma_f32_16x16x32_bf16 v[60:63], v[128:131], v[178:181], v[60:63]
	v_mfma_f32_16x16x32_bf16 v[56:59], v[136:139], v[178:181], v[56:59]
	v_mfma_f32_16x16x32_bf16 v[44:47], v[128:131], v[186:189], v[44:47]
	v_mfma_f32_16x16x32_bf16 v[40:43], v[136:139], v[186:189], v[40:43]
	v_mfma_f32_16x16x32_bf16 v[28:31], v[128:131], v[194:197], v[28:31]
	v_mfma_f32_16x16x32_bf16 v[24:27], v[136:139], v[194:197], v[24:27]
	v_mfma_f32_16x16x32_bf16 v[12:15], v[128:131], v[202:205], v[12:15]
	v_mfma_f32_16x16x32_bf16 v[8:11], v[136:139], v[202:205], v[8:11]
	v_mfma_f32_16x16x32_bf16 v[60:63], v[132:135], v[182:185], v[60:63]
	v_mfma_f32_16x16x32_bf16 v[56:59], v[140:143], v[182:185], v[56:59]
	v_mfma_f32_16x16x32_bf16 v[44:47], v[132:135], v[190:193], v[44:47]
	v_mfma_f32_16x16x32_bf16 v[40:43], v[140:143], v[190:193], v[40:43]
	v_mfma_f32_16x16x32_bf16 v[28:31], v[132:135], v[198:201], v[28:31]
	v_mfma_f32_16x16x32_bf16 v[24:27], v[140:143], v[198:201], v[24:27]
	v_mfma_f32_16x16x32_bf16 v[12:15], v[132:135], v[206:209], v[12:15]
	v_mfma_f32_16x16x32_bf16 v[8:11], v[140:143], v[206:209], v[8:11]
	v_mfma_f32_16x16x32_bf16 v[52:55], v[156:159], v[178:181], v[52:55]
	v_mfma_f32_16x16x32_bf16 v[48:51], v[170:173], v[178:181], v[48:51]
	v_mfma_f32_16x16x32_bf16 v[36:39], v[156:159], v[186:189], v[36:39]
	v_mfma_f32_16x16x32_bf16 v[32:35], v[170:173], v[186:189], v[32:35]
	v_mfma_f32_16x16x32_bf16 v[20:23], v[156:159], v[194:197], v[20:23]
	v_mfma_f32_16x16x32_bf16 v[16:19], v[170:173], v[194:197], v[16:19]
	v_mfma_f32_16x16x32_bf16 v[4:7], v[156:159], v[202:205], v[4:7]
	v_mfma_f32_16x16x32_bf16 v[0:3], v[170:173], v[202:205], v[0:3]
	v_mfma_f32_16x16x32_bf16 v[52:55], v[160:163], v[182:185], v[52:55]
	v_mfma_f32_16x16x32_bf16 v[48:51], v[174:177], v[182:185], v[48:51]
	v_mfma_f32_16x16x32_bf16 v[36:39], v[160:163], v[190:193], v[36:39]
	v_mfma_f32_16x16x32_bf16 v[32:35], v[174:177], v[190:193], v[32:35]
	v_mfma_f32_16x16x32_bf16 v[20:23], v[160:163], v[198:201], v[20:23]
	v_mfma_f32_16x16x32_bf16 v[16:19], v[174:177], v[198:201], v[16:19]
	v_mfma_f32_16x16x32_bf16 v[4:7], v[160:163], v[206:209], v[4:7]
	v_mfma_f32_16x16x32_bf16 v[0:3], v[174:177], v[206:209], v[0:3]
	s_barrier
	s_add_i32 s70, s70, 2
	s_add_u32 s48, s48, 0x100
	s_addc_u32 s49, s49, 0
	s_add_u32 s47, s47, 0x100
	s_addc_u32 s69, s69, 0
	s_cmp_gt_u32 s70, 13
	s_cbranch_scc0 .LBB0_1150
	s_setprio 0
	s_and_b64 vcc, exec, s[34:35]
	s_cbranch_vccz .LBB0_1153
	s_barrier

.LBB0_1233:
	s_ashr_i32 s23, s22, 31
	s_lshl_b64 s[34:35], s[22:23], 19
	s_add_u32 s34, s10, s34
	s_addc_u32 s35, s11, s35
	s_and_b64 s[36:37], s[6:7], exec
	s_cselect_b32 s9, s35, s41
	s_cselect_b32 s23, s34, s40
	s_ashr_i32 s21, s20, 31
	s_lshl_b64 s[36:37], s[20:21], 19
	s_add_u32 s36, s3, s36
	s_addc_u32 s37, s46, s37
	s_and_b64 s[44:45], s[6:7], exec
	s_cselect_b32 s21, s37, s43
	s_cselect_b32 s62, s36, s42
	s_add_u32 s40, s40, 0x40080
	s_addc_u32 s41, s41, 0
	s_add_u32 s63, s42, 0x100
	v_mov_b32_e32 v0, 0
	s_addc_u32 s64, s43, 0
	s_mov_b32 s65, -2
	v_mov_b32_e32 v1, v0
	v_mov_b32_e32 v2, v0
	v_mov_b32_e32 v3, v0
	v_mov_b32_e32 v4, v0
	v_mov_b32_e32 v5, v0
	v_mov_b32_e32 v6, v0
	v_mov_b32_e32 v7, v0
	v_mov_b32_e32 v16, v0
	v_mov_b32_e32 v17, v0
	v_mov_b32_e32 v18, v0
	v_mov_b32_e32 v19, v0
	v_mov_b32_e32 v20, v0
	v_mov_b32_e32 v21, v0
	v_mov_b32_e32 v22, v0
	v_mov_b32_e32 v23, v0
	v_mov_b32_e32 v32, v0
	v_mov_b32_e32 v33, v0
	v_mov_b32_e32 v34, v0
	v_mov_b32_e32 v35, v0
	v_mov_b32_e32 v36, v0
	v_mov_b32_e32 v37, v0
	v_mov_b32_e32 v38, v0
	v_mov_b32_e32 v39, v0
	v_mov_b32_e32 v48, v0
	v_mov_b32_e32 v49, v0
	v_mov_b32_e32 v50, v0
	v_mov_b32_e32 v51, v0
	v_mov_b32_e32 v52, v0
	v_mov_b32_e32 v53, v0
	v_mov_b32_e32 v54, v0
	v_mov_b32_e32 v55, v0
	v_mov_b32_e32 v8, v0
	v_mov_b32_e32 v9, v0
	v_mov_b32_e32 v10, v0
	v_mov_b32_e32 v11, v0
	v_mov_b32_e32 v12, v0
	v_mov_b32_e32 v13, v0
	v_mov_b32_e32 v14, v0
	v_mov_b32_e32 v15, v0
	v_mov_b32_e32 v24, v0
	v_mov_b32_e32 v25, v0
	v_mov_b32_e32 v26, v0
	v_mov_b32_e32 v27, v0
	v_mov_b32_e32 v28, v0
	v_mov_b32_e32 v29, v0
	v_mov_b32_e32 v30, v0
	v_mov_b32_e32 v31, v0
	v_mov_b32_e32 v40, v0
	v_mov_b32_e32 v41, v0
	v_mov_b32_e32 v42, v0
	v_mov_b32_e32 v43, v0
	v_mov_b32_e32 v44, v0
	v_mov_b32_e32 v45, v0
	v_mov_b32_e32 v46, v0
	v_mov_b32_e32 v47, v0
	v_mov_b32_e32 v56, v0
	v_mov_b32_e32 v57, v0
	v_mov_b32_e32 v58, v0
	v_mov_b32_e32 v59, v0
	v_mov_b32_e32 v60, v0
	v_mov_b32_e32 v61, v0
	v_mov_b32_e32 v62, v0
	v_mov_b32_e32 v63, v0
	v_mov_b32_e32 v64, v0
	v_mov_b32_e32 v65, v0
	v_mov_b32_e32 v66, v0
	v_mov_b32_e32 v67, v0
	v_mov_b32_e32 v68, v0
	v_mov_b32_e32 v69, v0
	v_mov_b32_e32 v70, v0
	v_mov_b32_e32 v71, v0
	v_mov_b32_e32 v80, v0
	v_mov_b32_e32 v81, v0
	v_mov_b32_e32 v82, v0
	v_mov_b32_e32 v83, v0
	v_mov_b32_e32 v84, v0
	v_mov_b32_e32 v85, v0
	v_mov_b32_e32 v86, v0
	v_mov_b32_e32 v87, v0
	v_mov_b32_e32 v96, v0
	v_mov_b32_e32 v97, v0
	v_mov_b32_e32 v98, v0
	v_mov_b32_e32 v99, v0
	v_mov_b32_e32 v100, v0
	v_mov_b32_e32 v101, v0
	v_mov_b32_e32 v102, v0
	v_mov_b32_e32 v103, v0
	v_mov_b32_e32 v112, v0
	v_mov_b32_e32 v113, v0
	v_mov_b32_e32 v114, v0
	v_mov_b32_e32 v115, v0
	v_mov_b32_e32 v116, v0
	v_mov_b32_e32 v117, v0
	v_mov_b32_e32 v118, v0
	v_mov_b32_e32 v119, v0
	v_mov_b32_e32 v72, v0
	v_mov_b32_e32 v73, v0
	v_mov_b32_e32 v74, v0
	v_mov_b32_e32 v75, v0
	v_mov_b32_e32 v76, v0
	v_mov_b32_e32 v77, v0
	v_mov_b32_e32 v78, v0
	v_mov_b32_e32 v79, v0
	v_mov_b32_e32 v88, v0
	v_mov_b32_e32 v89, v0
	v_mov_b32_e32 v90, v0
	v_mov_b32_e32 v91, v0
	v_mov_b32_e32 v92, v0
	v_mov_b32_e32 v93, v0
	v_mov_b32_e32 v94, v0
	v_mov_b32_e32 v95, v0
	v_mov_b32_e32 v104, v0
	v_mov_b32_e32 v105, v0
	v_mov_b32_e32 v106, v0
	v_mov_b32_e32 v107, v0
	v_mov_b32_e32 v108, v0
	v_mov_b32_e32 v109, v0
	v_mov_b32_e32 v110, v0
	v_mov_b32_e32 v111, v0
	v_mov_b32_e32 v120, v0
	v_mov_b32_e32 v121, v0
	v_mov_b32_e32 v122, v0
	v_mov_b32_e32 v123, v0
	v_mov_b32_e32 v124, v0
	v_mov_b32_e32 v125, v0
	v_mov_b32_e32 v126, v0
	v_mov_b32_e32 v127, v0
	s_and_b64 vcc, exec, s[18:19]
	s_cbranch_vccnz .Lmy_pr_8
	s_setprio 1
.Lmy_pr_8:
.LBB0_1234:
	ds_read_b128 v[144:147], v153
	ds_read_b128 v[158:161], v153 offset:1024
	ds_read_b128 v[162:165], v153 offset:2048
	ds_read_b128 v[166:169], v153 offset:3072
	ds_read_b128 v[170:173], v154
	ds_read_b128 v[174:177], v154 offset:1024
	ds_read_b128 v[178:181], v154 offset:2048
	ds_read_b128 v[182:185], v154 offset:3072
	s_add_u32 s42, s40, 0xfffc0080
	s_addc_u32 s43, s41, -1
	s_cmp_eq_u32 s65, 12
	s_cselect_b32 s45, s9, s43
	s_cselect_b32 s44, s23, s42
	s_cselect_b32 s43, s21, s64
	s_cselect_b32 s42, s62, s63
	v_lshl_add_u64 v[148:149], s[40:41], 0, v[136:137]
	s_add_i32 m0, s39, 0xc000
	ds_read_b128 v[186:189], v155
	ds_read_b128 v[190:193], v155 offset:1024
	ds_read_b128 v[194:197], v155 offset:2048
	ds_read_b128 v[198:201], v155 offset:3072
	ds_read_b128 v[202:205], v155 offset:4096
	ds_read_b128 v[206:209], v155 offset:5120
	ds_read_b128 v[210:213], v155 offset:6144
	ds_read_b128 v[214:217], v155 offset:7168
	global_load_lds_dwordx4 v[148:149], off
	v_lshl_add_u64 v[148:149], s[40:41], 0, v[138:139]
	s_add_i32 m0, s39, 0xe000
	s_nop 0
	global_load_lds_dwordx4 v[148:149], off
	s_waitcnt vmcnt(8)
	s_waitcnt lgkmcnt(0)
	s_barrier
	s_waitcnt lgkmcnt(0)
	v_mfma_f32_16x16x32_bf16 v[124:127], v[144:147], v[186:189], v[124:127]
	v_mfma_f32_16x16x32_bf16 v[120:123], v[162:165], v[186:189], v[120:123]
	v_mfma_f32_16x16x32_bf16 v[108:111], v[144:147], v[194:197], v[108:111]
	v_mfma_f32_16x16x32_bf16 v[104:107], v[162:165], v[194:197], v[104:107]
	v_mfma_f32_16x16x32_bf16 v[92:95], v[144:147], v[202:205], v[92:95]
	v_mfma_f32_16x16x32_bf16 v[88:91], v[162:165], v[202:205], v[88:91]
	v_mfma_f32_16x16x32_bf16 v[76:79], v[144:147], v[210:213], v[76:79]
	v_mfma_f32_16x16x32_bf16 v[72:75], v[162:165], v[210:213], v[72:75]
	v_mfma_f32_16x16x32_bf16 v[124:127], v[158:161], v[190:193], v[124:127]
	v_mfma_f32_16x16x32_bf16 v[120:123], v[166:169], v[190:193], v[120:123]
	v_mfma_f32_16x16x32_bf16 v[108:111], v[158:161], v[198:201], v[108:111]
	v_mfma_f32_16x16x32_bf16 v[104:107], v[166:169], v[198:201], v[104:107]
	v_mfma_f32_16x16x32_bf16 v[92:95], v[158:161], v[206:209], v[92:95]
	v_mfma_f32_16x16x32_bf16 v[88:91], v[166:169], v[206:209], v[88:91]
	v_mfma_f32_16x16x32_bf16 v[76:79], v[158:161], v[214:217], v[76:79]
	v_mfma_f32_16x16x32_bf16 v[72:75], v[166:169], v[214:217], v[72:75]
	v_mfma_f32_16x16x32_bf16 v[116:119], v[170:173], v[186:189], v[116:119]
	v_mfma_f32_16x16x32_bf16 v[112:115], v[178:181], v[186:189], v[112:115]
	v_mfma_f32_16x16x32_bf16 v[100:103], v[170:173], v[194:197], v[100:103]
	v_mfma_f32_16x16x32_bf16 v[96:99], v[178:181], v[194:197], v[96:99]
	v_mfma_f32_16x16x32_bf16 v[84:87], v[170:173], v[202:205], v[84:87]
	v_mfma_f32_16x16x32_bf16 v[80:83], v[178:181], v[202:205], v[80:83]
	v_mfma_f32_16x16x32_bf16 v[68:71], v[170:173], v[210:213], v[68:71]
	v_mfma_f32_16x16x32_bf16 v[64:67], v[178:181], v[210:213], v[64:67]
	v_mfma_f32_16x16x32_bf16 v[116:119], v[174:177], v[190:193], v[116:119]
	v_mfma_f32_16x16x32_bf16 v[112:115], v[182:185], v[190:193], v[112:115]
	v_mfma_f32_16x16x32_bf16 v[100:103], v[174:177], v[198:201], v[100:103]
	v_mfma_f32_16x16x32_bf16 v[96:99], v[182:185], v[198:201], v[96:99]
	v_mfma_f32_16x16x32_bf16 v[84:87], v[174:177], v[206:209], v[84:87]
	v_mfma_f32_16x16x32_bf16 v[80:83], v[182:185], v[206:209], v[80:83]
	v_mfma_f32_16x16x32_bf16 v[68:71], v[174:177], v[214:217], v[68:71]
	v_mfma_f32_16x16x32_bf16 v[64:67], v[182:185], v[214:217], v[64:67]
	s_barrier
	s_add_i32 s66, s58, s47
	v_lshl_add_u64 v[148:149], s[42:43], 0, v[132:133]
	s_mov_b32 m0, s66
	ds_read_b128 v[186:189], v155 offset:16384
	ds_read_b128 v[190:193], v155 offset:17408
	ds_read_b128 v[194:197], v155 offset:18432
	ds_read_b128 v[198:201], v155 offset:19456
	ds_read_b128 v[202:205], v155 offset:20480
	ds_read_b128 v[206:209], v155 offset:21504
	ds_read_b128 v[210:213], v155 offset:22528
	ds_read_b128 v[214:217], v155 offset:23552
	global_load_lds_dwordx4 v[148:149], off
	s_add_i32 m0, s66, 0x2000
	s_add_u32 s66, s42, 0x40000
	v_lshl_add_u64 v[218:219], s[42:43], 0, v[128:129]
	s_addc_u32 s67, s43, 0
	s_add_i32 s68, s59, s47
	global_load_lds_dwordx4 v[218:219], off
	v_lshl_add_u64 v[220:221], s[66:67], 0, v[132:133]
	s_mov_b32 m0, s68
	v_lshl_add_u64 v[222:223], s[44:45], 0, v[130:131]
	global_load_lds_dwordx4 v[220:221], off
	v_lshl_add_u64 v[220:221], s[66:67], 0, v[128:129]
	s_add_i32 m0, s68, 0x2000
	s_nop 0
	global_load_lds_dwordx4 v[220:221], off
	v_lshl_add_u64 v[220:221], s[44:45], 0, v[134:135]
	s_mov_b32 m0, s39
	s_nop 0
	global_load_lds_dwordx4 v[220:221], off
	s_mov_b32 m0, s50
	s_nop 0
	global_load_lds_dwordx4 v[222:223], off
	s_waitcnt vmcnt(8)
	s_waitcnt lgkmcnt(0)
	s_barrier
	s_waitcnt lgkmcnt(0)
	v_mfma_f32_16x16x32_bf16 v[60:63], v[144:147], v[186:189], v[60:63]
	v_mfma_f32_16x16x32_bf16 v[56:59], v[162:165], v[186:189], v[56:59]
	v_mfma_f32_16x16x32_bf16 v[44:47], v[144:147], v[194:197], v[44:47]
	v_mfma_f32_16x16x32_bf16 v[40:43], v[162:165], v[194:197], v[40:43]
	v_mfma_f32_16x16x32_bf16 v[28:31], v[144:147], v[202:205], v[28:31]
	v_mfma_f32_16x16x32_bf16 v[24:27], v[162:165], v[202:205], v[24:27]
	v_mfma_f32_16x16x32_bf16 v[12:15], v[144:147], v[210:213], v[12:15]
	v_mfma_f32_16x16x32_bf16 v[8:11], v[162:165], v[210:213], v[8:11]
	v_mfma_f32_16x16x32_bf16 v[60:63], v[158:161], v[190:193], v[60:63]
	v_mfma_f32_16x16x32_bf16 v[56:59], v[166:169], v[190:193], v[56:59]
	v_mfma_f32_16x16x32_bf16 v[44:47], v[158:161], v[198:201], v[44:47]
	v_mfma_f32_16x16x32_bf16 v[40:43], v[166:169], v[198:201], v[40:43]
	v_mfma_f32_16x16x32_bf16 v[28:31], v[158:161], v[206:209], v[28:31]
	v_mfma_f32_16x16x32_bf16 v[24:27], v[166:169], v[206:209], v[24:27]
	v_mfma_f32_16x16x32_bf16 v[12:15], v[158:161], v[214:217], v[12:15]
	v_mfma_f32_16x16x32_bf16 v[8:11], v[166:169], v[214:217], v[8:11]
	v_mfma_f32_16x16x32_bf16 v[52:55], v[170:173], v[186:189], v[52:55]
	v_mfma_f32_16x16x32_bf16 v[48:51], v[178:181], v[186:189], v[48:51]
	v_mfma_f32_16x16x32_bf16 v[36:39], v[170:173], v[194:197], v[36:39]
	v_mfma_f32_16x16x32_bf16 v[32:35], v[178:181], v[194:197], v[32:35]
	v_mfma_f32_16x16x32_bf16 v[20:23], v[170:173], v[202:205], v[20:23]
	v_mfma_f32_16x16x32_bf16 v[16:19], v[178:181], v[202:205], v[16:19]
	v_mfma_f32_16x16x32_bf16 v[4:7], v[170:173], v[210:213], v[4:7]
	v_mfma_f32_16x16x32_bf16 v[0:3], v[178:181], v[210:213], v[0:3]
	v_mfma_f32_16x16x32_bf16 v[52:55], v[174:177], v[190:193], v[52:55]
	v_mfma_f32_16x16x32_bf16 v[48:51], v[182:185], v[190:193], v[48:51]
	v_mfma_f32_16x16x32_bf16 v[36:39], v[174:177], v[198:201], v[36:39]
	v_mfma_f32_16x16x32_bf16 v[32:35], v[182:185], v[198:201], v[32:35]
	v_mfma_f32_16x16x32_bf16 v[20:23], v[174:177], v[206:209], v[20:23]
	v_mfma_f32_16x16x32_bf16 v[16:19], v[182:185], v[206:209], v[16:19]
	v_mfma_f32_16x16x32_bf16 v[4:7], v[174:177], v[214:217], v[4:7]
	v_mfma_f32_16x16x32_bf16 v[0:3], v[182:185], v[214:217], v[0:3]
	s_barrier
	s_add_i32 s66, 0, 0x18000
	v_add_u32_e32 v157, s66, v151
	s_add_i32 s67, 0, 0x1c000
	ds_read_b128 v[144:147], v157
	ds_read_b128 v[158:161], v157 offset:1024
	ds_read_b128 v[162:165], v157 offset:2048
	ds_read_b128 v[166:169], v157 offset:3072
	v_add_u32_e32 v157, s67, v151
	ds_read_b128 v[170:173], v157
	ds_read_b128 v[174:177], v157 offset:1024
	ds_read_b128 v[178:181], v157 offset:2048
	ds_read_b128 v[182:185], v157 offset:3072
	s_add_u32 s44, s44, 0x40000
	s_addc_u32 s45, s45, 0
	s_mov_b32 m0, s51
	v_lshl_add_u64 v[224:225], s[44:45], 0, v[134:135]
	ds_read_b128 v[186:189], v155 offset:32768
	ds_read_b128 v[190:193], v155 offset:33792
	ds_read_b128 v[194:197], v155 offset:34816
	ds_read_b128 v[198:201], v155 offset:35840
	ds_read_b128 v[202:205], v155 offset:36864
	ds_read_b128 v[206:209], v155 offset:37888
	ds_read_b128 v[210:213], v155 offset:38912
	ds_read_b128 v[214:217], v155 offset:39936
	global_load_lds_dwordx4 v[224:225], off
	v_lshl_add_u64 v[224:225], s[44:45], 0, v[130:131]
	s_mov_b32 m0, s52
	s_nop 0
	global_load_lds_dwordx4 v[224:225], off
	s_waitcnt vmcnt(8)
	s_waitcnt lgkmcnt(0)
	s_barrier
	s_waitcnt lgkmcnt(0)
	v_mfma_f32_16x16x32_bf16 v[124:127], v[144:147], v[186:189], v[124:127]
	v_mfma_f32_16x16x32_bf16 v[120:123], v[162:165], v[186:189], v[120:123]
	v_mfma_f32_16x16x32_bf16 v[108:111], v[144:147], v[194:197], v[108:111]
	v_mfma_f32_16x16x32_bf16 v[104:107], v[162:165], v[194:197], v[104:107]
	v_mfma_f32_16x16x32_bf16 v[92:95], v[144:147], v[202:205], v[92:95]
	v_mfma_f32_16x16x32_bf16 v[88:91], v[162:165], v[202:205], v[88:91]
	v_mfma_f32_16x16x32_bf16 v[76:79], v[144:147], v[210:213], v[76:79]
	v_mfma_f32_16x16x32_bf16 v[72:75], v[162:165], v[210:213], v[72:75]
	v_mfma_f32_16x16x32_bf16 v[124:127], v[158:161], v[190:193], v[124:127]
	v_mfma_f32_16x16x32_bf16 v[120:123], v[166:169], v[190:193], v[120:123]
	v_mfma_f32_16x16x32_bf16 v[108:111], v[158:161], v[198:201], v[108:111]
	v_mfma_f32_16x16x32_bf16 v[104:107], v[166:169], v[198:201], v[104:107]
	v_mfma_f32_16x16x32_bf16 v[92:95], v[158:161], v[206:209], v[92:95]
	v_mfma_f32_16x16x32_bf16 v[88:91], v[166:169], v[206:209], v[88:91]
	v_mfma_f32_16x16x32_bf16 v[76:79], v[158:161], v[214:217], v[76:79]
	v_mfma_f32_16x16x32_bf16 v[72:75], v[166:169], v[214:217], v[72:75]
	v_mfma_f32_16x16x32_bf16 v[116:119], v[170:173], v[186:189], v[116:119]
	v_mfma_f32_16x16x32_bf16 v[112:115], v[178:181], v[186:189], v[112:115]
	v_mfma_f32_16x16x32_bf16 v[100:103], v[170:173], v[194:197], v[100:103]
	v_mfma_f32_16x16x32_bf16 v[96:99], v[178:181], v[194:197], v[96:99]
	v_mfma_f32_16x16x32_bf16 v[84:87], v[170:173], v[202:205], v[84:87]
	v_mfma_f32_16x16x32_bf16 v[80:83], v[178:181], v[202:205], v[80:83]
	v_mfma_f32_16x16x32_bf16 v[68:71], v[170:173], v[210:213], v[68:71]
	v_mfma_f32_16x16x32_bf16 v[64:67], v[178:181], v[210:213], v[64:67]
	v_mfma_f32_16x16x32_bf16 v[116:119], v[174:177], v[190:193], v[116:119]
	v_mfma_f32_16x16x32_bf16 v[112:115], v[182:185], v[190:193], v[112:115]
	v_mfma_f32_16x16x32_bf16 v[100:103], v[174:177], v[198:201], v[100:103]
	v_mfma_f32_16x16x32_bf16 v[96:99], v[182:185], v[198:201], v[96:99]
	v_mfma_f32_16x16x32_bf16 v[84:87], v[174:177], v[206:209], v[84:87]
	v_mfma_f32_16x16x32_bf16 v[80:83], v[182:185], v[206:209], v[80:83]
	v_mfma_f32_16x16x32_bf16 v[68:71], v[174:177], v[214:217], v[68:71]
	v_mfma_f32_16x16x32_bf16 v[64:67], v[182:185], v[214:217], v[64:67]
	s_barrier
	s_add_i32 s44, s66, s47
	v_lshl_add_u64 v[148:149], v[148:149], 0, s[16:17]
	s_mov_b32 m0, s44
	ds_read_b128 v[186:189], v155 offset:49152
	ds_read_b128 v[190:193], v155 offset:50176
	ds_read_b128 v[194:197], v155 offset:51200
	ds_read_b128 v[198:201], v155 offset:52224
	ds_read_b128 v[202:205], v155 offset:53248
	ds_read_b128 v[206:209], v155 offset:54272
	ds_read_b128 v[210:213], v155 offset:55296
	ds_read_b128 v[214:217], v155 offset:56320
	global_load_lds_dwordx4 v[148:149], off
	s_add_i32 m0, s44, 0x2000
	s_add_u32 s42, s42, 0x40080
	v_lshl_add_u64 v[148:149], v[218:219], 0, s[16:17]
	s_addc_u32 s43, s43, 0
	s_add_i32 s44, s67, s47
	global_load_lds_dwordx4 v[148:149], off
	v_lshl_add_u64 v[148:149], s[42:43], 0, v[132:133]
	s_mov_b32 m0, s44
	s_nop 0
	global_load_lds_dwordx4 v[148:149], off
	v_lshl_add_u64 v[148:149], s[42:43], 0, v[128:129]
	s_add_i32 m0, s44, 0x2000
	s_nop 0
	global_load_lds_dwordx4 v[148:149], off
	v_lshl_add_u64 v[148:149], v[220:221], 0, s[16:17]
	s_mov_b32 m0, s54
	s_nop 0
	global_load_lds_dwordx4 v[148:149], off
	v_lshl_add_u64 v[148:149], v[222:223], 0, s[16:17]
	s_mov_b32 m0, s55
	s_nop 0
	global_load_lds_dwordx4 v[148:149], off
	s_waitcnt vmcnt(8)
	s_waitcnt lgkmcnt(0)
	s_barrier
	s_waitcnt lgkmcnt(0)
	v_mfma_f32_16x16x32_bf16 v[60:63], v[144:147], v[186:189], v[60:63]
	v_mfma_f32_16x16x32_bf16 v[56:59], v[162:165], v[186:189], v[56:59]
	v_mfma_f32_16x16x32_bf16 v[44:47], v[144:147], v[194:197], v[44:47]
	v_mfma_f32_16x16x32_bf16 v[40:43], v[162:165], v[194:197], v[40:43]
	v_mfma_f32_16x16x32_bf16 v[28:31], v[144:147], v[202:205], v[28:31]
	v_mfma_f32_16x16x32_bf16 v[24:27], v[162:165], v[202:205], v[24:27]
	v_mfma_f32_16x16x32_bf16 v[12:15], v[144:147], v[210:213], v[12:15]
	v_mfma_f32_16x16x32_bf16 v[8:11], v[162:165], v[210:213], v[8:11]
	v_mfma_f32_16x16x32_bf16 v[60:63], v[158:161], v[190:193], v[60:63]
	v_mfma_f32_16x16x32_bf16 v[56:59], v[166:169], v[190:193], v[56:59]
	v_mfma_f32_16x16x32_bf16 v[44:47], v[158:161], v[198:201], v[44:47]
	v_mfma_f32_16x16x32_bf16 v[40:43], v[166:169], v[198:201], v[40:43]
	v_mfma_f32_16x16x32_bf16 v[28:31], v[158:161], v[206:209], v[28:31]
	v_mfma_f32_16x16x32_bf16 v[24:27], v[166:169], v[206:209], v[24:27]
	v_mfma_f32_16x16x32_bf16 v[12:15], v[158:161], v[214:217], v[12:15]
	v_mfma_f32_16x16x32_bf16 v[8:11], v[166:169], v[214:217], v[8:11]
	v_mfma_f32_16x16x32_bf16 v[52:55], v[170:173], v[186:189], v[52:55]
	v_mfma_f32_16x16x32_bf16 v[48:51], v[178:181], v[186:189], v[48:51]
	v_mfma_f32_16x16x32_bf16 v[36:39], v[170:173], v[194:197], v[36:39]
	v_mfma_f32_16x16x32_bf16 v[32:35], v[178:181], v[194:197], v[32:35]
	v_mfma_f32_16x16x32_bf16 v[20:23], v[170:173], v[202:205], v[20:23]
	v_mfma_f32_16x16x32_bf16 v[16:19], v[178:181], v[202:205], v[16:19]
	v_mfma_f32_16x16x32_bf16 v[4:7], v[170:173], v[210:213], v[4:7]
	v_mfma_f32_16x16x32_bf16 v[0:3], v[178:181], v[210:213], v[0:3]
	v_mfma_f32_16x16x32_bf16 v[52:55], v[174:177], v[190:193], v[52:55]
	v_mfma_f32_16x16x32_bf16 v[48:51], v[182:185], v[190:193], v[48:51]
	v_mfma_f32_16x16x32_bf16 v[36:39], v[174:177], v[198:201], v[36:39]
	v_mfma_f32_16x16x32_bf16 v[32:35], v[182:185], v[198:201], v[32:35]
	v_mfma_f32_16x16x32_bf16 v[20:23], v[174:177], v[206:209], v[20:23]
	v_mfma_f32_16x16x32_bf16 v[16:19], v[182:185], v[206:209], v[16:19]
	v_mfma_f32_16x16x32_bf16 v[4:7], v[174:177], v[214:217], v[4:7]
	v_mfma_f32_16x16x32_bf16 v[0:3], v[182:185], v[214:217], v[0:3]
	s_barrier
	s_add_i32 s65, s65, 2
	s_add_u32 s40, s40, 0x100
	s_addc_u32 s41, s41, 0
	s_add_u32 s63, s63, 0x100
	s_addc_u32 s64, s64, 0
	s_cmp_gt_u32 s65, 13
	s_cbranch_scc0 .LBB0_1234
	s_setprio 0
	s_and_b64 vcc, exec, s[18:19]
	s_cbranch_vccz .LBB0_1237
	s_barrier

.LBB0_1313:
	s_add_u32 s47, s20, 0x100
	v_mov_b32_e32 v0, 0
	s_addc_u32 s48, s21, 0
	s_mov_b32 s49, -2
	v_mov_b32_e32 v1, v0
	v_mov_b32_e32 v2, v0
	v_mov_b32_e32 v3, v0
	v_mov_b32_e32 v4, v0
	v_mov_b32_e32 v5, v0
	v_mov_b32_e32 v6, v0
	v_mov_b32_e32 v7, v0
	v_mov_b32_e32 v12, v0
	v_mov_b32_e32 v13, v0
	v_mov_b32_e32 v14, v0
	v_mov_b32_e32 v15, v0
	v_mov_b32_e32 v20, v0
	v_mov_b32_e32 v21, v0
	v_mov_b32_e32 v22, v0
	v_mov_b32_e32 v23, v0
	v_mov_b32_e32 v28, v0
	v_mov_b32_e32 v29, v0
	v_mov_b32_e32 v30, v0
	v_mov_b32_e32 v31, v0
	v_mov_b32_e32 v36, v0
	v_mov_b32_e32 v37, v0
	v_mov_b32_e32 v38, v0
	v_mov_b32_e32 v39, v0
	v_mov_b32_e32 v44, v0
	v_mov_b32_e32 v45, v0
	v_mov_b32_e32 v46, v0
	v_mov_b32_e32 v47, v0
	v_mov_b32_e32 v52, v0
	v_mov_b32_e32 v53, v0
	v_mov_b32_e32 v54, v0
	v_mov_b32_e32 v55, v0
	v_mov_b32_e32 v8, v0
	v_mov_b32_e32 v9, v0
	v_mov_b32_e32 v10, v0
	v_mov_b32_e32 v11, v0
	v_mov_b32_e32 v16, v0
	v_mov_b32_e32 v17, v0
	v_mov_b32_e32 v18, v0
	v_mov_b32_e32 v19, v0
	v_mov_b32_e32 v24, v0
	v_mov_b32_e32 v25, v0
	v_mov_b32_e32 v26, v0
	v_mov_b32_e32 v27, v0
	v_mov_b32_e32 v32, v0
	v_mov_b32_e32 v33, v0
	v_mov_b32_e32 v34, v0
	v_mov_b32_e32 v35, v0
	v_mov_b32_e32 v40, v0
	v_mov_b32_e32 v41, v0
	v_mov_b32_e32 v42, v0
	v_mov_b32_e32 v43, v0
	v_mov_b32_e32 v48, v0
	v_mov_b32_e32 v49, v0
	v_mov_b32_e32 v50, v0
	v_mov_b32_e32 v51, v0
	v_mov_b32_e32 v56, v0
	v_mov_b32_e32 v57, v0
	v_mov_b32_e32 v58, v0
	v_mov_b32_e32 v59, v0
	v_mov_b32_e32 v60, v0
	v_mov_b32_e32 v61, v0
	v_mov_b32_e32 v62, v0
	v_mov_b32_e32 v63, v0
	v_mov_b32_e32 v64, v0
	v_mov_b32_e32 v65, v0
	v_mov_b32_e32 v66, v0
	v_mov_b32_e32 v67, v0
	v_mov_b32_e32 v68, v0
	v_mov_b32_e32 v69, v0
	v_mov_b32_e32 v70, v0
	v_mov_b32_e32 v71, v0
	v_mov_b32_e32 v76, v0
	v_mov_b32_e32 v77, v0
	v_mov_b32_e32 v78, v0
	v_mov_b32_e32 v79, v0
	v_mov_b32_e32 v84, v0
	v_mov_b32_e32 v85, v0
	v_mov_b32_e32 v86, v0
	v_mov_b32_e32 v87, v0
	v_mov_b32_e32 v92, v0
	v_mov_b32_e32 v93, v0
	v_mov_b32_e32 v94, v0
	v_mov_b32_e32 v95, v0
	v_mov_b32_e32 v100, v0
	v_mov_b32_e32 v101, v0
	v_mov_b32_e32 v102, v0
	v_mov_b32_e32 v103, v0
	v_mov_b32_e32 v112, v0
	v_mov_b32_e32 v113, v0
	v_mov_b32_e32 v114, v0
	v_mov_b32_e32 v115, v0
	v_mov_b32_e32 v116, v0
	v_mov_b32_e32 v117, v0
	v_mov_b32_e32 v118, v0
	v_mov_b32_e32 v119, v0
	v_mov_b32_e32 v72, v0
	v_mov_b32_e32 v73, v0
	v_mov_b32_e32 v74, v0
	v_mov_b32_e32 v75, v0
	v_mov_b32_e32 v80, v0
	v_mov_b32_e32 v81, v0
	v_mov_b32_e32 v82, v0
	v_mov_b32_e32 v83, v0
	v_mov_b32_e32 v88, v0
	v_mov_b32_e32 v89, v0
	v_mov_b32_e32 v90, v0
	v_mov_b32_e32 v91, v0
	v_mov_b32_e32 v96, v0
	v_mov_b32_e32 v97, v0
	v_mov_b32_e32 v98, v0
	v_mov_b32_e32 v99, v0
	v_mov_b32_e32 v104, v0
	v_mov_b32_e32 v105, v0
	v_mov_b32_e32 v106, v0
	v_mov_b32_e32 v107, v0
	v_mov_b32_e32 v108, v0
	v_mov_b32_e32 v109, v0
	v_mov_b32_e32 v110, v0
	v_mov_b32_e32 v111, v0
	v_mov_b32_e32 v120, v0
	v_mov_b32_e32 v121, v0
	v_mov_b32_e32 v122, v0
	v_mov_b32_e32 v123, v0
	v_mov_b32_e32 v124, v0
	v_mov_b32_e32 v125, v0
	v_mov_b32_e32 v126, v0
	v_mov_b32_e32 v127, v0
	s_and_b64 vcc, exec, s[14:15]
	s_cbranch_vccnz .Lmy_pr_9
	s_setprio 1
.Lmy_pr_9:
.LBB0_1314:
	ds_read_b128 v[140:143], v151
	ds_read_b128 v[144:147], v151 offset:1024
	ds_read_b128 v[154:157], v151 offset:2048
	ds_read_b128 v[158:161], v151 offset:3072
	ds_read_b128 v[162:165], v152
	ds_read_b128 v[166:169], v152 offset:1024
	ds_read_b128 v[170:173], v152 offset:2048
	ds_read_b128 v[174:177], v152 offset:3072
	s_add_u32 s20, s18, 0x100
	s_addc_u32 s21, s19, 0
	s_cmp_eq_u32 s49, 40
	s_cselect_b32 s27, s5, s21
	s_cselect_b32 s26, s4, s20
	s_cselect_b32 s23, s17, s48
	s_cselect_b32 s22, s16, s47
	v_lshl_add_u64 v[210:211], s[18:19], 0, v[132:133]
	s_add_i32 m0, s33, 0xc000
	ds_read_b128 v[178:181], v153
	ds_read_b128 v[182:185], v153 offset:1024
	ds_read_b128 v[186:189], v153 offset:2048
	ds_read_b128 v[190:193], v153 offset:3072
	ds_read_b128 v[194:197], v153 offset:4096
	ds_read_b128 v[198:201], v153 offset:5120
	ds_read_b128 v[202:205], v153 offset:6144
	ds_read_b128 v[206:209], v153 offset:7168
	global_load_lds_dwordx4 v[210:211], off
	v_lshl_add_u64 v[210:211], s[18:19], 0, v[134:135]
	s_add_i32 m0, s33, 0xe000
	s_nop 0
	global_load_lds_dwordx4 v[210:211], off
	s_waitcnt vmcnt(8)
	s_waitcnt lgkmcnt(0)
	s_barrier
	s_waitcnt lgkmcnt(0)
	v_mfma_f32_16x16x32_bf16 v[124:127], v[140:143], v[178:181], v[124:127]
	v_mfma_f32_16x16x32_bf16 v[120:123], v[154:157], v[178:181], v[120:123]
	v_mfma_f32_16x16x32_bf16 v[108:111], v[140:143], v[186:189], v[108:111]
	v_mfma_f32_16x16x32_bf16 v[104:107], v[154:157], v[186:189], v[104:107]
	v_mfma_f32_16x16x32_bf16 v[96:99], v[140:143], v[194:197], v[96:99]
	v_mfma_f32_16x16x32_bf16 v[88:91], v[154:157], v[194:197], v[88:91]
	v_mfma_f32_16x16x32_bf16 v[80:83], v[140:143], v[202:205], v[80:83]
	v_mfma_f32_16x16x32_bf16 v[72:75], v[154:157], v[202:205], v[72:75]
	v_mfma_f32_16x16x32_bf16 v[124:127], v[144:147], v[182:185], v[124:127]
	v_mfma_f32_16x16x32_bf16 v[120:123], v[158:161], v[182:185], v[120:123]
	v_mfma_f32_16x16x32_bf16 v[108:111], v[144:147], v[190:193], v[108:111]
	v_mfma_f32_16x16x32_bf16 v[104:107], v[158:161], v[190:193], v[104:107]
	v_mfma_f32_16x16x32_bf16 v[96:99], v[144:147], v[198:201], v[96:99]
	v_mfma_f32_16x16x32_bf16 v[88:91], v[158:161], v[198:201], v[88:91]
	v_mfma_f32_16x16x32_bf16 v[80:83], v[144:147], v[206:209], v[80:83]
	v_mfma_f32_16x16x32_bf16 v[72:75], v[158:161], v[206:209], v[72:75]
	v_mfma_f32_16x16x32_bf16 v[116:119], v[162:165], v[178:181], v[116:119]
	v_mfma_f32_16x16x32_bf16 v[112:115], v[170:173], v[178:181], v[112:115]
	v_mfma_f32_16x16x32_bf16 v[100:103], v[162:165], v[186:189], v[100:103]
	v_mfma_f32_16x16x32_bf16 v[92:95], v[170:173], v[186:189], v[92:95]
	v_mfma_f32_16x16x32_bf16 v[84:87], v[162:165], v[194:197], v[84:87]
	v_mfma_f32_16x16x32_bf16 v[76:79], v[170:173], v[194:197], v[76:79]
	v_mfma_f32_16x16x32_bf16 v[68:71], v[162:165], v[202:205], v[68:71]
	v_mfma_f32_16x16x32_bf16 v[64:67], v[170:173], v[202:205], v[64:67]
	v_mfma_f32_16x16x32_bf16 v[116:119], v[166:169], v[182:185], v[116:119]
	v_mfma_f32_16x16x32_bf16 v[112:115], v[174:177], v[182:185], v[112:115]
	v_mfma_f32_16x16x32_bf16 v[100:103], v[166:169], v[190:193], v[100:103]
	v_mfma_f32_16x16x32_bf16 v[92:95], v[174:177], v[190:193], v[92:95]
	v_mfma_f32_16x16x32_bf16 v[84:87], v[166:169], v[198:201], v[84:87]
	v_mfma_f32_16x16x32_bf16 v[76:79], v[174:177], v[198:201], v[76:79]
	v_mfma_f32_16x16x32_bf16 v[68:71], v[166:169], v[206:209], v[68:71]
	v_mfma_f32_16x16x32_bf16 v[64:67], v[174:177], v[206:209], v[64:67]
	s_barrier
	s_add_i32 s18, s41, s31
	v_lshl_add_u64 v[210:211], s[22:23], 0, v[128:129]
	s_mov_b32 m0, s18
	ds_read_b128 v[178:181], v153 offset:16384
	ds_read_b128 v[182:185], v153 offset:17408
	ds_read_b128 v[186:189], v153 offset:18432
	ds_read_b128 v[190:193], v153 offset:19456
	ds_read_b128 v[194:197], v153 offset:20480
	ds_read_b128 v[198:201], v153 offset:21504
	ds_read_b128 v[202:205], v153 offset:22528
	ds_read_b128 v[206:209], v153 offset:23552
	global_load_lds_dwordx4 v[210:211], off
	s_add_i32 m0, s18, 0x2000
	s_add_u32 s18, s22, 0xb0000
	v_lshl_add_u64 v[212:213], s[22:23], 0, v[130:131]
	s_addc_u32 s19, s23, 0
	s_add_i32 s50, s42, s31
	global_load_lds_dwordx4 v[212:213], off
	v_lshl_add_u64 v[214:215], s[18:19], 0, v[128:129]
	s_mov_b32 m0, s50
	v_lshl_add_u64 v[216:217], s[26:27], 0, v[130:131]
	global_load_lds_dwordx4 v[214:215], off
	v_lshl_add_u64 v[214:215], s[18:19], 0, v[130:131]
	s_add_i32 m0, s50, 0x2000
	s_nop 0
	global_load_lds_dwordx4 v[214:215], off
	v_lshl_add_u64 v[214:215], s[26:27], 0, v[128:129]
	s_mov_b32 m0, s33
	s_nop 0
	global_load_lds_dwordx4 v[214:215], off
	s_mov_b32 m0, s34
	s_nop 0
	global_load_lds_dwordx4 v[216:217], off
	s_waitcnt vmcnt(8)
	s_waitcnt lgkmcnt(0)
	s_barrier
	s_waitcnt lgkmcnt(0)
	v_mfma_f32_16x16x32_bf16 v[60:63], v[140:143], v[178:181], v[60:63]
	v_mfma_f32_16x16x32_bf16 v[56:59], v[154:157], v[178:181], v[56:59]
	v_mfma_f32_16x16x32_bf16 v[48:51], v[140:143], v[186:189], v[48:51]
	v_mfma_f32_16x16x32_bf16 v[40:43], v[154:157], v[186:189], v[40:43]
	v_mfma_f32_16x16x32_bf16 v[32:35], v[140:143], v[194:197], v[32:35]
	v_mfma_f32_16x16x32_bf16 v[24:27], v[154:157], v[194:197], v[24:27]
	v_mfma_f32_16x16x32_bf16 v[16:19], v[140:143], v[202:205], v[16:19]
	v_mfma_f32_16x16x32_bf16 v[8:11], v[154:157], v[202:205], v[8:11]
	v_mfma_f32_16x16x32_bf16 v[60:63], v[144:147], v[182:185], v[60:63]
	v_mfma_f32_16x16x32_bf16 v[56:59], v[158:161], v[182:185], v[56:59]
	v_mfma_f32_16x16x32_bf16 v[48:51], v[144:147], v[190:193], v[48:51]
	v_mfma_f32_16x16x32_bf16 v[40:43], v[158:161], v[190:193], v[40:43]
	v_mfma_f32_16x16x32_bf16 v[32:35], v[144:147], v[198:201], v[32:35]
	v_mfma_f32_16x16x32_bf16 v[24:27], v[158:161], v[198:201], v[24:27]
	v_mfma_f32_16x16x32_bf16 v[16:19], v[144:147], v[206:209], v[16:19]
	v_mfma_f32_16x16x32_bf16 v[8:11], v[158:161], v[206:209], v[8:11]
	v_mfma_f32_16x16x32_bf16 v[52:55], v[162:165], v[178:181], v[52:55]
	v_mfma_f32_16x16x32_bf16 v[44:47], v[170:173], v[178:181], v[44:47]
	v_mfma_f32_16x16x32_bf16 v[36:39], v[162:165], v[186:189], v[36:39]
	v_mfma_f32_16x16x32_bf16 v[28:31], v[170:173], v[186:189], v[28:31]
	v_mfma_f32_16x16x32_bf16 v[20:23], v[162:165], v[194:197], v[20:23]
	v_mfma_f32_16x16x32_bf16 v[12:15], v[170:173], v[194:197], v[12:15]
	v_mfma_f32_16x16x32_bf16 v[4:7], v[162:165], v[202:205], v[4:7]
	v_mfma_f32_16x16x32_bf16 v[0:3], v[170:173], v[202:205], v[0:3]
	v_mfma_f32_16x16x32_bf16 v[52:55], v[166:169], v[182:185], v[52:55]
	v_mfma_f32_16x16x32_bf16 v[44:47], v[174:177], v[182:185], v[44:47]
	v_mfma_f32_16x16x32_bf16 v[36:39], v[166:169], v[190:193], v[36:39]
	v_mfma_f32_16x16x32_bf16 v[28:31], v[174:177], v[190:193], v[28:31]
	v_mfma_f32_16x16x32_bf16 v[20:23], v[166:169], v[198:201], v[20:23]
	v_mfma_f32_16x16x32_bf16 v[12:15], v[174:177], v[198:201], v[12:15]
	v_mfma_f32_16x16x32_bf16 v[4:7], v[166:169], v[206:209], v[4:7]
	v_mfma_f32_16x16x32_bf16 v[0:3], v[174:177], v[206:209], v[0:3]
	s_barrier
	s_add_i32 s50, 0, 0x18000
	s_add_i32 s51, 0, 0x1c000
	v_add_u32_e32 v158, s50, v149
	v_add_u32_e32 v174, s51, v149
	ds_read_b128 v[140:143], v158
	ds_read_b128 v[144:147], v158 offset:1024
	ds_read_b128 v[154:157], v158 offset:2048
	ds_read_b128 v[158:161], v158 offset:3072
	ds_read_b128 v[162:165], v174
	ds_read_b128 v[166:169], v174 offset:1024
	ds_read_b128 v[170:173], v174 offset:2048
	ds_read_b128 v[174:177], v174 offset:3072
	s_add_u32 s18, s26, 0xb0000
	s_addc_u32 s19, s27, 0
	s_mov_b32 m0, s35
	v_lshl_add_u64 v[218:219], s[18:19], 0, v[128:129]
	ds_read_b128 v[178:181], v153 offset:32768
	ds_read_b128 v[182:185], v153 offset:33792
	ds_read_b128 v[186:189], v153 offset:34816
	ds_read_b128 v[190:193], v153 offset:35840
	ds_read_b128 v[194:197], v153 offset:36864
	ds_read_b128 v[198:201], v153 offset:37888
	ds_read_b128 v[202:205], v153 offset:38912
	ds_read_b128 v[206:209], v153 offset:39936
	global_load_lds_dwordx4 v[218:219], off
	v_lshl_add_u64 v[218:219], s[18:19], 0, v[130:131]
	s_mov_b32 m0, s36
	s_nop 0
	global_load_lds_dwordx4 v[218:219], off
	s_waitcnt vmcnt(8)
	s_waitcnt lgkmcnt(0)
	s_barrier
	s_waitcnt lgkmcnt(0)
	v_mfma_f32_16x16x32_bf16 v[124:127], v[140:143], v[178:181], v[124:127]
	v_mfma_f32_16x16x32_bf16 v[120:123], v[154:157], v[178:181], v[120:123]
	v_mfma_f32_16x16x32_bf16 v[108:111], v[140:143], v[186:189], v[108:111]
	v_mfma_f32_16x16x32_bf16 v[104:107], v[154:157], v[186:189], v[104:107]
	v_mfma_f32_16x16x32_bf16 v[96:99], v[140:143], v[194:197], v[96:99]
	v_mfma_f32_16x16x32_bf16 v[88:91], v[154:157], v[194:197], v[88:91]
	v_mfma_f32_16x16x32_bf16 v[80:83], v[140:143], v[202:205], v[80:83]
	v_mfma_f32_16x16x32_bf16 v[72:75], v[154:157], v[202:205], v[72:75]
	v_mfma_f32_16x16x32_bf16 v[124:127], v[144:147], v[182:185], v[124:127]
	v_mfma_f32_16x16x32_bf16 v[120:123], v[158:161], v[182:185], v[120:123]
	v_mfma_f32_16x16x32_bf16 v[108:111], v[144:147], v[190:193], v[108:111]
	v_mfma_f32_16x16x32_bf16 v[104:107], v[158:161], v[190:193], v[104:107]
	v_mfma_f32_16x16x32_bf16 v[96:99], v[144:147], v[198:201], v[96:99]
	v_mfma_f32_16x16x32_bf16 v[88:91], v[158:161], v[198:201], v[88:91]
	v_mfma_f32_16x16x32_bf16 v[80:83], v[144:147], v[206:209], v[80:83]
	v_mfma_f32_16x16x32_bf16 v[72:75], v[158:161], v[206:209], v[72:75]
	v_mfma_f32_16x16x32_bf16 v[116:119], v[162:165], v[178:181], v[116:119]
	v_mfma_f32_16x16x32_bf16 v[112:115], v[170:173], v[178:181], v[112:115]
	v_mfma_f32_16x16x32_bf16 v[100:103], v[162:165], v[186:189], v[100:103]
	v_mfma_f32_16x16x32_bf16 v[92:95], v[170:173], v[186:189], v[92:95]
	v_mfma_f32_16x16x32_bf16 v[84:87], v[162:165], v[194:197], v[84:87]
	v_mfma_f32_16x16x32_bf16 v[76:79], v[170:173], v[194:197], v[76:79]
	v_mfma_f32_16x16x32_bf16 v[68:71], v[162:165], v[202:205], v[68:71]
	v_mfma_f32_16x16x32_bf16 v[64:67], v[170:173], v[202:205], v[64:67]
	v_mfma_f32_16x16x32_bf16 v[116:119], v[166:169], v[182:185], v[116:119]
	v_mfma_f32_16x16x32_bf16 v[112:115], v[174:177], v[182:185], v[112:115]
	v_mfma_f32_16x16x32_bf16 v[100:103], v[166:169], v[190:193], v[100:103]
	v_mfma_f32_16x16x32_bf16 v[92:95], v[174:177], v[190:193], v[92:95]
	v_mfma_f32_16x16x32_bf16 v[84:87], v[166:169], v[198:201], v[84:87]
	v_mfma_f32_16x16x32_bf16 v[76:79], v[174:177], v[198:201], v[76:79]
	v_mfma_f32_16x16x32_bf16 v[68:71], v[166:169], v[206:209], v[68:71]
	v_mfma_f32_16x16x32_bf16 v[64:67], v[174:177], v[206:209], v[64:67]
	s_barrier
	s_add_i32 s18, s50, s31
	v_lshl_add_u64 v[210:211], v[210:211], 0, s[8:9]
	s_mov_b32 m0, s18
	ds_read_b128 v[178:181], v153 offset:49152
	ds_read_b128 v[182:185], v153 offset:50176
	ds_read_b128 v[186:189], v153 offset:51200
	ds_read_b128 v[190:193], v153 offset:52224
	ds_read_b128 v[194:197], v153 offset:53248
	ds_read_b128 v[198:201], v153 offset:54272
	ds_read_b128 v[202:205], v153 offset:55296
	ds_read_b128 v[206:209], v153 offset:56320
	global_load_lds_dwordx4 v[210:211], off
	s_add_i32 m0, s18, 0x2000
	s_add_u32 s18, s22, 0xb0080
	v_lshl_add_u64 v[210:211], v[212:213], 0, s[8:9]
	s_addc_u32 s19, s23, 0
	s_add_i32 s22, s51, s31
	global_load_lds_dwordx4 v[210:211], off
	v_lshl_add_u64 v[210:211], s[18:19], 0, v[128:129]
	s_mov_b32 m0, s22
	s_nop 0
	global_load_lds_dwordx4 v[210:211], off
	v_lshl_add_u64 v[210:211], s[18:19], 0, v[130:131]
	s_add_i32 m0, s22, 0x2000
	s_nop 0
	global_load_lds_dwordx4 v[210:211], off
	v_lshl_add_u64 v[210:211], v[214:215], 0, s[8:9]
	s_mov_b32 m0, s38
	s_nop 0
	global_load_lds_dwordx4 v[210:211], off
	v_lshl_add_u64 v[210:211], v[216:217], 0, s[8:9]
	s_mov_b32 m0, s39
	s_nop 0
	global_load_lds_dwordx4 v[210:211], off
	s_waitcnt vmcnt(8)
	s_waitcnt lgkmcnt(0)
	s_barrier
	s_waitcnt lgkmcnt(0)
	v_mfma_f32_16x16x32_bf16 v[60:63], v[140:143], v[178:181], v[60:63]
	v_mfma_f32_16x16x32_bf16 v[56:59], v[154:157], v[178:181], v[56:59]
	v_mfma_f32_16x16x32_bf16 v[48:51], v[140:143], v[186:189], v[48:51]
	v_mfma_f32_16x16x32_bf16 v[40:43], v[154:157], v[186:189], v[40:43]
	v_mfma_f32_16x16x32_bf16 v[32:35], v[140:143], v[194:197], v[32:35]
	v_mfma_f32_16x16x32_bf16 v[24:27], v[154:157], v[194:197], v[24:27]
	v_mfma_f32_16x16x32_bf16 v[16:19], v[140:143], v[202:205], v[16:19]
	v_mfma_f32_16x16x32_bf16 v[8:11], v[154:157], v[202:205], v[8:11]
	v_mfma_f32_16x16x32_bf16 v[60:63], v[144:147], v[182:185], v[60:63]
	v_mfma_f32_16x16x32_bf16 v[56:59], v[158:161], v[182:185], v[56:59]
	v_mfma_f32_16x16x32_bf16 v[48:51], v[144:147], v[190:193], v[48:51]
	v_mfma_f32_16x16x32_bf16 v[40:43], v[158:161], v[190:193], v[40:43]
	v_mfma_f32_16x16x32_bf16 v[32:35], v[144:147], v[198:201], v[32:35]
	v_mfma_f32_16x16x32_bf16 v[24:27], v[158:161], v[198:201], v[24:27]
	v_mfma_f32_16x16x32_bf16 v[16:19], v[144:147], v[206:209], v[16:19]
	v_mfma_f32_16x16x32_bf16 v[8:11], v[158:161], v[206:209], v[8:11]
	v_mfma_f32_16x16x32_bf16 v[52:55], v[162:165], v[178:181], v[52:55]
	v_mfma_f32_16x16x32_bf16 v[44:47], v[170:173], v[178:181], v[44:47]
	v_mfma_f32_16x16x32_bf16 v[36:39], v[162:165], v[186:189], v[36:39]
	v_mfma_f32_16x16x32_bf16 v[28:31], v[170:173], v[186:189], v[28:31]
	v_mfma_f32_16x16x32_bf16 v[20:23], v[162:165], v[194:197], v[20:23]
	v_mfma_f32_16x16x32_bf16 v[12:15], v[170:173], v[194:197], v[12:15]
	v_mfma_f32_16x16x32_bf16 v[4:7], v[162:165], v[202:205], v[4:7]
	v_mfma_f32_16x16x32_bf16 v[0:3], v[170:173], v[202:205], v[0:3]
	v_mfma_f32_16x16x32_bf16 v[52:55], v[166:169], v[182:185], v[52:55]
	v_mfma_f32_16x16x32_bf16 v[44:47], v[174:177], v[182:185], v[44:47]
	v_mfma_f32_16x16x32_bf16 v[36:39], v[166:169], v[190:193], v[36:39]
	v_mfma_f32_16x16x32_bf16 v[28:31], v[174:177], v[190:193], v[28:31]
	v_mfma_f32_16x16x32_bf16 v[20:23], v[166:169], v[198:201], v[20:23]
	v_mfma_f32_16x16x32_bf16 v[12:15], v[174:177], v[198:201], v[12:15]
	v_mfma_f32_16x16x32_bf16 v[4:7], v[166:169], v[206:209], v[4:7]
	v_mfma_f32_16x16x32_bf16 v[0:3], v[174:177], v[206:209], v[0:3]
	s_barrier
	s_add_i32 s49, s49, 2
	s_add_u32 s47, s47, 0x100
	s_addc_u32 s48, s48, 0
	s_cmp_gt_u32 s49, 41
	s_mov_b64 s[18:19], s[20:21]
	s_cbranch_scc0 .LBB0_1314
	s_setprio 0
	s_and_b64 vcc, exec, s[14:15]
	s_cbranch_vccz .LBB0_1317
	s_barrier
